# phase 11 split-K tail epilogue: f32 partial stores made lane-contiguous (8 rows x 128B per instruction) via ds_bpermute
# speedup vs baseline: 1.0003x; 1.0003x over previous
; #define PG8_STAGE(bufoff, gbase, voff) do { _Pragma("unroll") for (int _i = 0; _i < 2; ++_i) \
;         __builtin_amdgcn_global_load_lds((const unsigned*)((const char*)(gbase) + (voff)[_i]), (LAS unsigned*)(lds + (bufoff) + ldsw + _i * 8192), 16, 0, 0); } while (0)
; #define PG8_LDA(dst, b, h) do { _Pragma("unroll") for (int m = 0; m < 4; ++m) _Pragma("unroll") for (int k = 0; k < 2; ++k) dst[m][k] = *(const LAS bf16x8*)(lds + PG8_SA(b, h) + aoff + m * 2048 + k * 1024); } while (0)
; #define PG8_LDB(dst, b, h) do { _Pragma("unroll") for (int n = 0; n < 2; ++n) _Pragma("unroll") for (int k = 0; k < 2; ++k) dst[n][k] = *(const LAS bf16x8*)(lds + PG8_SB(b, h) + boff + n * 2048 + k * 1024); } while (0)
; #define PG8_MMA(ai, bj, At, Bt) do { __builtin_amdgcn_s_setprio(1); _Pragma("unroll") for (int m = 0; m < 4; ++m) _Pragma("unroll") for (int n = 0; n < 2; ++n) _Pragma("unroll") for (int k = 0; k < 2; ++k) \
;         acc[ai][bj][m][n] = __builtin_amdgcn_mfma_f32_16x16x32_bf16(Bt[n][k], At[m][k], acc[ai][bj][m][n], 0, 0, 0); __builtin_amdgcn_s_setprio(0); } while (0)
; #define PG8_WAIT_V(n) asm volatile("s_waitcnt vmcnt(" #n ")" ::: "memory")
; #define PG8_WAIT_L(n) asm volatile("s_waitcnt lgkmcnt(" #n ")" ::: "memory")
; #define PG8_BAR __builtin_amdgcn_s_barrier()
; #define PG8_SCHED __builtin_amdgcn_sched_barrier(0)
; template <class Epi, class Sched>
; DI void gemm_phase(LAS unsigned char* lds, const Gemm g, const Sched& S, const Epi& E) {
;     ...
;             PG8_LDB(B0, 0, 0); PG8_SCHED; PG8_LDA(At, 0, 0); PG8_STAGE(PG8_SA(1, 1), a1 + hstep, voffA);
;             PG8_WAIT_L(8); PG8_BAR; PG8_WAIT_L(0); PG8_MMA(0, 0, At, B0); PG8_BAR; PG8_SCHED;
;             PG8_LDB(B1, 0, 1); PG8_STAGE(PG8_SB(0, 0), b2, voffB);
;             PG8_BAR; PG8_WAIT_L(0); PG8_MMA(0, 1, At, B1); PG8_BAR;
;             PG8_LDA(At, 0, 1); PG8_STAGE(PG8_SA(0, 0), a2, voffA);
;             PG8_BAR; PG8_WAIT_L(0); PG8_MMA(1, 0, At, B0); PG8_BAR; PG8_SCHED;
;             PG8_STAGE(PG8_SB(0, 1), b2 + hstep, voffB);
;             PG8_WAIT_V(6); PG8_BAR; PG8_MMA(1, 1, At, B1); PG8_BAR;
;             PG8_LDB(B0, 1, 0); PG8_SCHED; PG8_LDA(At, 1, 0); PG8_STAGE(PG8_SA(0, 1), a2 + hstep, voffA);
;             PG8_WAIT_L(8); PG8_BAR; PG8_WAIT_L(0); PG8_MMA(0, 0, At, B0); PG8_BAR; PG8_SCHED;
.LBB0_1007:
	ds_read_b128 v[140:143], v147
	ds_read_b128 v[154:157], v147 offset:1024
	ds_read_b128 v[158:161], v147 offset:2048
	ds_read_b128 v[164:167], v147 offset:3072
	s_add_u32 s24, s22, 0xfffc0080
	s_addc_u32 s25, s23, -1
	s_cmp_eq_u32 s66, 12
	s_cselect_b32 s27, s47, s25
	s_cselect_b32 s26, s53, s24
	s_cselect_b32 s25, s54, s59
	s_cselect_b32 s24, s55, s58
	s_mov_b32 m0, s36
	v_lshl_add_u64 v[150:151], s[22:23], 0, v[136:137]
	ds_read_b128 v[168:171], v148
	ds_read_b128 v[172:175], v148 offset:1024
	ds_read_b128 v[176:179], v148 offset:2048
	ds_read_b128 v[180:183], v148 offset:3072
	ds_read_b128 v[184:187], v148 offset:4096
	ds_read_b128 v[188:191], v148 offset:5120
	ds_read_b128 v[192:195], v148 offset:6144
	ds_read_b128 v[198:201], v148 offset:7168
	global_load_lds_dwordx4 v[150:151], off
	v_lshl_add_u64 v[150:151], s[22:23], 0, v[138:139]
	s_mov_b32 m0, s37
	s_nop 0
	global_load_lds_dwordx4 v[150:151], off
	s_waitcnt lgkmcnt(8)
	s_barrier
	s_waitcnt lgkmcnt(0)
	s_setprio 1
	s_waitcnt lgkmcnt(0)
	v_mfma_f32_16x16x32_bf16 v[126:129], v[140:143], v[168:171], v[126:129]
	v_mfma_f32_16x16x32_bf16 v[122:125], v[158:161], v[168:171], v[122:125]
	v_mfma_f32_16x16x32_bf16 v[114:117], v[140:143], v[176:179], v[114:117]
	v_mfma_f32_16x16x32_bf16 v[106:109], v[158:161], v[176:179], v[106:109]
	v_mfma_f32_16x16x32_bf16 v[98:101], v[140:143], v[184:187], v[98:101]
	v_mfma_f32_16x16x32_bf16 v[90:93], v[158:161], v[184:187], v[90:93]
	v_mfma_f32_16x16x32_bf16 v[82:85], v[140:143], v[192:195], v[82:85]
	v_mfma_f32_16x16x32_bf16 v[74:77], v[158:161], v[192:195], v[74:77]
	v_mfma_f32_16x16x32_bf16 v[126:129], v[154:157], v[172:175], v[126:129]
	v_mfma_f32_16x16x32_bf16 v[122:125], v[164:167], v[172:175], v[122:125]
	v_mfma_f32_16x16x32_bf16 v[114:117], v[154:157], v[180:183], v[114:117]
	v_mfma_f32_16x16x32_bf16 v[106:109], v[164:167], v[180:183], v[106:109]
	v_mfma_f32_16x16x32_bf16 v[98:101], v[154:157], v[188:191], v[98:101]
	v_mfma_f32_16x16x32_bf16 v[90:93], v[164:167], v[188:191], v[90:93]
	v_mfma_f32_16x16x32_bf16 v[82:85], v[154:157], v[198:201], v[82:85]
	v_mfma_f32_16x16x32_bf16 v[74:77], v[164:167], v[198:201], v[74:77]
	s_setprio 0
	s_barrier
	s_mov_b32 m0, s38
	v_lshl_add_u64 v[150:151], s[24:25], 0, v[132:133]
	ds_read_b128 v[202:205], v149
	ds_read_b128 v[206:209], v149 offset:1024
	ds_read_b128 v[210:213], v149 offset:2048
	ds_read_b128 v[214:217], v149 offset:3072
	global_load_lds_dwordx4 v[150:151], off
	v_lshl_add_u64 v[218:219], s[24:25], 0, v[130:131]
	s_mov_b32 m0, s39
	s_nop 0
	global_load_lds_dwordx4 v[218:219], off
	s_barrier
	s_waitcnt lgkmcnt(0)
	s_setprio 1
	s_waitcnt lgkmcnt(0)
	v_mfma_f32_16x16x32_bf16 v[118:121], v[202:205], v[168:171], v[118:121]
	v_mfma_f32_16x16x32_bf16 v[110:113], v[210:213], v[168:171], v[110:113]
	v_mfma_f32_16x16x32_bf16 v[102:105], v[202:205], v[176:179], v[102:105]
	v_mfma_f32_16x16x32_bf16 v[94:97], v[210:213], v[176:179], v[94:97]
	v_mfma_f32_16x16x32_bf16 v[86:89], v[202:205], v[184:187], v[86:89]
	v_mfma_f32_16x16x32_bf16 v[78:81], v[210:213], v[184:187], v[78:81]
	v_mfma_f32_16x16x32_bf16 v[70:73], v[202:205], v[192:195], v[70:73]
	v_mfma_f32_16x16x32_bf16 v[66:69], v[210:213], v[192:195], v[66:69]
	v_mfma_f32_16x16x32_bf16 v[118:121], v[206:209], v[172:175], v[118:121]
	v_mfma_f32_16x16x32_bf16 v[110:113], v[214:217], v[172:175], v[110:113]
	v_mfma_f32_16x16x32_bf16 v[102:105], v[206:209], v[180:183], v[102:105]
	v_mfma_f32_16x16x32_bf16 v[94:97], v[214:217], v[180:183], v[94:97]
	v_mfma_f32_16x16x32_bf16 v[86:89], v[206:209], v[188:191], v[86:89]
	v_mfma_f32_16x16x32_bf16 v[78:81], v[214:217], v[188:191], v[78:81]
	v_mfma_f32_16x16x32_bf16 v[70:73], v[206:209], v[198:201], v[70:73]
	v_mfma_f32_16x16x32_bf16 v[66:69], v[214:217], v[198:201], v[66:69]
	s_setprio 0
	s_mov_b32 m0, s13
	v_lshl_add_u64 v[220:221], s[26:27], 0, v[132:133]
	s_barrier
	ds_read_b128 v[168:171], v148 offset:16384
	ds_read_b128 v[172:175], v148 offset:17408
	ds_read_b128 v[176:179], v148 offset:18432
	ds_read_b128 v[180:183], v148 offset:19456
	ds_read_b128 v[184:187], v148 offset:20480
	ds_read_b128 v[188:191], v148 offset:21504
	ds_read_b128 v[192:195], v148 offset:22528
	ds_read_b128 v[198:201], v148 offset:23552
	global_load_lds_dwordx4 v[220:221], off
	v_lshl_add_u64 v[222:223], s[26:27], 0, v[130:131]
	s_mov_b32 m0, s28
	s_nop 0
	global_load_lds_dwordx4 v[222:223], off
	s_barrier
	s_waitcnt lgkmcnt(0)
	s_setprio 1
	s_waitcnt lgkmcnt(0)
	v_mfma_f32_16x16x32_bf16 v[62:65], v[140:143], v[168:171], v[62:65]
	v_mfma_f32_16x16x32_bf16 v[58:61], v[158:161], v[168:171], v[58:61]
	v_mfma_f32_16x16x32_bf16 v[50:53], v[140:143], v[176:179], v[50:53]
	v_mfma_f32_16x16x32_bf16 v[42:45], v[158:161], v[176:179], v[42:45]
	v_mfma_f32_16x16x32_bf16 v[34:37], v[140:143], v[184:187], v[34:37]
	v_mfma_f32_16x16x32_bf16 v[26:29], v[158:161], v[184:187], v[26:29]
	v_mfma_f32_16x16x32_bf16 v[18:21], v[140:143], v[192:195], v[18:21]
	v_mfma_f32_16x16x32_bf16 v[10:13], v[158:161], v[192:195], v[10:13]
	v_mfma_f32_16x16x32_bf16 v[62:65], v[154:157], v[172:175], v[62:65]
	v_mfma_f32_16x16x32_bf16 v[58:61], v[164:167], v[172:175], v[58:61]
	v_mfma_f32_16x16x32_bf16 v[50:53], v[154:157], v[180:183], v[50:53]
	v_mfma_f32_16x16x32_bf16 v[42:45], v[164:167], v[180:183], v[42:45]
	v_mfma_f32_16x16x32_bf16 v[34:37], v[154:157], v[188:191], v[34:37]
	v_mfma_f32_16x16x32_bf16 v[26:29], v[164:167], v[188:191], v[26:29]
	v_mfma_f32_16x16x32_bf16 v[18:21], v[154:157], v[198:201], v[18:21]
	v_mfma_f32_16x16x32_bf16 v[10:13], v[164:167], v[198:201], v[10:13]
	s_setprio 0
	s_barrier
; #define PG8_STAGE(bufoff, gbase, voff) do { _Pragma("unroll") for (int _i = 0; _i < 2; ++_i) \
;         __builtin_amdgcn_global_load_lds((const unsigned*)((const char*)(gbase) + (voff)[_i]), (LAS unsigned*)(lds + (bufoff) + ldsw + _i * 8192), 16, 0, 0); } while (0)
; #define PG8_LDA(dst, b, h) do { _Pragma("unroll") for (int m = 0; m < 4; ++m) _Pragma("unroll") for (int k = 0; k < 2; ++k) dst[m][k] = *(const LAS bf16x8*)(lds + PG8_SA(b, h) + aoff + m * 2048 + k * 1024); } while (0)
; #define PG8_LDB(dst, b, h) do { _Pragma("unroll") for (int n = 0; n < 2; ++n) _Pragma("unroll") for (int k = 0; k < 2; ++k) dst[n][k] = *(const LAS bf16x8*)(lds + PG8_SB(b, h) + boff + n * 2048 + k * 1024); } while (0)
; #define PG8_MMA(ai, bj, At, Bt) do { __builtin_amdgcn_s_setprio(1); _Pragma("unroll") for (int m = 0; m < 4; ++m) _Pragma("unroll") for (int n = 0; n < 2; ++n) _Pragma("unroll") for (int k = 0; k < 2; ++k) \
;         acc[ai][bj][m][n] = __builtin_amdgcn_mfma_f32_16x16x32_bf16(Bt[n][k], At[m][k], acc[ai][bj][m][n], 0, 0, 0); __builtin_amdgcn_s_setprio(0); } while (0)
; #define PG8_WAIT_V(n) asm volatile("s_waitcnt vmcnt(" #n ")" ::: "memory")
; #define PG8_WAIT_L(n) asm volatile("s_waitcnt lgkmcnt(" #n ")" ::: "memory")
; #define PG8_BAR __builtin_amdgcn_s_barrier()
; #define PG8_SCHED __builtin_amdgcn_sched_barrier(0)
; template <class Epi, class Sched>
; DI void gemm_phase(LAS unsigned char* lds, const Gemm g, const Sched& S, const Epi& E) {
;     ...
;             PG8_STAGE(PG8_SB(0, 1), b2 + hstep, voffB);
;             PG8_WAIT_V(6); PG8_BAR; PG8_MMA(1, 1, At, B1); PG8_BAR;
;             PG8_LDB(B0, 1, 0); PG8_SCHED; PG8_LDA(At, 1, 0); PG8_STAGE(PG8_SA(0, 1), a2 + hstep, voffA);
;             PG8_WAIT_L(8); PG8_BAR; PG8_WAIT_L(0); PG8_MMA(0, 0, At, B0); PG8_BAR; PG8_SCHED;
;             PG8_LDB(B1, 1, 1); PG8_STAGE(PG8_SB(1, 0), b3, voffB);
;             PG8_BAR; PG8_WAIT_L(0); PG8_MMA(0, 1, At, B1); PG8_BAR;
;             PG8_LDA(At, 1, 1); PG8_STAGE(PG8_SA(1, 0), a3, voffA);
;             PG8_BAR; PG8_WAIT_L(0); PG8_MMA(1, 0, At, B0); PG8_BAR; PG8_SCHED;
	s_add_u32 s72, s24, 0x40000
	s_addc_u32 s73, s25, 0
	s_add_i32 s67, s35, s12
	v_lshl_add_u64 v[140:141], s[72:73], 0, v[132:133]
	s_mov_b32 m0, s67
	s_nop 0
	global_load_lds_dwordx4 v[140:141], off
	v_lshl_add_u64 v[140:141], s[72:73], 0, v[130:131]
	s_add_i32 m0, s67, 0x2000
	s_nop 0
	global_load_lds_dwordx4 v[140:141], off
	s_waitcnt vmcnt(6)
	s_barrier
	s_setprio 1
	v_mfma_f32_16x16x32_bf16 v[54:57], v[202:205], v[168:171], v[54:57]
	v_mfma_f32_16x16x32_bf16 v[46:49], v[210:213], v[168:171], v[46:49]
	v_mfma_f32_16x16x32_bf16 v[38:41], v[202:205], v[176:179], v[38:41]
	v_mfma_f32_16x16x32_bf16 v[30:33], v[210:213], v[176:179], v[30:33]
	v_mfma_f32_16x16x32_bf16 v[22:25], v[202:205], v[184:187], v[22:25]
	v_mfma_f32_16x16x32_bf16 v[14:17], v[210:213], v[184:187], v[14:17]
	v_mfma_f32_16x16x32_bf16 v[6:9], v[202:205], v[192:195], v[6:9]
	v_mfma_f32_16x16x32_bf16 v[2:5], v[210:213], v[192:195], v[2:5]
	v_mfma_f32_16x16x32_bf16 v[54:57], v[206:209], v[172:175], v[54:57]
	v_mfma_f32_16x16x32_bf16 v[46:49], v[214:217], v[172:175], v[46:49]
	v_mfma_f32_16x16x32_bf16 v[38:41], v[206:209], v[180:183], v[38:41]
	v_mfma_f32_16x16x32_bf16 v[30:33], v[214:217], v[180:183], v[30:33]
	v_mfma_f32_16x16x32_bf16 v[22:25], v[206:209], v[188:191], v[22:25]
	v_mfma_f32_16x16x32_bf16 v[14:17], v[214:217], v[188:191], v[14:17]
	v_mfma_f32_16x16x32_bf16 v[6:9], v[206:209], v[198:201], v[6:9]
	v_mfma_f32_16x16x32_bf16 v[2:5], v[214:217], v[198:201], v[2:5]
	s_setprio 0
	s_add_i32 s67, 0, 0x18000
	v_add_u32_e32 v134, s67, v145
	s_barrier
	ds_read_b128 v[140:143], v134
	ds_read_b128 v[154:157], v134 offset:1024
	ds_read_b128 v[158:161], v134 offset:2048
	ds_read_b128 v[164:167], v134 offset:3072
	s_add_u32 s26, s26, 0x40000
	s_addc_u32 s27, s27, 0
	s_mov_b32 m0, s29
	v_lshl_add_u64 v[202:203], s[26:27], 0, v[132:133]
	ds_read_b128 v[168:171], v148 offset:32768
	ds_read_b128 v[172:175], v148 offset:33792
	ds_read_b128 v[176:179], v148 offset:34816
	ds_read_b128 v[180:183], v148 offset:35840
	ds_read_b128 v[184:187], v148 offset:36864
	ds_read_b128 v[188:191], v148 offset:37888
	ds_read_b128 v[192:195], v148 offset:38912
	ds_read_b128 v[198:201], v148 offset:39936
	global_load_lds_dwordx4 v[202:203], off
	v_lshl_add_u64 v[202:203], s[26:27], 0, v[130:131]
	s_mov_b32 m0, s30
	s_nop 0
	global_load_lds_dwordx4 v[202:203], off
	s_waitcnt lgkmcnt(8)
	s_barrier
	s_waitcnt lgkmcnt(0)
	s_setprio 1
	s_waitcnt lgkmcnt(0)
	v_mfma_f32_16x16x32_bf16 v[126:129], v[140:143], v[168:171], v[126:129]
	v_mfma_f32_16x16x32_bf16 v[122:125], v[158:161], v[168:171], v[122:125]
	v_mfma_f32_16x16x32_bf16 v[114:117], v[140:143], v[176:179], v[114:117]
	v_mfma_f32_16x16x32_bf16 v[106:109], v[158:161], v[176:179], v[106:109]
	v_mfma_f32_16x16x32_bf16 v[98:101], v[140:143], v[184:187], v[98:101]
	v_mfma_f32_16x16x32_bf16 v[90:93], v[158:161], v[184:187], v[90:93]
	v_mfma_f32_16x16x32_bf16 v[82:85], v[140:143], v[192:195], v[82:85]
	v_mfma_f32_16x16x32_bf16 v[74:77], v[158:161], v[192:195], v[74:77]
	v_mfma_f32_16x16x32_bf16 v[126:129], v[154:157], v[172:175], v[126:129]
	v_mfma_f32_16x16x32_bf16 v[122:125], v[164:167], v[172:175], v[122:125]
	v_mfma_f32_16x16x32_bf16 v[114:117], v[154:157], v[180:183], v[114:117]
	v_mfma_f32_16x16x32_bf16 v[106:109], v[164:167], v[180:183], v[106:109]
	v_mfma_f32_16x16x32_bf16 v[98:101], v[154:157], v[188:191], v[98:101]
	v_mfma_f32_16x16x32_bf16 v[90:93], v[164:167], v[188:191], v[90:93]
	v_mfma_f32_16x16x32_bf16 v[82:85], v[154:157], v[198:201], v[82:85]
	v_mfma_f32_16x16x32_bf16 v[74:77], v[164:167], v[198:201], v[74:77]
	s_setprio 0
	s_barrier
	s_add_i32 s26, 0, 0x1c000
	s_add_i32 s27, s67, s12
	v_add_u32_e32 v134, s26, v145
	v_lshl_add_u64 v[150:151], v[150:151], 0, s[10:11]
	s_mov_b32 m0, s27
	ds_read_b128 v[202:205], v134
	ds_read_b128 v[206:209], v134 offset:1024
	ds_read_b128 v[210:213], v134 offset:2048
	ds_read_b128 v[214:217], v134 offset:3072
	global_load_lds_dwordx4 v[150:151], off
	v_lshl_add_u64 v[150:151], v[218:219], 0, s[10:11]
	s_add_i32 m0, s27, 0x2000
	s_nop 0
	global_load_lds_dwordx4 v[150:151], off
	s_barrier
	s_waitcnt lgkmcnt(0)
	s_setprio 1
	s_waitcnt lgkmcnt(0)
	v_mfma_f32_16x16x32_bf16 v[118:121], v[202:205], v[168:171], v[118:121]
	v_mfma_f32_16x16x32_bf16 v[110:113], v[210:213], v[168:171], v[110:113]
	v_mfma_f32_16x16x32_bf16 v[102:105], v[202:205], v[176:179], v[102:105]
	v_mfma_f32_16x16x32_bf16 v[94:97], v[210:213], v[176:179], v[94:97]
	v_mfma_f32_16x16x32_bf16 v[86:89], v[202:205], v[184:187], v[86:89]
	v_mfma_f32_16x16x32_bf16 v[78:81], v[210:213], v[184:187], v[78:81]
	v_mfma_f32_16x16x32_bf16 v[70:73], v[202:205], v[192:195], v[70:73]
	v_mfma_f32_16x16x32_bf16 v[66:69], v[210:213], v[192:195], v[66:69]
	v_mfma_f32_16x16x32_bf16 v[118:121], v[206:209], v[172:175], v[118:121]
	v_mfma_f32_16x16x32_bf16 v[110:113], v[214:217], v[172:175], v[110:113]
	v_mfma_f32_16x16x32_bf16 v[102:105], v[206:209], v[180:183], v[102:105]
	v_mfma_f32_16x16x32_bf16 v[94:97], v[214:217], v[180:183], v[94:97]
	v_mfma_f32_16x16x32_bf16 v[86:89], v[206:209], v[188:191], v[86:89]
	v_mfma_f32_16x16x32_bf16 v[78:81], v[214:217], v[188:191], v[78:81]
	v_mfma_f32_16x16x32_bf16 v[70:73], v[206:209], v[198:201], v[70:73]
	v_mfma_f32_16x16x32_bf16 v[66:69], v[214:217], v[198:201], v[66:69]
	s_setprio 0
	s_mov_b32 m0, s33
	v_lshl_add_u64 v[150:151], v[220:221], 0, s[10:11]
	s_barrier
	ds_read_b128 v[168:171], v148 offset:49152
	ds_read_b128 v[172:175], v148 offset:50176
	ds_read_b128 v[176:179], v148 offset:51200
	ds_read_b128 v[180:183], v148 offset:52224
	ds_read_b128 v[184:187], v148 offset:53248
	ds_read_b128 v[188:191], v148 offset:54272
	ds_read_b128 v[192:195], v148 offset:55296
	ds_read_b128 v[198:201], v148 offset:56320
	global_load_lds_dwordx4 v[150:151], off
	v_lshl_add_u64 v[150:151], v[222:223], 0, s[10:11]
	s_mov_b32 m0, s34
	s_nop 0
	global_load_lds_dwordx4 v[150:151], off
	s_barrier
; DI float bflo(unsigned u) { return __uint_as_float(u << 16); }
; DI float bfhi(unsigned u) { return __uint_as_float(u & 0xffff0000u); }
; #define PG8_STAGE(bufoff, gbase, voff) do { _Pragma("unroll") for (int _i = 0; _i < 2; ++_i) \
;         __builtin_amdgcn_global_load_lds((const unsigned*)((const char*)(gbase) + (voff)[_i]), (LAS unsigned*)(lds + (bufoff) + ldsw + _i * 8192), 16, 0, 0); } while (0)
; #define PG8_LDA(dst, b, h) do { _Pragma("unroll") for (int m = 0; m < 4; ++m) _Pragma("unroll") for (int k = 0; k < 2; ++k) dst[m][k] = *(const LAS bf16x8*)(lds + PG8_SA(b, h) + aoff + m * 2048 + k * 1024); } while (0)
; #define PG8_MMA(ai, bj, At, Bt) do { __builtin_amdgcn_s_setprio(1); _Pragma("unroll") for (int m = 0; m < 4; ++m) _Pragma("unroll") for (int n = 0; n < 2; ++n) _Pragma("unroll") for (int k = 0; k < 2; ++k) \
;         acc[ai][bj][m][n] = __builtin_amdgcn_mfma_f32_16x16x32_bf16(Bt[n][k], At[m][k], acc[ai][bj][m][n], 0, 0, 0); __builtin_amdgcn_s_setprio(0); } while (0)
; #define PG8_WAIT_V(n) asm volatile("s_waitcnt vmcnt(" #n ")" ::: "memory")
;     DI void operator()(const f32x4 (&acc)[2][2][4][2], const Unit& u, int wr, int wc, int fr, int fq) const {
;         const int row0 = u.pm * BM + wr * 64 + fr, col0 = u.pn * BM + wc * 32 + 4 * fq;
; #pragma unroll
;         for (int ai = 0; ai < 2; ++ai)
; #pragma unroll
;             for (int m = 0; m < 4; ++m) { const size_t o = (size_t)(row0 + ai * HALF + m * 16) * 1024 + col0;
; #pragma unroll
;                 for (int bj = 0; bj < 2; ++bj)
; #pragma unroll
;                     for (int n = 0; n < 2; ++n) { const size_t oo = o + bj * HALF + n * 16; f32x4 rv;
;                         if (RES_BF16) { const u32x2 t = *(const u32x2*)((const bf16_t*)res + oo); rv = (f32x4){bflo(t.x), bfhi(t.x), bflo(t.y), bfhi(t.y)}; }
;                         else rv = *(const f32x4*)((const float*)res + oo);
; template <class Epi, class Sched>
; DI void gemm_phase(LAS unsigned char* lds, const Gemm g, const Sched& S, const Epi& E) {
;     ...
;             PG8_BAR; PG8_WAIT_L(0); PG8_MMA(0, 1, At, B1); PG8_BAR;
;             PG8_LDA(At, 1, 1); PG8_STAGE(PG8_SA(1, 0), a3, voffA);
;             PG8_BAR; PG8_WAIT_L(0); PG8_MMA(1, 0, At, B0); PG8_BAR; PG8_SCHED;
;             PG8_STAGE(PG8_SB(1, 1), b3 + hstep, voffB);
;             PG8_WAIT_V(6); PG8_BAR; PG8_MMA(1, 1, At, B1); PG8_BAR;
	s_waitcnt lgkmcnt(0)
	s_setprio 1
	s_waitcnt lgkmcnt(0)
	v_mfma_f32_16x16x32_bf16 v[62:65], v[140:143], v[168:171], v[62:65]
	v_mfma_f32_16x16x32_bf16 v[58:61], v[158:161], v[168:171], v[58:61]
	v_mfma_f32_16x16x32_bf16 v[50:53], v[140:143], v[176:179], v[50:53]
	v_mfma_f32_16x16x32_bf16 v[42:45], v[158:161], v[176:179], v[42:45]
	v_mfma_f32_16x16x32_bf16 v[34:37], v[140:143], v[184:187], v[34:37]
	v_mfma_f32_16x16x32_bf16 v[26:29], v[158:161], v[184:187], v[26:29]
	v_mfma_f32_16x16x32_bf16 v[18:21], v[140:143], v[192:195], v[18:21]
	v_mfma_f32_16x16x32_bf16 v[10:13], v[158:161], v[192:195], v[10:13]
	v_mfma_f32_16x16x32_bf16 v[62:65], v[154:157], v[172:175], v[62:65]
	v_mfma_f32_16x16x32_bf16 v[58:61], v[164:167], v[172:175], v[58:61]
	v_mfma_f32_16x16x32_bf16 v[50:53], v[154:157], v[180:183], v[50:53]
	v_mfma_f32_16x16x32_bf16 v[42:45], v[164:167], v[180:183], v[42:45]
	v_mfma_f32_16x16x32_bf16 v[34:37], v[154:157], v[188:191], v[34:37]
	v_mfma_f32_16x16x32_bf16 v[26:29], v[164:167], v[188:191], v[26:29]
	v_mfma_f32_16x16x32_bf16 v[18:21], v[154:157], v[198:201], v[18:21]
	v_mfma_f32_16x16x32_bf16 v[10:13], v[164:167], v[198:201], v[10:13]
	s_setprio 0
	s_barrier
	s_add_u32 s24, s24, 0x40080
	s_addc_u32 s25, s25, 0
	s_add_i32 s26, s26, s12
	v_lshl_add_u64 v[140:141], s[24:25], 0, v[132:133]
	s_mov_b32 m0, s26
	s_nop 0
	global_load_lds_dwordx4 v[140:141], off
	v_lshl_add_u64 v[140:141], s[24:25], 0, v[130:131]
	s_add_i32 m0, s26, 0x2000
	s_nop 0
	global_load_lds_dwordx4 v[140:141], off
	s_waitcnt vmcnt(6)
	s_barrier
	s_setprio 1
	v_mfma_f32_16x16x32_bf16 v[54:57], v[202:205], v[168:171], v[54:57]
	v_mfma_f32_16x16x32_bf16 v[46:49], v[210:213], v[168:171], v[46:49]
	v_mfma_f32_16x16x32_bf16 v[38:41], v[202:205], v[176:179], v[38:41]
	v_mfma_f32_16x16x32_bf16 v[30:33], v[210:213], v[176:179], v[30:33]
	v_mfma_f32_16x16x32_bf16 v[22:25], v[202:205], v[184:187], v[22:25]
	v_mfma_f32_16x16x32_bf16 v[14:17], v[210:213], v[184:187], v[14:17]
	v_mfma_f32_16x16x32_bf16 v[6:9], v[202:205], v[192:195], v[6:9]
	v_mfma_f32_16x16x32_bf16 v[2:5], v[210:213], v[192:195], v[2:5]
	v_mfma_f32_16x16x32_bf16 v[54:57], v[206:209], v[172:175], v[54:57]
	v_mfma_f32_16x16x32_bf16 v[46:49], v[214:217], v[172:175], v[46:49]
	v_mfma_f32_16x16x32_bf16 v[38:41], v[206:209], v[180:183], v[38:41]
	v_mfma_f32_16x16x32_bf16 v[30:33], v[214:217], v[180:183], v[30:33]
	v_mfma_f32_16x16x32_bf16 v[22:25], v[206:209], v[188:191], v[22:25]
	v_mfma_f32_16x16x32_bf16 v[14:17], v[214:217], v[188:191], v[14:17]
	v_mfma_f32_16x16x32_bf16 v[6:9], v[206:209], v[198:201], v[6:9]
	v_mfma_f32_16x16x32_bf16 v[2:5], v[214:217], v[198:201], v[2:5]
	s_setprio 0
	s_add_i32 s66, s66, 2
	s_add_u32 s22, s22, 0x100
	s_addc_u32 s23, s23, 0
	s_add_u32 s58, s58, 0x100
	s_addc_u32 s59, s59, 0
	s_cmp_gt_u32 s66, 13
	s_barrier
	s_cbranch_scc0 .LBB0_1007
	v_lshl_add_u32 v224, s43, 8, v144
	v_lshl_or_b32 v243, s42, 8, v146
	v_lshl_or_b32 v224, v224, 10, v243
	v_lshlrev_b32_e32 v225, 2, v224
	v_lshlrev_b32_e32 v233, 1, v224
	v_add_u32_e32 v234, 0x4000, v224
	v_lshlrev_b32_e32 v226, 2, v234
	v_lshlrev_b32_e32 v234, 1, v234
	v_add_u32_e32 v235, 0x8000, v224
	v_lshlrev_b32_e32 v227, 2, v235
	v_lshlrev_b32_e32 v235, 1, v235
	v_add_u32_e32 v236, 0xc000, v224
	v_lshlrev_b32_e32 v228, 2, v236
	v_lshlrev_b32_e32 v236, 1, v236
	v_add_u32_e32 v237, 0x20000, v224
	v_lshlrev_b32_e32 v229, 2, v237
	v_lshlrev_b32_e32 v237, 1, v237
	v_add_u32_e32 v240, 0x24000, v224
	v_lshlrev_b32_e32 v230, 2, v240
	v_lshlrev_b32_e32 v240, 1, v240
	v_add_u32_e32 v241, 0x28000, v224
	v_lshlrev_b32_e32 v231, 2, v241
	v_lshlrev_b32_e32 v241, 1, v241
	v_add_u32_e32 v242, 0x2c000, v224
	v_lshlrev_b32_e32 v232, 2, v242
	v_lshlrev_b32_e32 v242, 1, v242
	v_and_b32_e32 v248, 63, v1
	v_lshrrev_b32_e32 v249, 3, v248
	v_and_b32_e32 v250, 3, v248
	v_lshl_or_b32 v250, v250, 4, v249
	v_lshlrev_b32_e32 v244, 2, v250
	v_add_u32_e32 v245, 32, v244
	v_and_b32_e32 v250, 0xffffffc0, v144
	v_add_u32_e32 v250, v250, v249
	v_lshl_add_u32 v250, s43, 8, v250
	v_mul_u32_u24_e32 v250, 0x800, v250
	v_and_b32_e32 v247, 0xffffffe0, v146
	v_lshl_or_b32 v247, s42, 8, v247
	v_lshlrev_b32_e32 v247, 1, v247
	v_and_b32_e32 v248, 7, v248
	v_lshl_add_u32 v247, v248, 3, v247
	v_add_u32_e32 v246, v250, v247
	s_mov_b32 s98, 0xf0f0f0f0
	s_mov_b32 s99, 0xf0f0f0f0
	global_load_dwordx4 v[140:143], v225, s[60:61]
	global_load_dwordx4 v[154:157], v225, s[60:61] offset:64
	global_load_dwordx4 v[158:161], v225, s[60:61] offset:512
	global_load_dwordx4 v[164:167], v225, s[60:61] offset:576
	global_load_dwordx4 v[168:171], v226, s[60:61]
	global_load_dwordx4 v[172:175], v226, s[60:61] offset:64
	global_load_dwordx4 v[176:179], v226, s[60:61] offset:512
	global_load_dwordx4 v[180:183], v226, s[60:61] offset:576
	global_load_dwordx4 v[184:187], v227, s[60:61]
	global_load_dwordx4 v[188:191], v227, s[60:61] offset:64
	global_load_dwordx4 v[192:195], v227, s[60:61] offset:512
	global_load_dwordx4 v[198:201], v227, s[60:61] offset:576
	global_load_dwordx4 v[202:205], v228, s[60:61]
	global_load_dwordx4 v[206:209], v228, s[60:61] offset:64
	global_load_dwordx4 v[210:213], v228, s[60:61] offset:512
	global_load_dwordx4 v[214:217], v228, s[60:61] offset:576
	s_waitcnt vmcnt(12)
; DI unsigned pk_bf16(float a, float b) { f32x2 v = {a, b}; bf2_t r = __builtin_convertvector(v, bf2_t); return __builtin_bit_cast(unsigned, r); }
; DI float bflo(unsigned u) { return __uint_as_float(u << 16); }
; DI float bfhi(unsigned u) { return __uint_as_float(u & 0xffff0000u); }
;     DI void operator()(const f32x4 (&acc)[2][2][4][2], const Unit& u, int wr, int wc, int fr, int fq) const {
;         const int row0 = u.pm * BM + wr * 64 + fr, col0 = u.pn * BM + wc * 32 + 4 * fq;
; #pragma unroll
;         for (int ai = 0; ai < 2; ++ai)
; #pragma unroll
;             for (int m = 0; m < 4; ++m) { const size_t o = (size_t)(row0 + ai * HALF + m * 16) * 1024 + col0;
; #pragma unroll
;                 for (int bj = 0; bj < 2; ++bj)
; #pragma unroll
;                     for (int n = 0; n < 2; ++n) { const size_t oo = o + bj * HALF + n * 16; f32x4 rv;
;                         if (RES_BF16) { const u32x2 t = *(const u32x2*)((const bf16_t*)res + oo); rv = (f32x4){bflo(t.x), bfhi(t.x), bflo(t.y), bfhi(t.y)}; }
;                         else rv = *(const f32x4*)((const float*)res + oo);
;                         const f32x4 v = acc[ai][bj][m][n] + rv; u32x2 w; w.x = pk_bf16(v.x, v.y); w.y = pk_bf16(v.z, v.w);
;                         *(u32x2*)(O + oo) = w; } }
	v_pk_add_f32 v[128:129], v[128:129], v[142:143]
	v_pk_add_f32 v[126:127], v[126:127], v[140:141]
	v_pk_add_f32 v[124:125], v[124:125], v[156:157]
	v_pk_add_f32 v[122:123], v[122:123], v[154:155]
	v_pk_add_f32 v[120:121], v[120:121], v[160:161]
	v_pk_add_f32 v[118:119], v[118:119], v[158:159]
	v_pk_add_f32 v[112:113], v[112:113], v[166:167]
	v_pk_add_f32 v[110:111], v[110:111], v[164:165]
	v_cvt_pk_bf16_f32 v126, v126, v127
	v_cvt_pk_bf16_f32 v127, v128, v129
	v_cvt_pk_bf16_f32 v122, v122, v123
	v_cvt_pk_bf16_f32 v123, v124, v125
	v_cvt_pk_bf16_f32 v118, v118, v119
	v_cvt_pk_bf16_f32 v119, v120, v121
	v_cvt_pk_bf16_f32 v110, v110, v111
	v_cvt_pk_bf16_f32 v111, v112, v113
	ds_bpermute_b32 v140, v244, v126
	ds_bpermute_b32 v141, v244, v127
	ds_bpermute_b32 v142, v244, v122
	ds_bpermute_b32 v143, v244, v123
	ds_bpermute_b32 v154, v245, v126
	ds_bpermute_b32 v155, v245, v127
	ds_bpermute_b32 v156, v245, v122
	ds_bpermute_b32 v157, v245, v123
	s_waitcnt lgkmcnt(0)
	v_cndmask_b32_e64 v140, v140, v142, s[98:99]
	v_cndmask_b32_e64 v141, v141, v143, s[98:99]
	v_mov_b32_e32 v142, v246
	global_store_dwordx2 v142, v[140:141], s[48:49]
	v_cndmask_b32_e64 v154, v154, v156, s[98:99]
	v_cndmask_b32_e64 v155, v155, v157, s[98:99]
	v_add_u32_e32 v156, 0x4000, v246
	global_store_dwordx2 v156, v[154:155], s[48:49]
	ds_bpermute_b32 v140, v244, v118
	ds_bpermute_b32 v141, v244, v119
	ds_bpermute_b32 v142, v244, v110
	ds_bpermute_b32 v143, v244, v111
	ds_bpermute_b32 v154, v245, v118
	ds_bpermute_b32 v155, v245, v119
	ds_bpermute_b32 v156, v245, v110
	ds_bpermute_b32 v157, v245, v111
	s_waitcnt lgkmcnt(0)
	v_cndmask_b32_e64 v140, v140, v142, s[98:99]
	v_cndmask_b32_e64 v141, v141, v143, s[98:99]
	v_mov_b32_e32 v142, v246
	global_store_dwordx2 v142, v[140:141], s[48:49] offset:256
	v_cndmask_b32_e64 v154, v154, v156, s[98:99]
	v_cndmask_b32_e64 v155, v155, v157, s[98:99]
	v_add_u32_e32 v156, 0x4000, v246
	global_store_dwordx2 v156, v[154:155], s[48:49] offset:256
	global_load_dwordx4 v[140:143], v229, s[60:61]
	global_load_dwordx4 v[154:157], v229, s[60:61] offset:64
	global_load_dwordx4 v[158:161], v229, s[60:61] offset:512
	global_load_dwordx4 v[164:167], v229, s[60:61] offset:576
	s_waitcnt vmcnt(16)
	v_pk_add_f32 v[116:117], v[116:117], v[170:171]
	v_pk_add_f32 v[114:115], v[114:115], v[168:169]
	v_pk_add_f32 v[108:109], v[108:109], v[174:175]
	v_pk_add_f32 v[106:107], v[106:107], v[172:173]
	v_pk_add_f32 v[104:105], v[104:105], v[178:179]
	v_pk_add_f32 v[102:103], v[102:103], v[176:177]
	v_pk_add_f32 v[96:97], v[96:97], v[182:183]
	v_pk_add_f32 v[94:95], v[94:95], v[180:181]
	v_cvt_pk_bf16_f32 v114, v114, v115
	v_cvt_pk_bf16_f32 v115, v116, v117
	v_cvt_pk_bf16_f32 v106, v106, v107
	v_cvt_pk_bf16_f32 v107, v108, v109
	v_cvt_pk_bf16_f32 v102, v102, v103
	v_cvt_pk_bf16_f32 v103, v104, v105
	v_cvt_pk_bf16_f32 v94, v94, v95
	v_cvt_pk_bf16_f32 v95, v96, v97
	ds_bpermute_b32 v168, v244, v114
	ds_bpermute_b32 v169, v244, v115
	ds_bpermute_b32 v170, v244, v106
	ds_bpermute_b32 v171, v244, v107
	ds_bpermute_b32 v172, v245, v114
	ds_bpermute_b32 v173, v245, v115
	ds_bpermute_b32 v174, v245, v106
	ds_bpermute_b32 v175, v245, v107
	s_waitcnt lgkmcnt(0)
	v_cndmask_b32_e64 v168, v168, v170, s[98:99]
	v_cndmask_b32_e64 v169, v169, v171, s[98:99]
	v_add_u32_e32 v170, 0x8000, v246
	global_store_dwordx2 v170, v[168:169], s[48:49]
	v_cndmask_b32_e64 v172, v172, v174, s[98:99]
	v_cndmask_b32_e64 v173, v173, v175, s[98:99]
	v_add_u32_e32 v174, 0xc000, v246
	global_store_dwordx2 v174, v[172:173], s[48:49]
	ds_bpermute_b32 v168, v244, v102
	ds_bpermute_b32 v169, v244, v103
	ds_bpermute_b32 v170, v244, v94
	ds_bpermute_b32 v171, v244, v95
	ds_bpermute_b32 v172, v245, v102
	ds_bpermute_b32 v173, v245, v103
	ds_bpermute_b32 v174, v245, v94
	ds_bpermute_b32 v175, v245, v95
	s_waitcnt lgkmcnt(0)
	v_cndmask_b32_e64 v168, v168, v170, s[98:99]
	v_cndmask_b32_e64 v169, v169, v171, s[98:99]
	v_add_u32_e32 v170, 0x8000, v246
	global_store_dwordx2 v170, v[168:169], s[48:49] offset:256
	v_cndmask_b32_e64 v172, v172, v174, s[98:99]
	v_cndmask_b32_e64 v173, v173, v175, s[98:99]
	v_add_u32_e32 v174, 0xc000, v246
	global_store_dwordx2 v174, v[172:173], s[48:49] offset:256
	global_load_dwordx4 v[168:171], v230, s[60:61]
	global_load_dwordx4 v[172:175], v230, s[60:61] offset:64
	global_load_dwordx4 v[176:179], v230, s[60:61] offset:512
	global_load_dwordx4 v[180:183], v230, s[60:61] offset:576
	s_waitcnt vmcnt(20)
	v_pk_add_f32 v[100:101], v[100:101], v[186:187]
	v_pk_add_f32 v[98:99], v[98:99], v[184:185]
	v_pk_add_f32 v[92:93], v[92:93], v[190:191]
	v_pk_add_f32 v[90:91], v[90:91], v[188:189]
	v_pk_add_f32 v[88:89], v[88:89], v[194:195]
	v_pk_add_f32 v[86:87], v[86:87], v[192:193]
	v_pk_add_f32 v[80:81], v[80:81], v[200:201]
	v_pk_add_f32 v[78:79], v[78:79], v[198:199]
	v_cvt_pk_bf16_f32 v98, v98, v99
	v_cvt_pk_bf16_f32 v99, v100, v101
	v_cvt_pk_bf16_f32 v90, v90, v91
	v_cvt_pk_bf16_f32 v91, v92, v93
	v_cvt_pk_bf16_f32 v86, v86, v87
	v_cvt_pk_bf16_f32 v87, v88, v89
	v_cvt_pk_bf16_f32 v78, v78, v79
	v_cvt_pk_bf16_f32 v79, v80, v81
	ds_bpermute_b32 v184, v244, v98
	ds_bpermute_b32 v185, v244, v99
	ds_bpermute_b32 v186, v244, v90
	ds_bpermute_b32 v187, v244, v91
	ds_bpermute_b32 v188, v245, v98
	ds_bpermute_b32 v189, v245, v99
	ds_bpermute_b32 v190, v245, v90
	ds_bpermute_b32 v191, v245, v91
	s_waitcnt lgkmcnt(0)
; DI unsigned pk_bf16(float a, float b) { f32x2 v = {a, b}; bf2_t r = __builtin_convertvector(v, bf2_t); return __builtin_bit_cast(unsigned, r); }
; DI float bflo(unsigned u) { return __uint_as_float(u << 16); }
; DI float bfhi(unsigned u) { return __uint_as_float(u & 0xffff0000u); }
;     DI void operator()(const f32x4 (&acc)[2][2][4][2], const Unit& u, int wr, int wc, int fr, int fq) const {
;         const int row0 = u.pm * BM + wr * 64 + fr, col0 = u.pn * BM + wc * 32 + 4 * fq;
; #pragma unroll
;         for (int ai = 0; ai < 2; ++ai)
; #pragma unroll
;             for (int m = 0; m < 4; ++m) { const size_t o = (size_t)(row0 + ai * HALF + m * 16) * 1024 + col0;
; #pragma unroll
;                 for (int bj = 0; bj < 2; ++bj)
; #pragma unroll
;                     for (int n = 0; n < 2; ++n) { const size_t oo = o + bj * HALF + n * 16; f32x4 rv;
;                         if (RES_BF16) { const u32x2 t = *(const u32x2*)((const bf16_t*)res + oo); rv = (f32x4){bflo(t.x), bfhi(t.x), bflo(t.y), bfhi(t.y)}; }
;                         else rv = *(const f32x4*)((const float*)res + oo);
;                         const f32x4 v = acc[ai][bj][m][n] + rv; u32x2 w; w.x = pk_bf16(v.x, v.y); w.y = pk_bf16(v.z, v.w);
;                         *(u32x2*)(O + oo) = w; } }
	v_cndmask_b32_e64 v184, v184, v186, s[98:99]
	v_cndmask_b32_e64 v185, v185, v187, s[98:99]
	v_add_u32_e32 v186, 0x10000, v246
	global_store_dwordx2 v186, v[184:185], s[48:49]
	v_cndmask_b32_e64 v188, v188, v190, s[98:99]
	v_cndmask_b32_e64 v189, v189, v191, s[98:99]
	v_add_u32_e32 v190, 0x14000, v246
	global_store_dwordx2 v190, v[188:189], s[48:49]
	ds_bpermute_b32 v184, v244, v86
	ds_bpermute_b32 v185, v244, v87
	ds_bpermute_b32 v186, v244, v78
	ds_bpermute_b32 v187, v244, v79
	ds_bpermute_b32 v188, v245, v86
	ds_bpermute_b32 v189, v245, v87
	ds_bpermute_b32 v190, v245, v78
	ds_bpermute_b32 v191, v245, v79
	s_waitcnt lgkmcnt(0)
	v_cndmask_b32_e64 v184, v184, v186, s[98:99]
	v_cndmask_b32_e64 v185, v185, v187, s[98:99]
	v_add_u32_e32 v186, 0x10000, v246
	global_store_dwordx2 v186, v[184:185], s[48:49] offset:256
	v_cndmask_b32_e64 v188, v188, v190, s[98:99]
	v_cndmask_b32_e64 v189, v189, v191, s[98:99]
	v_add_u32_e32 v190, 0x14000, v246
	global_store_dwordx2 v190, v[188:189], s[48:49] offset:256
	global_load_dwordx4 v[184:187], v231, s[60:61]
	global_load_dwordx4 v[188:191], v231, s[60:61] offset:64
	global_load_dwordx4 v[192:195], v231, s[60:61] offset:512
	global_load_dwordx4 v[198:201], v231, s[60:61] offset:576
	s_waitcnt vmcnt(24)
	v_pk_add_f32 v[84:85], v[84:85], v[204:205]
	v_pk_add_f32 v[82:83], v[82:83], v[202:203]
	v_pk_add_f32 v[76:77], v[76:77], v[208:209]
	v_pk_add_f32 v[74:75], v[74:75], v[206:207]
	v_pk_add_f32 v[72:73], v[72:73], v[212:213]
	v_pk_add_f32 v[70:71], v[70:71], v[210:211]
	v_pk_add_f32 v[68:69], v[68:69], v[216:217]
	v_pk_add_f32 v[66:67], v[66:67], v[214:215]
	v_cvt_pk_bf16_f32 v82, v82, v83
	v_cvt_pk_bf16_f32 v83, v84, v85
	v_cvt_pk_bf16_f32 v74, v74, v75
	v_cvt_pk_bf16_f32 v75, v76, v77
	v_cvt_pk_bf16_f32 v70, v70, v71
	v_cvt_pk_bf16_f32 v71, v72, v73
	v_cvt_pk_bf16_f32 v66, v66, v67
	v_cvt_pk_bf16_f32 v67, v68, v69
	ds_bpermute_b32 v202, v244, v82
	ds_bpermute_b32 v203, v244, v83
	ds_bpermute_b32 v204, v244, v74
	ds_bpermute_b32 v205, v244, v75
	ds_bpermute_b32 v206, v245, v82
	ds_bpermute_b32 v207, v245, v83
	ds_bpermute_b32 v208, v245, v74
	ds_bpermute_b32 v209, v245, v75
	s_waitcnt lgkmcnt(0)
	v_cndmask_b32_e64 v202, v202, v204, s[98:99]
	v_cndmask_b32_e64 v203, v203, v205, s[98:99]
	v_add_u32_e32 v204, 0x18000, v246
	global_store_dwordx2 v204, v[202:203], s[48:49]
	v_cndmask_b32_e64 v206, v206, v208, s[98:99]
	v_cndmask_b32_e64 v207, v207, v209, s[98:99]
	v_add_u32_e32 v208, 0x1c000, v246
	global_store_dwordx2 v208, v[206:207], s[48:49]
	ds_bpermute_b32 v202, v244, v70
	ds_bpermute_b32 v203, v244, v71
	ds_bpermute_b32 v204, v244, v66
	ds_bpermute_b32 v205, v244, v67
	ds_bpermute_b32 v206, v245, v70
	ds_bpermute_b32 v207, v245, v71
	ds_bpermute_b32 v208, v245, v66
	ds_bpermute_b32 v209, v245, v67
	s_waitcnt lgkmcnt(0)
	v_cndmask_b32_e64 v202, v202, v204, s[98:99]
	v_cndmask_b32_e64 v203, v203, v205, s[98:99]
	v_add_u32_e32 v204, 0x18000, v246
	global_store_dwordx2 v204, v[202:203], s[48:49] offset:256
	v_cndmask_b32_e64 v206, v206, v208, s[98:99]
	v_cndmask_b32_e64 v207, v207, v209, s[98:99]
	v_add_u32_e32 v208, 0x1c000, v246
	global_store_dwordx2 v208, v[206:207], s[48:49] offset:256
	global_load_dwordx4 v[202:205], v232, s[60:61]
	global_load_dwordx4 v[206:209], v232, s[60:61] offset:64
	global_load_dwordx4 v[210:213], v232, s[60:61] offset:512
	global_load_dwordx4 v[214:217], v232, s[60:61] offset:576
	s_waitcnt vmcnt(24)
	v_pk_add_f32 v[64:65], v[64:65], v[142:143]
	v_pk_add_f32 v[62:63], v[62:63], v[140:141]
	v_pk_add_f32 v[60:61], v[60:61], v[156:157]
	v_pk_add_f32 v[58:59], v[58:59], v[154:155]
	v_pk_add_f32 v[56:57], v[56:57], v[160:161]
	v_pk_add_f32 v[54:55], v[54:55], v[158:159]
	v_pk_add_f32 v[48:49], v[48:49], v[166:167]
	v_pk_add_f32 v[46:47], v[46:47], v[164:165]
	v_cvt_pk_bf16_f32 v62, v62, v63
	v_cvt_pk_bf16_f32 v63, v64, v65
	v_cvt_pk_bf16_f32 v58, v58, v59
	v_cvt_pk_bf16_f32 v59, v60, v61
	v_cvt_pk_bf16_f32 v54, v54, v55
	v_cvt_pk_bf16_f32 v55, v56, v57
	v_cvt_pk_bf16_f32 v46, v46, v47
	v_cvt_pk_bf16_f32 v47, v48, v49
	ds_bpermute_b32 v140, v244, v62
	ds_bpermute_b32 v141, v244, v63
	ds_bpermute_b32 v142, v244, v58
	ds_bpermute_b32 v143, v244, v59
	ds_bpermute_b32 v154, v245, v62
	ds_bpermute_b32 v155, v245, v63
	ds_bpermute_b32 v156, v245, v58
	ds_bpermute_b32 v157, v245, v59
	s_waitcnt lgkmcnt(0)
	v_cndmask_b32_e64 v140, v140, v142, s[98:99]
	v_cndmask_b32_e64 v141, v141, v143, s[98:99]
	v_add_u32_e32 v142, 0x40000, v246
	global_store_dwordx2 v142, v[140:141], s[48:49]
	v_cndmask_b32_e64 v154, v154, v156, s[98:99]
	v_cndmask_b32_e64 v155, v155, v157, s[98:99]
	v_add_u32_e32 v156, 0x44000, v246
	global_store_dwordx2 v156, v[154:155], s[48:49]
	ds_bpermute_b32 v140, v244, v54
	ds_bpermute_b32 v141, v244, v55
	ds_bpermute_b32 v142, v244, v46
	ds_bpermute_b32 v143, v244, v47
	ds_bpermute_b32 v154, v245, v54
	ds_bpermute_b32 v155, v245, v55
	ds_bpermute_b32 v156, v245, v46
	ds_bpermute_b32 v157, v245, v47
	s_waitcnt lgkmcnt(0)
	v_cndmask_b32_e64 v140, v140, v142, s[98:99]
	v_cndmask_b32_e64 v141, v141, v143, s[98:99]
	v_add_u32_e32 v142, 0x40000, v246
	global_store_dwordx2 v142, v[140:141], s[48:49] offset:256
	v_cndmask_b32_e64 v154, v154, v156, s[98:99]
	v_cndmask_b32_e64 v155, v155, v157, s[98:99]
	v_add_u32_e32 v156, 0x44000, v246
	global_store_dwordx2 v156, v[154:155], s[48:49] offset:256
	s_waitcnt vmcnt(20)
; DI unsigned pk_bf16(float a, float b) { f32x2 v = {a, b}; bf2_t r = __builtin_convertvector(v, bf2_t); return __builtin_bit_cast(unsigned, r); }
; DI float bflo(unsigned u) { return __uint_as_float(u << 16); }
; DI float bfhi(unsigned u) { return __uint_as_float(u & 0xffff0000u); }
;     DI void operator()(const f32x4 (&acc)[2][2][4][2], const Unit& u, int wr, int wc, int fr, int fq) const {
;         const int row0 = u.pm * BM + wr * 64 + fr, col0 = u.pn * BM + wc * 32 + 4 * fq;
; #pragma unroll
;         for (int ai = 0; ai < 2; ++ai)
; #pragma unroll
;             for (int m = 0; m < 4; ++m) { const size_t o = (size_t)(row0 + ai * HALF + m * 16) * 1024 + col0;
; #pragma unroll
;                 for (int bj = 0; bj < 2; ++bj)
; #pragma unroll
;                     for (int n = 0; n < 2; ++n) { const size_t oo = o + bj * HALF + n * 16; f32x4 rv;
;                         if (RES_BF16) { const u32x2 t = *(const u32x2*)((const bf16_t*)res + oo); rv = (f32x4){bflo(t.x), bfhi(t.x), bflo(t.y), bfhi(t.y)}; }
;                         else rv = *(const f32x4*)((const float*)res + oo);
;                         const f32x4 v = acc[ai][bj][m][n] + rv; u32x2 w; w.x = pk_bf16(v.x, v.y); w.y = pk_bf16(v.z, v.w);
;                         *(u32x2*)(O + oo) = w; } }
	v_pk_add_f32 v[52:53], v[52:53], v[170:171]
	v_pk_add_f32 v[50:51], v[50:51], v[168:169]
	v_pk_add_f32 v[44:45], v[44:45], v[174:175]
	v_pk_add_f32 v[42:43], v[42:43], v[172:173]
	v_pk_add_f32 v[40:41], v[40:41], v[178:179]
	v_pk_add_f32 v[38:39], v[38:39], v[176:177]
	v_pk_add_f32 v[32:33], v[32:33], v[182:183]
	v_pk_add_f32 v[30:31], v[30:31], v[180:181]
	v_cvt_pk_bf16_f32 v50, v50, v51
	v_cvt_pk_bf16_f32 v51, v52, v53
	v_cvt_pk_bf16_f32 v42, v42, v43
	v_cvt_pk_bf16_f32 v43, v44, v45
	v_cvt_pk_bf16_f32 v38, v38, v39
	v_cvt_pk_bf16_f32 v39, v40, v41
	v_cvt_pk_bf16_f32 v30, v30, v31
	v_cvt_pk_bf16_f32 v31, v32, v33
	ds_bpermute_b32 v168, v244, v50
	ds_bpermute_b32 v169, v244, v51
	ds_bpermute_b32 v170, v244, v42
	ds_bpermute_b32 v171, v244, v43
	ds_bpermute_b32 v172, v245, v50
	ds_bpermute_b32 v173, v245, v51
	ds_bpermute_b32 v174, v245, v42
	ds_bpermute_b32 v175, v245, v43
	s_waitcnt lgkmcnt(0)
	v_cndmask_b32_e64 v168, v168, v170, s[98:99]
	v_cndmask_b32_e64 v169, v169, v171, s[98:99]
	v_add_u32_e32 v170, 0x48000, v246
	global_store_dwordx2 v170, v[168:169], s[48:49]
	v_cndmask_b32_e64 v172, v172, v174, s[98:99]
	v_cndmask_b32_e64 v173, v173, v175, s[98:99]
	v_add_u32_e32 v174, 0x4c000, v246
	global_store_dwordx2 v174, v[172:173], s[48:49]
	ds_bpermute_b32 v168, v244, v38
	ds_bpermute_b32 v169, v244, v39
	ds_bpermute_b32 v170, v244, v30
	ds_bpermute_b32 v171, v244, v31
	ds_bpermute_b32 v172, v245, v38
	ds_bpermute_b32 v173, v245, v39
	ds_bpermute_b32 v174, v245, v30
	ds_bpermute_b32 v175, v245, v31
	s_waitcnt lgkmcnt(0)
	v_cndmask_b32_e64 v168, v168, v170, s[98:99]
	v_cndmask_b32_e64 v169, v169, v171, s[98:99]
	v_add_u32_e32 v170, 0x48000, v246
	global_store_dwordx2 v170, v[168:169], s[48:49] offset:256
	v_cndmask_b32_e64 v172, v172, v174, s[98:99]
	v_cndmask_b32_e64 v173, v173, v175, s[98:99]
	v_add_u32_e32 v174, 0x4c000, v246
	global_store_dwordx2 v174, v[172:173], s[48:49] offset:256
	s_waitcnt vmcnt(16)
	v_pk_add_f32 v[36:37], v[36:37], v[186:187]
	v_pk_add_f32 v[34:35], v[34:35], v[184:185]
	v_pk_add_f32 v[28:29], v[28:29], v[190:191]
	v_pk_add_f32 v[26:27], v[26:27], v[188:189]
	v_pk_add_f32 v[24:25], v[24:25], v[194:195]
	v_pk_add_f32 v[22:23], v[22:23], v[192:193]
	v_pk_add_f32 v[16:17], v[16:17], v[200:201]
	v_pk_add_f32 v[14:15], v[14:15], v[198:199]
	v_cvt_pk_bf16_f32 v34, v34, v35
	v_cvt_pk_bf16_f32 v35, v36, v37
	v_cvt_pk_bf16_f32 v26, v26, v27
	v_cvt_pk_bf16_f32 v27, v28, v29
	v_cvt_pk_bf16_f32 v22, v22, v23
	v_cvt_pk_bf16_f32 v23, v24, v25
	v_cvt_pk_bf16_f32 v14, v14, v15
	v_cvt_pk_bf16_f32 v15, v16, v17
	ds_bpermute_b32 v184, v244, v34
	ds_bpermute_b32 v185, v244, v35
	ds_bpermute_b32 v186, v244, v26
	ds_bpermute_b32 v187, v244, v27
	ds_bpermute_b32 v188, v245, v34
	ds_bpermute_b32 v189, v245, v35
	ds_bpermute_b32 v190, v245, v26
	ds_bpermute_b32 v191, v245, v27
	s_waitcnt lgkmcnt(0)
	v_cndmask_b32_e64 v184, v184, v186, s[98:99]
	v_cndmask_b32_e64 v185, v185, v187, s[98:99]
	v_add_u32_e32 v186, 0x50000, v246
	global_store_dwordx2 v186, v[184:185], s[48:49]
	v_cndmask_b32_e64 v188, v188, v190, s[98:99]
	v_cndmask_b32_e64 v189, v189, v191, s[98:99]
	v_add_u32_e32 v190, 0x54000, v246
	global_store_dwordx2 v190, v[188:189], s[48:49]
	ds_bpermute_b32 v184, v244, v22
	ds_bpermute_b32 v185, v244, v23
	ds_bpermute_b32 v186, v244, v14
	ds_bpermute_b32 v187, v244, v15
	ds_bpermute_b32 v188, v245, v22
	ds_bpermute_b32 v189, v245, v23
	ds_bpermute_b32 v190, v245, v14
	ds_bpermute_b32 v191, v245, v15
	s_waitcnt lgkmcnt(0)
	v_cndmask_b32_e64 v184, v184, v186, s[98:99]
	v_cndmask_b32_e64 v185, v185, v187, s[98:99]
	v_add_u32_e32 v186, 0x50000, v246
	global_store_dwordx2 v186, v[184:185], s[48:49] offset:256
	v_cndmask_b32_e64 v188, v188, v190, s[98:99]
	v_cndmask_b32_e64 v189, v189, v191, s[98:99]
	v_add_u32_e32 v190, 0x54000, v246
	global_store_dwordx2 v190, v[188:189], s[48:49] offset:256
	s_waitcnt vmcnt(12)
	v_pk_add_f32 v[20:21], v[20:21], v[204:205]
	v_pk_add_f32 v[18:19], v[18:19], v[202:203]
	v_pk_add_f32 v[12:13], v[12:13], v[208:209]
	v_pk_add_f32 v[10:11], v[10:11], v[206:207]
	v_pk_add_f32 v[8:9], v[8:9], v[212:213]
	v_pk_add_f32 v[6:7], v[6:7], v[210:211]
	v_pk_add_f32 v[4:5], v[4:5], v[216:217]
	v_pk_add_f32 v[2:3], v[2:3], v[214:215]
	v_cvt_pk_bf16_f32 v18, v18, v19
	v_cvt_pk_bf16_f32 v19, v20, v21
	v_cvt_pk_bf16_f32 v10, v10, v11
	v_cvt_pk_bf16_f32 v11, v12, v13
	v_cvt_pk_bf16_f32 v6, v6, v7
	v_cvt_pk_bf16_f32 v7, v8, v9
	v_cvt_pk_bf16_f32 v2, v2, v3
	v_cvt_pk_bf16_f32 v3, v4, v5
	ds_bpermute_b32 v202, v244, v18
	ds_bpermute_b32 v203, v244, v19
	ds_bpermute_b32 v204, v244, v10
	ds_bpermute_b32 v205, v244, v11
	ds_bpermute_b32 v206, v245, v18
	ds_bpermute_b32 v207, v245, v19
	ds_bpermute_b32 v208, v245, v10
	ds_bpermute_b32 v209, v245, v11
	s_waitcnt lgkmcnt(0)
	v_cndmask_b32_e64 v202, v202, v204, s[98:99]
	v_cndmask_b32_e64 v203, v203, v205, s[98:99]
	v_add_u32_e32 v204, 0x58000, v246
	global_store_dwordx2 v204, v[202:203], s[48:49]
	v_cndmask_b32_e64 v206, v206, v208, s[98:99]
	v_cndmask_b32_e64 v207, v207, v209, s[98:99]
	v_add_u32_e32 v208, 0x5c000, v246
	global_store_dwordx2 v208, v[206:207], s[48:49]
	ds_bpermute_b32 v202, v244, v6
	ds_bpermute_b32 v203, v244, v7
	ds_bpermute_b32 v204, v244, v2
	ds_bpermute_b32 v205, v244, v3
	ds_bpermute_b32 v206, v245, v6
	ds_bpermute_b32 v207, v245, v7
	ds_bpermute_b32 v208, v245, v2
	ds_bpermute_b32 v209, v245, v3
	s_waitcnt lgkmcnt(0)
	v_cndmask_b32_e64 v202, v202, v204, s[98:99]
	v_cndmask_b32_e64 v203, v203, v205, s[98:99]
	v_add_u32_e32 v204, 0x58000, v246
	global_store_dwordx2 v204, v[202:203], s[48:49] offset:256
	v_cndmask_b32_e64 v206, v206, v208, s[98:99]
	v_cndmask_b32_e64 v207, v207, v209, s[98:99]
	v_add_u32_e32 v208, 0x5c000, v246
	global_store_dwordx2 v208, v[206:207], s[48:49] offset:256
	s_and_b64 vcc, exec, s[20:21]
	s_mov_b32 s42, s40
	s_mov_b32 s43, s41
	s_mov_b64 s[22:23], 0x2c000
	s_cbranch_vccz .LBB0_1006
	s_waitcnt vmcnt(0)
	s_cmpk_gt_u32 s3, 0xff
	s_cbranch_scc1 .LBB0_1011
	s_barrier

; #define PG8_STAGE(bufoff, gbase, voff) do { _Pragma("unroll") for (int _i = 0; _i < 2; ++_i) \
;         __builtin_amdgcn_global_load_lds((const unsigned*)((const char*)(gbase) + (voff)[_i]), (LAS unsigned*)(lds + (bufoff) + ldsw + _i * 8192), 16, 0, 0); } while (0)
; #define PG8_LDA(dst, b, h) do { _Pragma("unroll") for (int m = 0; m < 4; ++m) _Pragma("unroll") for (int k = 0; k < 2; ++k) dst[m][k] = *(const LAS bf16x8*)(lds + PG8_SA(b, h) + aoff + m * 2048 + k * 1024); } while (0)
; #define PG8_LDB(dst, b, h) do { _Pragma("unroll") for (int n = 0; n < 2; ++n) _Pragma("unroll") for (int k = 0; k < 2; ++k) dst[n][k] = *(const LAS bf16x8*)(lds + PG8_SB(b, h) + boff + n * 2048 + k * 1024); } while (0)
; #define PG8_MMA(ai, bj, At, Bt) do { __builtin_amdgcn_s_setprio(1); _Pragma("unroll") for (int m = 0; m < 4; ++m) _Pragma("unroll") for (int n = 0; n < 2; ++n) _Pragma("unroll") for (int k = 0; k < 2; ++k) \
;         acc[ai][bj][m][n] = __builtin_amdgcn_mfma_f32_16x16x32_bf16(Bt[n][k], At[m][k], acc[ai][bj][m][n], 0, 0, 0); __builtin_amdgcn_s_setprio(0); } while (0)
; #define PG8_WAIT_L(n) asm volatile("s_waitcnt lgkmcnt(" #n ")" ::: "memory")
; #define PG8_BAR __builtin_amdgcn_s_barrier()
; #define PG8_SCHED __builtin_amdgcn_sched_barrier(0)
; template <class Epi, class Sched>
; DI void gemm_phase(LAS unsigned char* lds, const Gemm g, const Sched& S, const Epi& E) {
;     ...
;             PG8_LDB(B0, 0, 0); PG8_SCHED; PG8_LDA(At, 0, 0); PG8_STAGE(PG8_SA(1, 1), a1 + hstep, voffA);
;             PG8_WAIT_L(8); PG8_BAR; PG8_WAIT_L(0); PG8_MMA(0, 0, At, B0); PG8_BAR; PG8_SCHED;
;             PG8_LDB(B1, 0, 1); PG8_STAGE(PG8_SB(0, 0), b2, voffB);
;             PG8_BAR; PG8_WAIT_L(0); PG8_MMA(0, 1, At, B1); PG8_BAR;
;             PG8_LDA(At, 0, 1); PG8_STAGE(PG8_SA(0, 0), a2, voffA);
;             PG8_BAR; PG8_WAIT_L(0); PG8_MMA(1, 0, At, B0); PG8_BAR; PG8_SCHED;
.LBB0_1523:
	ds_read_b128 v[140:143], v146
	ds_read_b128 v[150:153], v146 offset:1024
	ds_read_b128 v[154:157], v146 offset:2048
	ds_read_b128 v[158:161], v146 offset:3072
	s_add_u32 s50, s42, 0xfff80080
	s_addc_u32 s51, s43, -1
	s_cmp_eq_u32 s73, 28
	s_cselect_b32 s53, s67, s51
	s_cselect_b32 s52, s68, s50
	s_cselect_b32 s51, s69, s72
	s_cselect_b32 s50, s70, s71
	v_lshl_add_u64 v[202:203], s[42:43], 0, v[136:137]
	s_add_i32 m0, s47, 0xc000
	ds_read_b128 v[168:171], v147
	ds_read_b128 v[172:175], v147 offset:1024
	ds_read_b128 v[176:179], v147 offset:2048
	ds_read_b128 v[180:183], v147 offset:3072
	ds_read_b128 v[184:187], v147 offset:4096
	ds_read_b128 v[188:191], v147 offset:5120
	ds_read_b128 v[192:195], v147 offset:6144
	ds_read_b128 v[198:201], v147 offset:7168
	global_load_lds_dwordx4 v[202:203], off
	v_lshl_add_u64 v[202:203], s[42:43], 0, v[138:139]
	s_add_i32 m0, s47, 0xe000
	s_nop 0
	global_load_lds_dwordx4 v[202:203], off
	s_waitcnt lgkmcnt(8)
	s_barrier
	s_waitcnt lgkmcnt(0)
	s_setprio 1
	s_waitcnt lgkmcnt(0)
	v_mfma_f32_16x16x32_bf16 v[126:129], v[140:143], v[168:171], v[126:129]
	v_mfma_f32_16x16x32_bf16 v[122:125], v[154:157], v[168:171], v[122:125]
	v_mfma_f32_16x16x32_bf16 v[110:113], v[140:143], v[176:179], v[110:113]
	v_mfma_f32_16x16x32_bf16 v[106:109], v[154:157], v[176:179], v[106:109]
	v_mfma_f32_16x16x32_bf16 v[94:97], v[140:143], v[184:187], v[94:97]
	v_mfma_f32_16x16x32_bf16 v[90:93], v[154:157], v[184:187], v[90:93]
	v_mfma_f32_16x16x32_bf16 v[78:81], v[140:143], v[192:195], v[78:81]
	v_mfma_f32_16x16x32_bf16 v[74:77], v[154:157], v[192:195], v[74:77]
	v_mfma_f32_16x16x32_bf16 v[126:129], v[150:153], v[172:175], v[126:129]
	v_mfma_f32_16x16x32_bf16 v[122:125], v[158:161], v[172:175], v[122:125]
	v_mfma_f32_16x16x32_bf16 v[110:113], v[150:153], v[180:183], v[110:113]
	v_mfma_f32_16x16x32_bf16 v[106:109], v[158:161], v[180:183], v[106:109]
	v_mfma_f32_16x16x32_bf16 v[94:97], v[150:153], v[188:191], v[94:97]
	v_mfma_f32_16x16x32_bf16 v[90:93], v[158:161], v[188:191], v[90:93]
	v_mfma_f32_16x16x32_bf16 v[78:81], v[150:153], v[198:201], v[78:81]
	v_mfma_f32_16x16x32_bf16 v[74:77], v[158:161], v[198:201], v[74:77]
	s_setprio 0
	s_barrier
	s_add_i32 s83, s63, s33
	v_lshl_add_u64 v[218:219], s[50:51], 0, v[132:133]
	s_mov_b32 m0, s83
	ds_read_b128 v[202:205], v148
	ds_read_b128 v[206:209], v148 offset:1024
	ds_read_b128 v[210:213], v148 offset:2048
	ds_read_b128 v[214:217], v148 offset:3072
	global_load_lds_dwordx4 v[218:219], off
	v_lshl_add_u64 v[220:221], s[50:51], 0, v[130:131]
	s_add_i32 m0, s83, 0x2000
	s_nop 0
	global_load_lds_dwordx4 v[220:221], off
	s_barrier
	s_waitcnt lgkmcnt(0)
	s_setprio 1
	s_waitcnt lgkmcnt(0)
	v_mfma_f32_16x16x32_bf16 v[118:121], v[202:205], v[168:171], v[118:121]
	v_mfma_f32_16x16x32_bf16 v[114:117], v[210:213], v[168:171], v[114:117]
	v_mfma_f32_16x16x32_bf16 v[102:105], v[202:205], v[176:179], v[102:105]
	v_mfma_f32_16x16x32_bf16 v[98:101], v[210:213], v[176:179], v[98:101]
	v_mfma_f32_16x16x32_bf16 v[86:89], v[202:205], v[184:187], v[86:89]
	v_mfma_f32_16x16x32_bf16 v[82:85], v[210:213], v[184:187], v[82:85]
	v_mfma_f32_16x16x32_bf16 v[70:73], v[202:205], v[192:195], v[70:73]
	v_mfma_f32_16x16x32_bf16 v[66:69], v[210:213], v[192:195], v[66:69]
	v_mfma_f32_16x16x32_bf16 v[118:121], v[206:209], v[172:175], v[118:121]
	v_mfma_f32_16x16x32_bf16 v[114:117], v[214:217], v[172:175], v[114:117]
	v_mfma_f32_16x16x32_bf16 v[102:105], v[206:209], v[180:183], v[102:105]
	v_mfma_f32_16x16x32_bf16 v[98:101], v[214:217], v[180:183], v[98:101]
	v_mfma_f32_16x16x32_bf16 v[86:89], v[206:209], v[188:191], v[86:89]
	v_mfma_f32_16x16x32_bf16 v[82:85], v[214:217], v[188:191], v[82:85]
	v_mfma_f32_16x16x32_bf16 v[70:73], v[206:209], v[198:201], v[70:73]
	v_mfma_f32_16x16x32_bf16 v[66:69], v[214:217], v[198:201], v[66:69]
	s_setprio 0
	s_mov_b32 m0, s47
	v_lshl_add_u64 v[222:223], s[52:53], 0, v[132:133]
	s_barrier
	ds_read_b128 v[168:171], v147 offset:16384
	ds_read_b128 v[172:175], v147 offset:17408
	ds_read_b128 v[176:179], v147 offset:18432
	ds_read_b128 v[180:183], v147 offset:19456
	ds_read_b128 v[184:187], v147 offset:20480
	ds_read_b128 v[188:191], v147 offset:21504
	ds_read_b128 v[192:195], v147 offset:22528
	ds_read_b128 v[198:201], v147 offset:23552
	global_load_lds_dwordx4 v[222:223], off
	v_lshl_add_u64 v[224:225], s[52:53], 0, v[130:131]
	s_mov_b32 m0, s54
	s_nop 0
	global_load_lds_dwordx4 v[224:225], off
	s_barrier
	s_waitcnt lgkmcnt(0)
	s_setprio 1
	s_waitcnt lgkmcnt(0)
	v_mfma_f32_16x16x32_bf16 v[62:65], v[140:143], v[168:171], v[62:65]
	v_mfma_f32_16x16x32_bf16 v[58:61], v[154:157], v[168:171], v[58:61]
	v_mfma_f32_16x16x32_bf16 v[46:49], v[140:143], v[176:179], v[46:49]
	v_mfma_f32_16x16x32_bf16 v[42:45], v[154:157], v[176:179], v[42:45]
	v_mfma_f32_16x16x32_bf16 v[30:33], v[140:143], v[184:187], v[30:33]
	v_mfma_f32_16x16x32_bf16 v[26:29], v[154:157], v[184:187], v[26:29]
	v_mfma_f32_16x16x32_bf16 v[14:17], v[140:143], v[192:195], v[14:17]
	v_mfma_f32_16x16x32_bf16 v[10:13], v[154:157], v[192:195], v[10:13]
	v_mfma_f32_16x16x32_bf16 v[62:65], v[150:153], v[172:175], v[62:65]
	v_mfma_f32_16x16x32_bf16 v[58:61], v[158:161], v[172:175], v[58:61]
	v_mfma_f32_16x16x32_bf16 v[46:49], v[150:153], v[180:183], v[46:49]
	v_mfma_f32_16x16x32_bf16 v[42:45], v[158:161], v[180:183], v[42:45]
	v_mfma_f32_16x16x32_bf16 v[30:33], v[150:153], v[188:191], v[30:33]
	v_mfma_f32_16x16x32_bf16 v[26:29], v[158:161], v[188:191], v[26:29]
	v_mfma_f32_16x16x32_bf16 v[14:17], v[150:153], v[198:201], v[14:17]
	v_mfma_f32_16x16x32_bf16 v[10:13], v[158:161], v[198:201], v[10:13]
	s_setprio 0
	s_barrier
; #define PG8_STAGE(bufoff, gbase, voff) do { _Pragma("unroll") for (int _i = 0; _i < 2; ++_i) \
;         __builtin_amdgcn_global_load_lds((const unsigned*)((const char*)(gbase) + (voff)[_i]), (LAS unsigned*)(lds + (bufoff) + ldsw + _i * 8192), 16, 0, 0); } while (0)
; #define PG8_LDA(dst, b, h) do { _Pragma("unroll") for (int m = 0; m < 4; ++m) _Pragma("unroll") for (int k = 0; k < 2; ++k) dst[m][k] = *(const LAS bf16x8*)(lds + PG8_SA(b, h) + aoff + m * 2048 + k * 1024); } while (0)
; #define PG8_LDB(dst, b, h) do { _Pragma("unroll") for (int n = 0; n < 2; ++n) _Pragma("unroll") for (int k = 0; k < 2; ++k) dst[n][k] = *(const LAS bf16x8*)(lds + PG8_SB(b, h) + boff + n * 2048 + k * 1024); } while (0)
; #define PG8_MMA(ai, bj, At, Bt) do { __builtin_amdgcn_s_setprio(1); _Pragma("unroll") for (int m = 0; m < 4; ++m) _Pragma("unroll") for (int n = 0; n < 2; ++n) _Pragma("unroll") for (int k = 0; k < 2; ++k) \
;         acc[ai][bj][m][n] = __builtin_amdgcn_mfma_f32_16x16x32_bf16(Bt[n][k], At[m][k], acc[ai][bj][m][n], 0, 0, 0); __builtin_amdgcn_s_setprio(0); } while (0)
; #define PG8_WAIT_V(n) asm volatile("s_waitcnt vmcnt(" #n ")" ::: "memory")
; #define PG8_WAIT_L(n) asm volatile("s_waitcnt lgkmcnt(" #n ")" ::: "memory")
; #define PG8_BAR __builtin_amdgcn_s_barrier()
; #define PG8_SCHED __builtin_amdgcn_sched_barrier(0)
; template <class Epi, class Sched>
; DI void gemm_phase(LAS unsigned char* lds, const Gemm g, const Sched& S, const Epi& E) {
;     ...
;             PG8_BAR; PG8_WAIT_L(0); PG8_MMA(1, 0, At, B0); PG8_BAR; PG8_SCHED;
;             PG8_STAGE(PG8_SB(0, 1), b2 + hstep, voffB);
;             PG8_WAIT_V(6); PG8_BAR; PG8_MMA(1, 1, At, B1); PG8_BAR;
;             PG8_LDB(B0, 1, 0); PG8_SCHED; PG8_LDA(At, 1, 0); PG8_STAGE(PG8_SA(0, 1), a2 + hstep, voffA);
;             PG8_WAIT_L(8); PG8_BAR; PG8_WAIT_L(0); PG8_MMA(0, 0, At, B0); PG8_BAR; PG8_SCHED;
;             PG8_LDB(B1, 1, 1); PG8_STAGE(PG8_SB(1, 0), b3, voffB);
;             PG8_BAR; PG8_WAIT_L(0); PG8_MMA(0, 1, At, B1); PG8_BAR;
;             PG8_LDA(At, 1, 1); PG8_STAGE(PG8_SA(1, 0), a3, voffA);
	s_add_u32 s88, s50, 0x80000
	s_addc_u32 s89, s51, 0
	s_add_i32 s83, s64, s33
	v_lshl_add_u64 v[140:141], s[88:89], 0, v[132:133]
	s_mov_b32 m0, s83
	s_nop 0
	global_load_lds_dwordx4 v[140:141], off
	v_lshl_add_u64 v[140:141], s[88:89], 0, v[130:131]
	s_add_i32 m0, s83, 0x2000
	s_nop 0
	global_load_lds_dwordx4 v[140:141], off
	s_waitcnt vmcnt(6)
	s_barrier
	s_setprio 1
	v_mfma_f32_16x16x32_bf16 v[54:57], v[202:205], v[168:171], v[54:57]
	v_mfma_f32_16x16x32_bf16 v[50:53], v[210:213], v[168:171], v[50:53]
	v_mfma_f32_16x16x32_bf16 v[38:41], v[202:205], v[176:179], v[38:41]
	v_mfma_f32_16x16x32_bf16 v[34:37], v[210:213], v[176:179], v[34:37]
	v_mfma_f32_16x16x32_bf16 v[22:25], v[202:205], v[184:187], v[22:25]
	v_mfma_f32_16x16x32_bf16 v[18:21], v[210:213], v[184:187], v[18:21]
	v_mfma_f32_16x16x32_bf16 v[6:9], v[202:205], v[192:195], v[6:9]
	v_mfma_f32_16x16x32_bf16 v[2:5], v[210:213], v[192:195], v[2:5]
	v_mfma_f32_16x16x32_bf16 v[54:57], v[206:209], v[172:175], v[54:57]
	v_mfma_f32_16x16x32_bf16 v[50:53], v[214:217], v[172:175], v[50:53]
	v_mfma_f32_16x16x32_bf16 v[38:41], v[206:209], v[180:183], v[38:41]
	v_mfma_f32_16x16x32_bf16 v[34:37], v[214:217], v[180:183], v[34:37]
	v_mfma_f32_16x16x32_bf16 v[22:25], v[206:209], v[188:191], v[22:25]
	v_mfma_f32_16x16x32_bf16 v[18:21], v[214:217], v[188:191], v[18:21]
	v_mfma_f32_16x16x32_bf16 v[6:9], v[206:209], v[198:201], v[6:9]
	v_mfma_f32_16x16x32_bf16 v[2:5], v[214:217], v[198:201], v[2:5]
	s_setprio 0
	s_add_i32 s83, 0, 0x18000
	v_add_u32_e32 v134, s83, v145
	s_barrier
	ds_read_b128 v[140:143], v134
	ds_read_b128 v[150:153], v134 offset:1024
	ds_read_b128 v[154:157], v134 offset:2048
	ds_read_b128 v[158:161], v134 offset:3072
	s_add_u32 s52, s52, 0x80000
	s_addc_u32 s53, s53, 0
	s_mov_b32 m0, s55
	v_lshl_add_u64 v[202:203], s[52:53], 0, v[132:133]
	ds_read_b128 v[168:171], v147 offset:32768
	ds_read_b128 v[172:175], v147 offset:33792
	ds_read_b128 v[176:179], v147 offset:34816
	ds_read_b128 v[180:183], v147 offset:35840
	ds_read_b128 v[184:187], v147 offset:36864
	ds_read_b128 v[188:191], v147 offset:37888
	ds_read_b128 v[192:195], v147 offset:38912
	ds_read_b128 v[198:201], v147 offset:39936
	global_load_lds_dwordx4 v[202:203], off
	v_lshl_add_u64 v[202:203], s[52:53], 0, v[130:131]
	s_mov_b32 m0, s57
	s_nop 0
	global_load_lds_dwordx4 v[202:203], off
	s_waitcnt lgkmcnt(8)
	s_barrier
	s_waitcnt lgkmcnt(0)
	s_setprio 1
	s_waitcnt lgkmcnt(0)
	v_mfma_f32_16x16x32_bf16 v[126:129], v[140:143], v[168:171], v[126:129]
	v_mfma_f32_16x16x32_bf16 v[122:125], v[154:157], v[168:171], v[122:125]
	v_mfma_f32_16x16x32_bf16 v[110:113], v[140:143], v[176:179], v[110:113]
	v_mfma_f32_16x16x32_bf16 v[106:109], v[154:157], v[176:179], v[106:109]
	v_mfma_f32_16x16x32_bf16 v[94:97], v[140:143], v[184:187], v[94:97]
	v_mfma_f32_16x16x32_bf16 v[90:93], v[154:157], v[184:187], v[90:93]
	v_mfma_f32_16x16x32_bf16 v[78:81], v[140:143], v[192:195], v[78:81]
	v_mfma_f32_16x16x32_bf16 v[74:77], v[154:157], v[192:195], v[74:77]
	v_mfma_f32_16x16x32_bf16 v[126:129], v[150:153], v[172:175], v[126:129]
	v_mfma_f32_16x16x32_bf16 v[122:125], v[158:161], v[172:175], v[122:125]
	v_mfma_f32_16x16x32_bf16 v[110:113], v[150:153], v[180:183], v[110:113]
	v_mfma_f32_16x16x32_bf16 v[106:109], v[158:161], v[180:183], v[106:109]
	v_mfma_f32_16x16x32_bf16 v[94:97], v[150:153], v[188:191], v[94:97]
	v_mfma_f32_16x16x32_bf16 v[90:93], v[158:161], v[188:191], v[90:93]
	v_mfma_f32_16x16x32_bf16 v[78:81], v[150:153], v[198:201], v[78:81]
	v_mfma_f32_16x16x32_bf16 v[74:77], v[158:161], v[198:201], v[74:77]
	s_setprio 0
	s_barrier
	s_add_i32 s52, 0, 0x1c000
	s_add_i32 s53, s83, s33
	v_add_u32_e32 v134, s52, v145
	v_lshl_add_u64 v[218:219], v[218:219], 0, s[10:11]
	s_mov_b32 m0, s53
	ds_read_b128 v[202:205], v134
	ds_read_b128 v[206:209], v134 offset:1024
	ds_read_b128 v[210:213], v134 offset:2048
	ds_read_b128 v[214:217], v134 offset:3072
	global_load_lds_dwordx4 v[218:219], off
	v_lshl_add_u64 v[218:219], v[220:221], 0, s[10:11]
	s_add_i32 m0, s53, 0x2000
	s_nop 0
	global_load_lds_dwordx4 v[218:219], off
	s_barrier
	s_waitcnt lgkmcnt(0)
	s_setprio 1
	s_waitcnt lgkmcnt(0)
	v_mfma_f32_16x16x32_bf16 v[118:121], v[202:205], v[168:171], v[118:121]
	v_mfma_f32_16x16x32_bf16 v[114:117], v[210:213], v[168:171], v[114:117]
	v_mfma_f32_16x16x32_bf16 v[102:105], v[202:205], v[176:179], v[102:105]
	v_mfma_f32_16x16x32_bf16 v[98:101], v[210:213], v[176:179], v[98:101]
	v_mfma_f32_16x16x32_bf16 v[86:89], v[202:205], v[184:187], v[86:89]
	v_mfma_f32_16x16x32_bf16 v[82:85], v[210:213], v[184:187], v[82:85]
	v_mfma_f32_16x16x32_bf16 v[70:73], v[202:205], v[192:195], v[70:73]
	v_mfma_f32_16x16x32_bf16 v[66:69], v[210:213], v[192:195], v[66:69]
	v_mfma_f32_16x16x32_bf16 v[118:121], v[206:209], v[172:175], v[118:121]
	v_mfma_f32_16x16x32_bf16 v[114:117], v[214:217], v[172:175], v[114:117]
	v_mfma_f32_16x16x32_bf16 v[102:105], v[206:209], v[180:183], v[102:105]
	v_mfma_f32_16x16x32_bf16 v[98:101], v[214:217], v[180:183], v[98:101]
	v_mfma_f32_16x16x32_bf16 v[86:89], v[206:209], v[188:191], v[86:89]
	v_mfma_f32_16x16x32_bf16 v[82:85], v[214:217], v[188:191], v[82:85]
	v_mfma_f32_16x16x32_bf16 v[70:73], v[206:209], v[198:201], v[70:73]
	v_mfma_f32_16x16x32_bf16 v[66:69], v[214:217], v[198:201], v[66:69]
	s_setprio 0
	s_mov_b32 m0, s59
	v_lshl_add_u64 v[218:219], v[222:223], 0, s[10:11]
	s_barrier
	ds_read_b128 v[168:171], v147 offset:49152
	ds_read_b128 v[172:175], v147 offset:50176
	ds_read_b128 v[176:179], v147 offset:51200
	ds_read_b128 v[180:183], v147 offset:52224
	ds_read_b128 v[184:187], v147 offset:53248
	ds_read_b128 v[188:191], v147 offset:54272
	ds_read_b128 v[192:195], v147 offset:55296
	ds_read_b128 v[198:201], v147 offset:56320
	global_load_lds_dwordx4 v[218:219], off
	v_lshl_add_u64 v[218:219], v[224:225], 0, s[10:11]
	s_mov_b32 m0, s62
	s_nop 0
	global_load_lds_dwordx4 v[218:219], off
	s_barrier
; DI float bflo(unsigned u) { return __uint_as_float(u << 16); }
; DI float bfhi(unsigned u) { return __uint_as_float(u & 0xffff0000u); }
; #define PG8_STAGE(bufoff, gbase, voff) do { _Pragma("unroll") for (int _i = 0; _i < 2; ++_i) \
;         __builtin_amdgcn_global_load_lds((const unsigned*)((const char*)(gbase) + (voff)[_i]), (LAS unsigned*)(lds + (bufoff) + ldsw + _i * 8192), 16, 0, 0); } while (0)
; #define PG8_MMA(ai, bj, At, Bt) do { __builtin_amdgcn_s_setprio(1); _Pragma("unroll") for (int m = 0; m < 4; ++m) _Pragma("unroll") for (int n = 0; n < 2; ++n) _Pragma("unroll") for (int k = 0; k < 2; ++k) \
;         acc[ai][bj][m][n] = __builtin_amdgcn_mfma_f32_16x16x32_bf16(Bt[n][k], At[m][k], acc[ai][bj][m][n], 0, 0, 0); __builtin_amdgcn_s_setprio(0); } while (0)
; #define PG8_WAIT_V(n) asm volatile("s_waitcnt vmcnt(" #n ")" ::: "memory")
; #define PG8_WAIT_L(n) asm volatile("s_waitcnt lgkmcnt(" #n ")" ::: "memory")
; #define PG8_BAR __builtin_amdgcn_s_barrier()
; #define PG8_SCHED __builtin_amdgcn_sched_barrier(0)
;     DI void operator()(const f32x4 (&acc)[2][2][4][2], const Unit& u, int wr, int wc, int fr, int fq) const {
;     ...
;             for (int m = 0; m < 4; ++m) { const size_t o = (size_t)(row0 + ai * HALF + m * 16) * 1024 + col0;
; #pragma unroll
;                 for (int bj = 0; bj < 2; ++bj)
; #pragma unroll
;                     for (int n = 0; n < 2; ++n) { const size_t oo = o + bj * HALF + n * 16; f32x4 rv;
;                         if (RES_BF16) { const u32x2 t = *(const u32x2*)((const bf16_t*)res + oo); rv = (f32x4){bflo(t.x), bfhi(t.x), bflo(t.y), bfhi(t.y)}; }
;                         else rv = *(const f32x4*)((const float*)res + oo);
; template <class Epi, class Sched>
; DI void gemm_phase(LAS unsigned char* lds, const Gemm g, const Sched& S, const Epi& E) {
;     ...
;             PG8_BAR; PG8_WAIT_L(0); PG8_MMA(1, 0, At, B0); PG8_BAR; PG8_SCHED;
;             PG8_STAGE(PG8_SB(1, 1), b3 + hstep, voffB);
;             PG8_WAIT_V(6); PG8_BAR; PG8_MMA(1, 1, At, B1); PG8_BAR;
	s_waitcnt lgkmcnt(0)
	s_setprio 1
	s_waitcnt lgkmcnt(0)
	v_mfma_f32_16x16x32_bf16 v[62:65], v[140:143], v[168:171], v[62:65]
	v_mfma_f32_16x16x32_bf16 v[58:61], v[154:157], v[168:171], v[58:61]
	v_mfma_f32_16x16x32_bf16 v[46:49], v[140:143], v[176:179], v[46:49]
	v_mfma_f32_16x16x32_bf16 v[42:45], v[154:157], v[176:179], v[42:45]
	v_mfma_f32_16x16x32_bf16 v[30:33], v[140:143], v[184:187], v[30:33]
	v_mfma_f32_16x16x32_bf16 v[26:29], v[154:157], v[184:187], v[26:29]
	v_mfma_f32_16x16x32_bf16 v[14:17], v[140:143], v[192:195], v[14:17]
	v_mfma_f32_16x16x32_bf16 v[10:13], v[154:157], v[192:195], v[10:13]
	v_mfma_f32_16x16x32_bf16 v[62:65], v[150:153], v[172:175], v[62:65]
	v_mfma_f32_16x16x32_bf16 v[58:61], v[158:161], v[172:175], v[58:61]
	v_mfma_f32_16x16x32_bf16 v[46:49], v[150:153], v[180:183], v[46:49]
	v_mfma_f32_16x16x32_bf16 v[42:45], v[158:161], v[180:183], v[42:45]
	v_mfma_f32_16x16x32_bf16 v[30:33], v[150:153], v[188:191], v[30:33]
	v_mfma_f32_16x16x32_bf16 v[26:29], v[158:161], v[188:191], v[26:29]
	v_mfma_f32_16x16x32_bf16 v[14:17], v[150:153], v[198:201], v[14:17]
	v_mfma_f32_16x16x32_bf16 v[10:13], v[158:161], v[198:201], v[10:13]
	s_setprio 0
	s_barrier
	s_add_u32 s50, s50, 0x80080
	s_addc_u32 s51, s51, 0
	s_add_i32 s52, s52, s33
	v_lshl_add_u64 v[140:141], s[50:51], 0, v[132:133]
	s_mov_b32 m0, s52
	s_nop 0
	global_load_lds_dwordx4 v[140:141], off
	v_lshl_add_u64 v[140:141], s[50:51], 0, v[130:131]
	s_add_i32 m0, s52, 0x2000
	s_nop 0
	global_load_lds_dwordx4 v[140:141], off
	s_waitcnt vmcnt(6)
	s_barrier
	s_setprio 1
	v_mfma_f32_16x16x32_bf16 v[54:57], v[202:205], v[168:171], v[54:57]
	v_mfma_f32_16x16x32_bf16 v[50:53], v[210:213], v[168:171], v[50:53]
	v_mfma_f32_16x16x32_bf16 v[38:41], v[202:205], v[176:179], v[38:41]
	v_mfma_f32_16x16x32_bf16 v[34:37], v[210:213], v[176:179], v[34:37]
	v_mfma_f32_16x16x32_bf16 v[22:25], v[202:205], v[184:187], v[22:25]
	v_mfma_f32_16x16x32_bf16 v[18:21], v[210:213], v[184:187], v[18:21]
	v_mfma_f32_16x16x32_bf16 v[6:9], v[202:205], v[192:195], v[6:9]
	v_mfma_f32_16x16x32_bf16 v[2:5], v[210:213], v[192:195], v[2:5]
	v_mfma_f32_16x16x32_bf16 v[54:57], v[206:209], v[172:175], v[54:57]
	v_mfma_f32_16x16x32_bf16 v[50:53], v[214:217], v[172:175], v[50:53]
	v_mfma_f32_16x16x32_bf16 v[38:41], v[206:209], v[180:183], v[38:41]
	v_mfma_f32_16x16x32_bf16 v[34:37], v[214:217], v[180:183], v[34:37]
	v_mfma_f32_16x16x32_bf16 v[22:25], v[206:209], v[188:191], v[22:25]
	v_mfma_f32_16x16x32_bf16 v[18:21], v[214:217], v[188:191], v[18:21]
	v_mfma_f32_16x16x32_bf16 v[6:9], v[206:209], v[198:201], v[6:9]
	v_mfma_f32_16x16x32_bf16 v[2:5], v[214:217], v[198:201], v[2:5]
	s_setprio 0
	s_add_i32 s73, s73, 2
	s_add_u32 s42, s42, 0x100
	s_addc_u32 s43, s43, 0
	s_add_u32 s71, s71, 0x100
	s_addc_u32 s72, s72, 0
	s_cmp_gt_u32 s73, 29
	s_barrier
	s_cbranch_scc0 .LBB0_1523
	v_lshl_add_u32 v236, s56, 8, v144
	v_lshl_or_b32 v237, s84, 9, v149
	v_lshl_or_b32 v236, v236, 11, v237
	v_mov_b32_e32 v228, v236
	v_add_u32_e32 v229, 0x8000, v236
	v_add_u32_e32 v230, 0x10000, v236
	v_add_u32_e32 v231, 0x18000, v236
	v_add_u32_e32 v232, 0x40000, v236
	v_add_u32_e32 v233, 0x48000, v236
	v_add_u32_e32 v234, 0x50000, v236
	v_add_u32_e32 v235, 0x58000, v236
	v_and_b32_e32 v248, 63, v1
	v_lshrrev_b32_e32 v249, 3, v248
	v_and_b32_e32 v250, 3, v248
	v_lshl_or_b32 v250, v250, 4, v249
	v_lshlrev_b32_e32 v244, 2, v250
	v_add_u32_e32 v245, 32, v244
	v_and_b32_e32 v250, 0xffffffc0, v144
	v_add_u32_e32 v250, v250, v249
	v_lshl_add_u32 v250, s56, 8, v250
	v_mul_u32_u24_e32 v250, 0x800, v250
	v_and_b32_e32 v247, 0xffffffc0, v149
	v_lshl_or_b32 v247, s84, 9, v247
	v_and_b32_e32 v248, 7, v248
	v_lshl_add_u32 v247, v248, 3, v247
	v_add_u32_e32 v246, v250, v247
	s_mov_b32 s98, 0xf0f0f0f0
	s_mov_b32 s99, 0xf0f0f0f0
	global_load_dwordx2 v[140:141], v228, s[48:49]
	global_load_dwordx2 v[142:143], v228, s[48:49] offset:32
	global_load_dwordx2 v[150:151], v228, s[48:49] offset:256
	global_load_dwordx2 v[152:153], v228, s[48:49] offset:288
	global_load_dwordx2 v[154:155], v229, s[48:49]
	global_load_dwordx2 v[156:157], v229, s[48:49] offset:32
	global_load_dwordx2 v[158:159], v229, s[48:49] offset:256
	global_load_dwordx2 v[160:161], v229, s[48:49] offset:288
	global_load_dwordx2 v[168:169], v230, s[48:49]
	global_load_dwordx2 v[170:171], v230, s[48:49] offset:32
	global_load_dwordx2 v[172:173], v230, s[48:49] offset:256
	global_load_dwordx2 v[174:175], v230, s[48:49] offset:288
	global_load_dwordx2 v[176:177], v231, s[48:49]
	global_load_dwordx2 v[178:179], v231, s[48:49] offset:32
	global_load_dwordx2 v[180:181], v231, s[48:49] offset:256
	global_load_dwordx2 v[182:183], v231, s[48:49] offset:288
	global_load_dwordx2 v[184:185], v232, s[48:49]
	global_load_dwordx2 v[186:187], v232, s[48:49] offset:32
	global_load_dwordx2 v[188:189], v232, s[48:49] offset:256
	global_load_dwordx2 v[190:191], v232, s[48:49] offset:288
	global_load_dwordx2 v[192:193], v233, s[48:49]
	global_load_dwordx2 v[194:195], v233, s[48:49] offset:32
	global_load_dwordx2 v[198:199], v233, s[48:49] offset:256
	global_load_dwordx2 v[200:201], v233, s[48:49] offset:288
	global_load_dwordx2 v[202:203], v234, s[48:49]
	global_load_dwordx2 v[204:205], v234, s[48:49] offset:32
	global_load_dwordx2 v[206:207], v234, s[48:49] offset:256
	global_load_dwordx2 v[208:209], v234, s[48:49] offset:288
	global_load_dwordx2 v[210:211], v235, s[48:49]
	global_load_dwordx2 v[212:213], v235, s[48:49] offset:32
	global_load_dwordx2 v[214:215], v235, s[48:49] offset:256
	global_load_dwordx2 v[216:217], v235, s[48:49] offset:288
	s_waitcnt vmcnt(28)
; DI unsigned pk_bf16(float a, float b) { f32x2 v = {a, b}; bf2_t r = __builtin_convertvector(v, bf2_t); return __builtin_bit_cast(unsigned, r); }
; DI float bflo(unsigned u) { return __uint_as_float(u << 16); }
; DI float bfhi(unsigned u) { return __uint_as_float(u & 0xffff0000u); }
;     DI void operator()(const f32x4 (&acc)[2][2][4][2], const Unit& u, int wr, int wc, int fr, int fq) const {
;     ...
;             for (int m = 0; m < 4; ++m) { const size_t o = (size_t)(row0 + ai * HALF + m * 16) * 1024 + col0;
; #pragma unroll
;                 for (int bj = 0; bj < 2; ++bj)
; #pragma unroll
;                     for (int n = 0; n < 2; ++n) { const size_t oo = o + bj * HALF + n * 16; f32x4 rv;
;                         if (RES_BF16) { const u32x2 t = *(const u32x2*)((const bf16_t*)res + oo); rv = (f32x4){bflo(t.x), bfhi(t.x), bflo(t.y), bfhi(t.y)}; }
;                         else rv = *(const f32x4*)((const float*)res + oo);
;                         const f32x4 v = acc[ai][bj][m][n] + rv; u32x2 w; w.x = pk_bf16(v.x, v.y); w.y = pk_bf16(v.z, v.w);
;                         *(u32x2*)(O + oo) = w; } }
	v_lshlrev_b32_e32 v226, 16, v141
	v_and_b32_e32 v227, 0xffff0000, v141
	v_and_b32_e32 v141, 0xffff0000, v140
	v_lshlrev_b32_e32 v140, 16, v140
	v_pk_add_f32 v[128:129], v[128:129], v[226:227]
	v_pk_add_f32 v[126:127], v[126:127], v[140:141]
	v_lshlrev_b32_e32 v240, 16, v143
	v_and_b32_e32 v241, 0xffff0000, v143
	v_and_b32_e32 v143, 0xffff0000, v142
	v_lshlrev_b32_e32 v142, 16, v142
	v_pk_add_f32 v[124:125], v[124:125], v[240:241]
	v_pk_add_f32 v[122:123], v[122:123], v[142:143]
	v_lshlrev_b32_e32 v226, 16, v151
	v_and_b32_e32 v227, 0xffff0000, v151
	v_and_b32_e32 v151, 0xffff0000, v150
	v_lshlrev_b32_e32 v150, 16, v150
	v_pk_add_f32 v[120:121], v[120:121], v[226:227]
	v_pk_add_f32 v[118:119], v[118:119], v[150:151]
	v_lshlrev_b32_e32 v240, 16, v153
	v_and_b32_e32 v241, 0xffff0000, v153
	v_and_b32_e32 v153, 0xffff0000, v152
	v_lshlrev_b32_e32 v152, 16, v152
	v_pk_add_f32 v[116:117], v[116:117], v[240:241]
	v_pk_add_f32 v[114:115], v[114:115], v[152:153]
	v_cvt_pk_bf16_f32 v126, v126, v127
	v_cvt_pk_bf16_f32 v127, v128, v129
	v_cvt_pk_bf16_f32 v122, v122, v123
	v_cvt_pk_bf16_f32 v123, v124, v125
	v_cvt_pk_bf16_f32 v118, v118, v119
	v_cvt_pk_bf16_f32 v119, v120, v121
	v_cvt_pk_bf16_f32 v114, v114, v115
	v_cvt_pk_bf16_f32 v115, v116, v117
	ds_bpermute_b32 v140, v244, v126
	ds_bpermute_b32 v141, v244, v127
	ds_bpermute_b32 v142, v244, v122
	ds_bpermute_b32 v143, v244, v123
	ds_bpermute_b32 v150, v245, v126
	ds_bpermute_b32 v151, v245, v127
	ds_bpermute_b32 v152, v245, v122
	ds_bpermute_b32 v153, v245, v123
	s_waitcnt lgkmcnt(0)
	v_cndmask_b32_e64 v140, v140, v142, s[98:99]
	v_cndmask_b32_e64 v141, v141, v143, s[98:99]
	v_mov_b32_e32 v142, v246
	global_store_dwordx2 v142, v[140:141], s[8:9]
	v_cndmask_b32_e64 v150, v150, v152, s[98:99]
	v_cndmask_b32_e64 v151, v151, v153, s[98:99]
	v_add_u32_e32 v152, 0x4000, v246
	global_store_dwordx2 v152, v[150:151], s[8:9]
	ds_bpermute_b32 v140, v244, v118
	ds_bpermute_b32 v141, v244, v119
	ds_bpermute_b32 v142, v244, v114
	ds_bpermute_b32 v143, v244, v115
	ds_bpermute_b32 v150, v245, v118
	ds_bpermute_b32 v151, v245, v119
	ds_bpermute_b32 v152, v245, v114
	ds_bpermute_b32 v153, v245, v115
	s_waitcnt lgkmcnt(0)
	v_cndmask_b32_e64 v140, v140, v142, s[98:99]
	v_cndmask_b32_e64 v141, v141, v143, s[98:99]
	v_mov_b32_e32 v142, v246
	global_store_dwordx2 v142, v[140:141], s[8:9] offset:256
	v_cndmask_b32_e64 v150, v150, v152, s[98:99]
	v_cndmask_b32_e64 v151, v151, v153, s[98:99]
	v_add_u32_e32 v152, 0x4000, v246
	global_store_dwordx2 v152, v[150:151], s[8:9] offset:256
	s_waitcnt vmcnt(28)
	v_lshlrev_b32_e32 v226, 16, v155
	v_and_b32_e32 v227, 0xffff0000, v155
	v_and_b32_e32 v155, 0xffff0000, v154
	v_lshlrev_b32_e32 v154, 16, v154
	v_pk_add_f32 v[112:113], v[112:113], v[226:227]
	v_pk_add_f32 v[110:111], v[110:111], v[154:155]
	v_lshlrev_b32_e32 v240, 16, v157
	v_and_b32_e32 v241, 0xffff0000, v157
	v_and_b32_e32 v157, 0xffff0000, v156
	v_lshlrev_b32_e32 v156, 16, v156
	v_pk_add_f32 v[108:109], v[108:109], v[240:241]
	v_pk_add_f32 v[106:107], v[106:107], v[156:157]
	v_lshlrev_b32_e32 v226, 16, v159
	v_and_b32_e32 v227, 0xffff0000, v159
	v_and_b32_e32 v159, 0xffff0000, v158
	v_lshlrev_b32_e32 v158, 16, v158
	v_pk_add_f32 v[104:105], v[104:105], v[226:227]
	v_pk_add_f32 v[102:103], v[102:103], v[158:159]
	v_lshlrev_b32_e32 v240, 16, v161
	v_and_b32_e32 v241, 0xffff0000, v161
	v_and_b32_e32 v161, 0xffff0000, v160
	v_lshlrev_b32_e32 v160, 16, v160
	v_pk_add_f32 v[100:101], v[100:101], v[240:241]
	v_pk_add_f32 v[98:99], v[98:99], v[160:161]
	v_cvt_pk_bf16_f32 v110, v110, v111
	v_cvt_pk_bf16_f32 v111, v112, v113
	v_cvt_pk_bf16_f32 v106, v106, v107
	v_cvt_pk_bf16_f32 v107, v108, v109
	v_cvt_pk_bf16_f32 v102, v102, v103
	v_cvt_pk_bf16_f32 v103, v104, v105
	v_cvt_pk_bf16_f32 v98, v98, v99
	v_cvt_pk_bf16_f32 v99, v100, v101
	ds_bpermute_b32 v154, v244, v110
	ds_bpermute_b32 v155, v244, v111
	ds_bpermute_b32 v156, v244, v106
	ds_bpermute_b32 v157, v244, v107
	ds_bpermute_b32 v158, v245, v110
	ds_bpermute_b32 v159, v245, v111
	ds_bpermute_b32 v160, v245, v106
	ds_bpermute_b32 v161, v245, v107
	s_waitcnt lgkmcnt(0)
	v_cndmask_b32_e64 v154, v154, v156, s[98:99]
	v_cndmask_b32_e64 v155, v155, v157, s[98:99]
	v_add_u32_e32 v156, 0x8000, v246
	global_store_dwordx2 v156, v[154:155], s[8:9]
	v_cndmask_b32_e64 v158, v158, v160, s[98:99]
	v_cndmask_b32_e64 v159, v159, v161, s[98:99]
	v_add_u32_e32 v160, 0xc000, v246
	global_store_dwordx2 v160, v[158:159], s[8:9]
	ds_bpermute_b32 v154, v244, v102
	ds_bpermute_b32 v155, v244, v103
	ds_bpermute_b32 v156, v244, v98
	ds_bpermute_b32 v157, v244, v99
	ds_bpermute_b32 v158, v245, v102
	ds_bpermute_b32 v159, v245, v103
	ds_bpermute_b32 v160, v245, v98
	ds_bpermute_b32 v161, v245, v99
	s_waitcnt lgkmcnt(0)
	v_cndmask_b32_e64 v154, v154, v156, s[98:99]
	v_cndmask_b32_e64 v155, v155, v157, s[98:99]
	v_add_u32_e32 v156, 0x8000, v246
	global_store_dwordx2 v156, v[154:155], s[8:9] offset:256
	v_cndmask_b32_e64 v158, v158, v160, s[98:99]
	v_cndmask_b32_e64 v159, v159, v161, s[98:99]
	v_add_u32_e32 v160, 0xc000, v246
	global_store_dwordx2 v160, v[158:159], s[8:9] offset:256
	s_waitcnt vmcnt(28)
; DI unsigned pk_bf16(float a, float b) { f32x2 v = {a, b}; bf2_t r = __builtin_convertvector(v, bf2_t); return __builtin_bit_cast(unsigned, r); }
; DI float bflo(unsigned u) { return __uint_as_float(u << 16); }
; DI float bfhi(unsigned u) { return __uint_as_float(u & 0xffff0000u); }
;     DI void operator()(const f32x4 (&acc)[2][2][4][2], const Unit& u, int wr, int wc, int fr, int fq) const {
;     ...
;             for (int m = 0; m < 4; ++m) { const size_t o = (size_t)(row0 + ai * HALF + m * 16) * 1024 + col0;
; #pragma unroll
;                 for (int bj = 0; bj < 2; ++bj)
; #pragma unroll
;                     for (int n = 0; n < 2; ++n) { const size_t oo = o + bj * HALF + n * 16; f32x4 rv;
;                         if (RES_BF16) { const u32x2 t = *(const u32x2*)((const bf16_t*)res + oo); rv = (f32x4){bflo(t.x), bfhi(t.x), bflo(t.y), bfhi(t.y)}; }
;                         else rv = *(const f32x4*)((const float*)res + oo);
;                         const f32x4 v = acc[ai][bj][m][n] + rv; u32x2 w; w.x = pk_bf16(v.x, v.y); w.y = pk_bf16(v.z, v.w);
;                         *(u32x2*)(O + oo) = w; } }
	v_lshlrev_b32_e32 v226, 16, v169
	v_and_b32_e32 v227, 0xffff0000, v169
	v_and_b32_e32 v169, 0xffff0000, v168
	v_lshlrev_b32_e32 v168, 16, v168
	v_pk_add_f32 v[96:97], v[96:97], v[226:227]
	v_pk_add_f32 v[94:95], v[94:95], v[168:169]
	v_lshlrev_b32_e32 v240, 16, v171
	v_and_b32_e32 v241, 0xffff0000, v171
	v_and_b32_e32 v171, 0xffff0000, v170
	v_lshlrev_b32_e32 v170, 16, v170
	v_pk_add_f32 v[92:93], v[92:93], v[240:241]
	v_pk_add_f32 v[90:91], v[90:91], v[170:171]
	v_lshlrev_b32_e32 v226, 16, v173
	v_and_b32_e32 v227, 0xffff0000, v173
	v_and_b32_e32 v173, 0xffff0000, v172
	v_lshlrev_b32_e32 v172, 16, v172
	v_pk_add_f32 v[88:89], v[88:89], v[226:227]
	v_pk_add_f32 v[86:87], v[86:87], v[172:173]
	v_lshlrev_b32_e32 v240, 16, v175
	v_and_b32_e32 v241, 0xffff0000, v175
	v_and_b32_e32 v175, 0xffff0000, v174
	v_lshlrev_b32_e32 v174, 16, v174
	v_pk_add_f32 v[84:85], v[84:85], v[240:241]
	v_pk_add_f32 v[82:83], v[82:83], v[174:175]
	v_cvt_pk_bf16_f32 v94, v94, v95
	v_cvt_pk_bf16_f32 v95, v96, v97
	v_cvt_pk_bf16_f32 v90, v90, v91
	v_cvt_pk_bf16_f32 v91, v92, v93
	v_cvt_pk_bf16_f32 v86, v86, v87
	v_cvt_pk_bf16_f32 v87, v88, v89
	v_cvt_pk_bf16_f32 v82, v82, v83
	v_cvt_pk_bf16_f32 v83, v84, v85
	ds_bpermute_b32 v168, v244, v94
	ds_bpermute_b32 v169, v244, v95
	ds_bpermute_b32 v170, v244, v90
	ds_bpermute_b32 v171, v244, v91
	ds_bpermute_b32 v172, v245, v94
	ds_bpermute_b32 v173, v245, v95
	ds_bpermute_b32 v174, v245, v90
	ds_bpermute_b32 v175, v245, v91
	s_waitcnt lgkmcnt(0)
	v_cndmask_b32_e64 v168, v168, v170, s[98:99]
	v_cndmask_b32_e64 v169, v169, v171, s[98:99]
	v_add_u32_e32 v170, 0x10000, v246
	global_store_dwordx2 v170, v[168:169], s[8:9]
	v_cndmask_b32_e64 v172, v172, v174, s[98:99]
	v_cndmask_b32_e64 v173, v173, v175, s[98:99]
	v_add_u32_e32 v174, 0x14000, v246
	global_store_dwordx2 v174, v[172:173], s[8:9]
	ds_bpermute_b32 v168, v244, v86
	ds_bpermute_b32 v169, v244, v87
	ds_bpermute_b32 v170, v244, v82
	ds_bpermute_b32 v171, v244, v83
	ds_bpermute_b32 v172, v245, v86
	ds_bpermute_b32 v173, v245, v87
	ds_bpermute_b32 v174, v245, v82
	ds_bpermute_b32 v175, v245, v83
	s_waitcnt lgkmcnt(0)
	v_cndmask_b32_e64 v168, v168, v170, s[98:99]
	v_cndmask_b32_e64 v169, v169, v171, s[98:99]
	v_add_u32_e32 v170, 0x10000, v246
	global_store_dwordx2 v170, v[168:169], s[8:9] offset:256
	v_cndmask_b32_e64 v172, v172, v174, s[98:99]
	v_cndmask_b32_e64 v173, v173, v175, s[98:99]
	v_add_u32_e32 v174, 0x14000, v246
	global_store_dwordx2 v174, v[172:173], s[8:9] offset:256
	s_waitcnt vmcnt(28)
	v_lshlrev_b32_e32 v226, 16, v177
	v_and_b32_e32 v227, 0xffff0000, v177
	v_and_b32_e32 v177, 0xffff0000, v176
	v_lshlrev_b32_e32 v176, 16, v176
	v_pk_add_f32 v[80:81], v[80:81], v[226:227]
	v_pk_add_f32 v[78:79], v[78:79], v[176:177]
	v_lshlrev_b32_e32 v240, 16, v179
	v_and_b32_e32 v241, 0xffff0000, v179
	v_and_b32_e32 v179, 0xffff0000, v178
	v_lshlrev_b32_e32 v178, 16, v178
	v_pk_add_f32 v[76:77], v[76:77], v[240:241]
	v_pk_add_f32 v[74:75], v[74:75], v[178:179]
	v_lshlrev_b32_e32 v226, 16, v181
	v_and_b32_e32 v227, 0xffff0000, v181
	v_and_b32_e32 v181, 0xffff0000, v180
	v_lshlrev_b32_e32 v180, 16, v180
	v_pk_add_f32 v[72:73], v[72:73], v[226:227]
	v_pk_add_f32 v[70:71], v[70:71], v[180:181]
	v_lshlrev_b32_e32 v240, 16, v183
	v_and_b32_e32 v241, 0xffff0000, v183
	v_and_b32_e32 v183, 0xffff0000, v182
	v_lshlrev_b32_e32 v182, 16, v182
	v_pk_add_f32 v[68:69], v[68:69], v[240:241]
	v_pk_add_f32 v[66:67], v[66:67], v[182:183]
	v_cvt_pk_bf16_f32 v78, v78, v79
	v_cvt_pk_bf16_f32 v79, v80, v81
	v_cvt_pk_bf16_f32 v74, v74, v75
	v_cvt_pk_bf16_f32 v75, v76, v77
	v_cvt_pk_bf16_f32 v70, v70, v71
	v_cvt_pk_bf16_f32 v71, v72, v73
	v_cvt_pk_bf16_f32 v66, v66, v67
	v_cvt_pk_bf16_f32 v67, v68, v69
	ds_bpermute_b32 v176, v244, v78
	ds_bpermute_b32 v177, v244, v79
	ds_bpermute_b32 v178, v244, v74
	ds_bpermute_b32 v179, v244, v75
	ds_bpermute_b32 v180, v245, v78
	ds_bpermute_b32 v181, v245, v79
	ds_bpermute_b32 v182, v245, v74
	ds_bpermute_b32 v183, v245, v75
	s_waitcnt lgkmcnt(0)
	v_cndmask_b32_e64 v176, v176, v178, s[98:99]
	v_cndmask_b32_e64 v177, v177, v179, s[98:99]
	v_add_u32_e32 v178, 0x18000, v246
	global_store_dwordx2 v178, v[176:177], s[8:9]
	v_cndmask_b32_e64 v180, v180, v182, s[98:99]
	v_cndmask_b32_e64 v181, v181, v183, s[98:99]
	v_add_u32_e32 v182, 0x1c000, v246
	global_store_dwordx2 v182, v[180:181], s[8:9]
	ds_bpermute_b32 v176, v244, v70
	ds_bpermute_b32 v177, v244, v71
	ds_bpermute_b32 v178, v244, v66
	ds_bpermute_b32 v179, v244, v67
	ds_bpermute_b32 v180, v245, v70
	ds_bpermute_b32 v181, v245, v71
	ds_bpermute_b32 v182, v245, v66
	ds_bpermute_b32 v183, v245, v67
	s_waitcnt lgkmcnt(0)
	v_cndmask_b32_e64 v176, v176, v178, s[98:99]
	v_cndmask_b32_e64 v177, v177, v179, s[98:99]
	v_add_u32_e32 v178, 0x18000, v246
	global_store_dwordx2 v178, v[176:177], s[8:9] offset:256
	v_cndmask_b32_e64 v180, v180, v182, s[98:99]
	v_cndmask_b32_e64 v181, v181, v183, s[98:99]
	v_add_u32_e32 v182, 0x1c000, v246
	global_store_dwordx2 v182, v[180:181], s[8:9] offset:256
	s_waitcnt vmcnt(28)
; DI unsigned pk_bf16(float a, float b) { f32x2 v = {a, b}; bf2_t r = __builtin_convertvector(v, bf2_t); return __builtin_bit_cast(unsigned, r); }
; DI float bflo(unsigned u) { return __uint_as_float(u << 16); }
; DI float bfhi(unsigned u) { return __uint_as_float(u & 0xffff0000u); }
;     DI void operator()(const f32x4 (&acc)[2][2][4][2], const Unit& u, int wr, int wc, int fr, int fq) const {
;     ...
;             for (int m = 0; m < 4; ++m) { const size_t o = (size_t)(row0 + ai * HALF + m * 16) * 1024 + col0;
; #pragma unroll
;                 for (int bj = 0; bj < 2; ++bj)
; #pragma unroll
;                     for (int n = 0; n < 2; ++n) { const size_t oo = o + bj * HALF + n * 16; f32x4 rv;
;                         if (RES_BF16) { const u32x2 t = *(const u32x2*)((const bf16_t*)res + oo); rv = (f32x4){bflo(t.x), bfhi(t.x), bflo(t.y), bfhi(t.y)}; }
;                         else rv = *(const f32x4*)((const float*)res + oo);
;                         const f32x4 v = acc[ai][bj][m][n] + rv; u32x2 w; w.x = pk_bf16(v.x, v.y); w.y = pk_bf16(v.z, v.w);
;                         *(u32x2*)(O + oo) = w; } }
	v_lshlrev_b32_e32 v226, 16, v185
	v_and_b32_e32 v227, 0xffff0000, v185
	v_and_b32_e32 v185, 0xffff0000, v184
	v_lshlrev_b32_e32 v184, 16, v184
	v_pk_add_f32 v[64:65], v[64:65], v[226:227]
	v_pk_add_f32 v[62:63], v[62:63], v[184:185]
	v_lshlrev_b32_e32 v240, 16, v187
	v_and_b32_e32 v241, 0xffff0000, v187
	v_and_b32_e32 v187, 0xffff0000, v186
	v_lshlrev_b32_e32 v186, 16, v186
	v_pk_add_f32 v[60:61], v[60:61], v[240:241]
	v_pk_add_f32 v[58:59], v[58:59], v[186:187]
	v_lshlrev_b32_e32 v226, 16, v189
	v_and_b32_e32 v227, 0xffff0000, v189
	v_and_b32_e32 v189, 0xffff0000, v188
	v_lshlrev_b32_e32 v188, 16, v188
	v_pk_add_f32 v[56:57], v[56:57], v[226:227]
	v_pk_add_f32 v[54:55], v[54:55], v[188:189]
	v_lshlrev_b32_e32 v240, 16, v191
	v_and_b32_e32 v241, 0xffff0000, v191
	v_and_b32_e32 v191, 0xffff0000, v190
	v_lshlrev_b32_e32 v190, 16, v190
	v_pk_add_f32 v[52:53], v[52:53], v[240:241]
	v_pk_add_f32 v[50:51], v[50:51], v[190:191]
	v_cvt_pk_bf16_f32 v62, v62, v63
	v_cvt_pk_bf16_f32 v63, v64, v65
	v_cvt_pk_bf16_f32 v58, v58, v59
	v_cvt_pk_bf16_f32 v59, v60, v61
	v_cvt_pk_bf16_f32 v54, v54, v55
	v_cvt_pk_bf16_f32 v55, v56, v57
	v_cvt_pk_bf16_f32 v50, v50, v51
	v_cvt_pk_bf16_f32 v51, v52, v53
	ds_bpermute_b32 v184, v244, v62
	ds_bpermute_b32 v185, v244, v63
	ds_bpermute_b32 v186, v244, v58
	ds_bpermute_b32 v187, v244, v59
	ds_bpermute_b32 v188, v245, v62
	ds_bpermute_b32 v189, v245, v63
	ds_bpermute_b32 v190, v245, v58
	ds_bpermute_b32 v191, v245, v59
	s_waitcnt lgkmcnt(0)
	v_cndmask_b32_e64 v184, v184, v186, s[98:99]
	v_cndmask_b32_e64 v185, v185, v187, s[98:99]
	v_add_u32_e32 v186, 0x40000, v246
	global_store_dwordx2 v186, v[184:185], s[8:9]
	v_cndmask_b32_e64 v188, v188, v190, s[98:99]
	v_cndmask_b32_e64 v189, v189, v191, s[98:99]
	v_add_u32_e32 v190, 0x44000, v246
	global_store_dwordx2 v190, v[188:189], s[8:9]
	ds_bpermute_b32 v184, v244, v54
	ds_bpermute_b32 v185, v244, v55
	ds_bpermute_b32 v186, v244, v50
	ds_bpermute_b32 v187, v244, v51
	ds_bpermute_b32 v188, v245, v54
	ds_bpermute_b32 v189, v245, v55
	ds_bpermute_b32 v190, v245, v50
	ds_bpermute_b32 v191, v245, v51
	s_waitcnt lgkmcnt(0)
	v_cndmask_b32_e64 v184, v184, v186, s[98:99]
	v_cndmask_b32_e64 v185, v185, v187, s[98:99]
	v_add_u32_e32 v186, 0x40000, v246
	global_store_dwordx2 v186, v[184:185], s[8:9] offset:256
	v_cndmask_b32_e64 v188, v188, v190, s[98:99]
	v_cndmask_b32_e64 v189, v189, v191, s[98:99]
	v_add_u32_e32 v190, 0x44000, v246
	global_store_dwordx2 v190, v[188:189], s[8:9] offset:256
	s_waitcnt vmcnt(28)
	v_lshlrev_b32_e32 v226, 16, v193
	v_and_b32_e32 v227, 0xffff0000, v193
	v_and_b32_e32 v193, 0xffff0000, v192
	v_lshlrev_b32_e32 v192, 16, v192
	v_pk_add_f32 v[48:49], v[48:49], v[226:227]
	v_pk_add_f32 v[46:47], v[46:47], v[192:193]
	v_lshlrev_b32_e32 v240, 16, v195
	v_and_b32_e32 v241, 0xffff0000, v195
	v_and_b32_e32 v195, 0xffff0000, v194
	v_lshlrev_b32_e32 v194, 16, v194
	v_pk_add_f32 v[44:45], v[44:45], v[240:241]
	v_pk_add_f32 v[42:43], v[42:43], v[194:195]
	v_lshlrev_b32_e32 v226, 16, v199
	v_and_b32_e32 v227, 0xffff0000, v199
	v_and_b32_e32 v199, 0xffff0000, v198
	v_lshlrev_b32_e32 v198, 16, v198
	v_pk_add_f32 v[40:41], v[40:41], v[226:227]
	v_pk_add_f32 v[38:39], v[38:39], v[198:199]
	v_lshlrev_b32_e32 v240, 16, v201
	v_and_b32_e32 v241, 0xffff0000, v201
	v_and_b32_e32 v201, 0xffff0000, v200
	v_lshlrev_b32_e32 v200, 16, v200
	v_pk_add_f32 v[36:37], v[36:37], v[240:241]
	v_pk_add_f32 v[34:35], v[34:35], v[200:201]
	v_cvt_pk_bf16_f32 v46, v46, v47
	v_cvt_pk_bf16_f32 v47, v48, v49
	v_cvt_pk_bf16_f32 v42, v42, v43
	v_cvt_pk_bf16_f32 v43, v44, v45
	v_cvt_pk_bf16_f32 v38, v38, v39
	v_cvt_pk_bf16_f32 v39, v40, v41
	v_cvt_pk_bf16_f32 v34, v34, v35
	v_cvt_pk_bf16_f32 v35, v36, v37
	ds_bpermute_b32 v192, v244, v46
	ds_bpermute_b32 v193, v244, v47
	ds_bpermute_b32 v194, v244, v42
	ds_bpermute_b32 v195, v244, v43
	ds_bpermute_b32 v198, v245, v46
	ds_bpermute_b32 v199, v245, v47
	ds_bpermute_b32 v200, v245, v42
	ds_bpermute_b32 v201, v245, v43
	s_waitcnt lgkmcnt(0)
	v_cndmask_b32_e64 v192, v192, v194, s[98:99]
	v_cndmask_b32_e64 v193, v193, v195, s[98:99]
	v_add_u32_e32 v194, 0x48000, v246
	global_store_dwordx2 v194, v[192:193], s[8:9]
	v_cndmask_b32_e64 v198, v198, v200, s[98:99]
	v_cndmask_b32_e64 v199, v199, v201, s[98:99]
	v_add_u32_e32 v200, 0x4c000, v246
	global_store_dwordx2 v200, v[198:199], s[8:9]
	ds_bpermute_b32 v192, v244, v38
	ds_bpermute_b32 v193, v244, v39
	ds_bpermute_b32 v194, v244, v34
	ds_bpermute_b32 v195, v244, v35
	ds_bpermute_b32 v198, v245, v38
	ds_bpermute_b32 v199, v245, v39
	ds_bpermute_b32 v200, v245, v34
	ds_bpermute_b32 v201, v245, v35
	s_waitcnt lgkmcnt(0)
	v_cndmask_b32_e64 v192, v192, v194, s[98:99]
	v_cndmask_b32_e64 v193, v193, v195, s[98:99]
	v_add_u32_e32 v194, 0x48000, v246
	global_store_dwordx2 v194, v[192:193], s[8:9] offset:256
	v_cndmask_b32_e64 v198, v198, v200, s[98:99]
	v_cndmask_b32_e64 v199, v199, v201, s[98:99]
	v_add_u32_e32 v200, 0x4c000, v246
	global_store_dwordx2 v200, v[198:199], s[8:9] offset:256
	s_waitcnt vmcnt(28)
; DI unsigned pk_bf16(float a, float b) { f32x2 v = {a, b}; bf2_t r = __builtin_convertvector(v, bf2_t); return __builtin_bit_cast(unsigned, r); }
; DI float bflo(unsigned u) { return __uint_as_float(u << 16); }
; DI float bfhi(unsigned u) { return __uint_as_float(u & 0xffff0000u); }
;     DI void operator()(const f32x4 (&acc)[2][2][4][2], const Unit& u, int wr, int wc, int fr, int fq) const {
;     ...
;             for (int m = 0; m < 4; ++m) { const size_t o = (size_t)(row0 + ai * HALF + m * 16) * 1024 + col0;
; #pragma unroll
;                 for (int bj = 0; bj < 2; ++bj)
; #pragma unroll
;                     for (int n = 0; n < 2; ++n) { const size_t oo = o + bj * HALF + n * 16; f32x4 rv;
;                         if (RES_BF16) { const u32x2 t = *(const u32x2*)((const bf16_t*)res + oo); rv = (f32x4){bflo(t.x), bfhi(t.x), bflo(t.y), bfhi(t.y)}; }
;                         else rv = *(const f32x4*)((const float*)res + oo);
;                         const f32x4 v = acc[ai][bj][m][n] + rv; u32x2 w; w.x = pk_bf16(v.x, v.y); w.y = pk_bf16(v.z, v.w);
;                         *(u32x2*)(O + oo) = w; } }
; template <class Epi, class Sched>
; DI void gemm_phase(LAS unsigned char* lds, const Gemm g, const Sched& S, const Epi& E) {
;     ...
;         E(acc, cur, wr, wc, fr, fq);
;         if (!has_next) break;
	v_lshlrev_b32_e32 v226, 16, v203
	v_and_b32_e32 v227, 0xffff0000, v203
	v_and_b32_e32 v203, 0xffff0000, v202
	v_lshlrev_b32_e32 v202, 16, v202
	v_pk_add_f32 v[32:33], v[32:33], v[226:227]
	v_pk_add_f32 v[30:31], v[30:31], v[202:203]
	v_lshlrev_b32_e32 v240, 16, v205
	v_and_b32_e32 v241, 0xffff0000, v205
	v_and_b32_e32 v205, 0xffff0000, v204
	v_lshlrev_b32_e32 v204, 16, v204
	v_pk_add_f32 v[28:29], v[28:29], v[240:241]
	v_pk_add_f32 v[26:27], v[26:27], v[204:205]
	v_lshlrev_b32_e32 v226, 16, v207
	v_and_b32_e32 v227, 0xffff0000, v207
	v_and_b32_e32 v207, 0xffff0000, v206
	v_lshlrev_b32_e32 v206, 16, v206
	v_pk_add_f32 v[24:25], v[24:25], v[226:227]
	v_pk_add_f32 v[22:23], v[22:23], v[206:207]
	v_lshlrev_b32_e32 v240, 16, v209
	v_and_b32_e32 v241, 0xffff0000, v209
	v_and_b32_e32 v209, 0xffff0000, v208
	v_lshlrev_b32_e32 v208, 16, v208
	v_pk_add_f32 v[20:21], v[20:21], v[240:241]
	v_pk_add_f32 v[18:19], v[18:19], v[208:209]
	v_cvt_pk_bf16_f32 v30, v30, v31
	v_cvt_pk_bf16_f32 v31, v32, v33
	v_cvt_pk_bf16_f32 v26, v26, v27
	v_cvt_pk_bf16_f32 v27, v28, v29
	v_cvt_pk_bf16_f32 v22, v22, v23
	v_cvt_pk_bf16_f32 v23, v24, v25
	v_cvt_pk_bf16_f32 v18, v18, v19
	v_cvt_pk_bf16_f32 v19, v20, v21
	ds_bpermute_b32 v202, v244, v30
	ds_bpermute_b32 v203, v244, v31
	ds_bpermute_b32 v204, v244, v26
	ds_bpermute_b32 v205, v244, v27
	ds_bpermute_b32 v206, v245, v30
	ds_bpermute_b32 v207, v245, v31
	ds_bpermute_b32 v208, v245, v26
	ds_bpermute_b32 v209, v245, v27
	s_waitcnt lgkmcnt(0)
	v_cndmask_b32_e64 v202, v202, v204, s[98:99]
	v_cndmask_b32_e64 v203, v203, v205, s[98:99]
	v_add_u32_e32 v204, 0x50000, v246
	global_store_dwordx2 v204, v[202:203], s[8:9]
	v_cndmask_b32_e64 v206, v206, v208, s[98:99]
	v_cndmask_b32_e64 v207, v207, v209, s[98:99]
	v_add_u32_e32 v208, 0x54000, v246
	global_store_dwordx2 v208, v[206:207], s[8:9]
	ds_bpermute_b32 v202, v244, v22
	ds_bpermute_b32 v203, v244, v23
	ds_bpermute_b32 v204, v244, v18
	ds_bpermute_b32 v205, v244, v19
	ds_bpermute_b32 v206, v245, v22
	ds_bpermute_b32 v207, v245, v23
	ds_bpermute_b32 v208, v245, v18
	ds_bpermute_b32 v209, v245, v19
	s_waitcnt lgkmcnt(0)
	v_cndmask_b32_e64 v202, v202, v204, s[98:99]
	v_cndmask_b32_e64 v203, v203, v205, s[98:99]
	v_add_u32_e32 v204, 0x50000, v246
	global_store_dwordx2 v204, v[202:203], s[8:9] offset:256
	v_cndmask_b32_e64 v206, v206, v208, s[98:99]
	v_cndmask_b32_e64 v207, v207, v209, s[98:99]
	v_add_u32_e32 v208, 0x54000, v246
	global_store_dwordx2 v208, v[206:207], s[8:9] offset:256
	s_waitcnt vmcnt(28)
	v_lshlrev_b32_e32 v226, 16, v211
	v_and_b32_e32 v227, 0xffff0000, v211
	v_and_b32_e32 v211, 0xffff0000, v210
	v_lshlrev_b32_e32 v210, 16, v210
	v_pk_add_f32 v[16:17], v[16:17], v[226:227]
	v_pk_add_f32 v[14:15], v[14:15], v[210:211]
	v_lshlrev_b32_e32 v240, 16, v213
	v_and_b32_e32 v241, 0xffff0000, v213
	v_and_b32_e32 v213, 0xffff0000, v212
	v_lshlrev_b32_e32 v212, 16, v212
	v_pk_add_f32 v[12:13], v[12:13], v[240:241]
	v_pk_add_f32 v[10:11], v[10:11], v[212:213]
	v_lshlrev_b32_e32 v226, 16, v215
	v_and_b32_e32 v227, 0xffff0000, v215
	v_and_b32_e32 v215, 0xffff0000, v214
	v_lshlrev_b32_e32 v214, 16, v214
	v_pk_add_f32 v[8:9], v[8:9], v[226:227]
	v_pk_add_f32 v[6:7], v[6:7], v[214:215]
	v_lshlrev_b32_e32 v240, 16, v217
	v_and_b32_e32 v241, 0xffff0000, v217
	v_and_b32_e32 v217, 0xffff0000, v216
	v_lshlrev_b32_e32 v216, 16, v216
	v_pk_add_f32 v[4:5], v[4:5], v[240:241]
	v_pk_add_f32 v[2:3], v[2:3], v[216:217]
	v_cvt_pk_bf16_f32 v14, v14, v15
	v_cvt_pk_bf16_f32 v15, v16, v17
	v_cvt_pk_bf16_f32 v10, v10, v11
	v_cvt_pk_bf16_f32 v11, v12, v13
	v_cvt_pk_bf16_f32 v6, v6, v7
	v_cvt_pk_bf16_f32 v7, v8, v9
	v_cvt_pk_bf16_f32 v2, v2, v3
	v_cvt_pk_bf16_f32 v3, v4, v5
	ds_bpermute_b32 v210, v244, v14
	ds_bpermute_b32 v211, v244, v15
	ds_bpermute_b32 v212, v244, v10
	ds_bpermute_b32 v213, v244, v11
	ds_bpermute_b32 v214, v245, v14
	ds_bpermute_b32 v215, v245, v15
	ds_bpermute_b32 v216, v245, v10
	ds_bpermute_b32 v217, v245, v11
	s_waitcnt lgkmcnt(0)
	v_cndmask_b32_e64 v210, v210, v212, s[98:99]
	v_cndmask_b32_e64 v211, v211, v213, s[98:99]
	v_add_u32_e32 v212, 0x58000, v246
	global_store_dwordx2 v212, v[210:211], s[8:9]
	v_cndmask_b32_e64 v214, v214, v216, s[98:99]
	v_cndmask_b32_e64 v215, v215, v217, s[98:99]
	v_add_u32_e32 v216, 0x5c000, v246
	global_store_dwordx2 v216, v[214:215], s[8:9]
	ds_bpermute_b32 v210, v244, v6
	ds_bpermute_b32 v211, v244, v7
	ds_bpermute_b32 v212, v244, v2
	ds_bpermute_b32 v213, v244, v3
	ds_bpermute_b32 v214, v245, v6
	ds_bpermute_b32 v215, v245, v7
	ds_bpermute_b32 v216, v245, v2
	ds_bpermute_b32 v217, v245, v3
	s_waitcnt lgkmcnt(0)
	v_cndmask_b32_e64 v210, v210, v212, s[98:99]
	v_cndmask_b32_e64 v211, v211, v213, s[98:99]
	v_add_u32_e32 v212, 0x58000, v246
	global_store_dwordx2 v212, v[210:211], s[8:9] offset:256
	v_cndmask_b32_e64 v214, v214, v216, s[98:99]
	v_cndmask_b32_e64 v215, v215, v217, s[98:99]
	v_add_u32_e32 v216, 0x5c000, v246
	global_store_dwordx2 v216, v[214:215], s[8:9] offset:256
	s_and_b64 vcc, exec, s[40:41]
	s_mov_b32 s84, s65
	s_mov_b32 s56, s66
	s_cbranch_vccz .LBB0_1522
	s_waitcnt vmcnt(0)
	s_cmpk_gt_u32 s3, 0xff
	s_cbranch_scc1 .LBB0_1527
	s_barrier

; #define PG8_STAGE(bufoff, gbase, voff) do { _Pragma("unroll") for (int _i = 0; _i < 2; ++_i) \
;         __builtin_amdgcn_global_load_lds((const unsigned*)((const char*)(gbase) + (voff)[_i]), (LAS unsigned*)(lds + (bufoff) + ldsw + _i * 8192), 16, 0, 0); } while (0)
; #define PG8_LDA(dst, b, h) do { _Pragma("unroll") for (int m = 0; m < 4; ++m) _Pragma("unroll") for (int k = 0; k < 2; ++k) dst[m][k] = *(const LAS bf16x8*)(lds + PG8_SA(b, h) + aoff + m * 2048 + k * 1024); } while (0)
; #define PG8_LDB(dst, b, h) do { _Pragma("unroll") for (int n = 0; n < 2; ++n) _Pragma("unroll") for (int k = 0; k < 2; ++k) dst[n][k] = *(const LAS bf16x8*)(lds + PG8_SB(b, h) + boff + n * 2048 + k * 1024); } while (0)
; #define PG8_MMA(ai, bj, At, Bt) do { __builtin_amdgcn_s_setprio(1); _Pragma("unroll") for (int m = 0; m < 4; ++m) _Pragma("unroll") for (int n = 0; n < 2; ++n) _Pragma("unroll") for (int k = 0; k < 2; ++k) \
;         acc[ai][bj][m][n] = __builtin_amdgcn_mfma_f32_16x16x32_bf16(Bt[n][k], At[m][k], acc[ai][bj][m][n], 0, 0, 0); __builtin_amdgcn_s_setprio(0); } while (0)
; #define PG8_WAIT_V(n) asm volatile("s_waitcnt vmcnt(" #n ")" ::: "memory")
; #define PG8_WAIT_L(n) asm volatile("s_waitcnt lgkmcnt(" #n ")" ::: "memory")
; #define PG8_BAR __builtin_amdgcn_s_barrier()
; #define PG8_SCHED __builtin_amdgcn_sched_barrier(0)
; template <class Epi, class Sched>
; DI void gemm_phase(LAS unsigned char* lds, const Gemm g, const Sched& S, const Epi& E) {
;     ...
;             PG8_LDB(B0, 0, 0); PG8_SCHED; PG8_LDA(At, 0, 0); PG8_STAGE(PG8_SA(1, 1), a1 + hstep, voffA);
;             PG8_WAIT_L(8); PG8_BAR; PG8_WAIT_L(0); PG8_MMA(0, 0, At, B0); PG8_BAR; PG8_SCHED;
;             PG8_LDB(B1, 0, 1); PG8_STAGE(PG8_SB(0, 0), b2, voffB);
;             PG8_BAR; PG8_WAIT_L(0); PG8_MMA(0, 1, At, B1); PG8_BAR;
;             PG8_LDA(At, 0, 1); PG8_STAGE(PG8_SA(0, 0), a2, voffA);
;             PG8_BAR; PG8_WAIT_L(0); PG8_MMA(1, 0, At, B0); PG8_BAR; PG8_SCHED;
;             PG8_STAGE(PG8_SB(0, 1), b2 + hstep, voffB);
;             PG8_WAIT_V(6); PG8_BAR; PG8_MMA(1, 1, At, B1); PG8_BAR;
.LBB0_1532:
	ds_read_b128 v[12:15], v9
	ds_read_b128 v[16:19], v9 offset:1024
	ds_read_b128 v[20:23], v9 offset:2048
	ds_read_b128 v[24:27], v9 offset:3072
	s_add_u32 s62, s36, 0x80080
	s_addc_u32 s63, s37, 0
	s_mov_b32 m0, s53
	v_lshl_add_u64 v[60:61], s[62:63], 0, v[4:5]
	ds_read_b128 v[28:31], v10
	ds_read_b128 v[32:35], v10 offset:1024
	ds_read_b128 v[36:39], v10 offset:2048
	ds_read_b128 v[40:43], v10 offset:3072
	ds_read_b128 v[44:47], v10 offset:4096
	ds_read_b128 v[48:51], v10 offset:5120
	ds_read_b128 v[52:55], v10 offset:6144
	ds_read_b128 v[56:59], v10 offset:7168
	global_load_lds_dwordx4 v[60:61], off
	v_lshl_add_u64 v[60:61], s[62:63], 0, v[2:3]
	s_mov_b32 m0, s54
	s_nop 0
	global_load_lds_dwordx4 v[60:61], off
	s_waitcnt lgkmcnt(8)
	s_barrier
	s_waitcnt lgkmcnt(0)
	s_setprio 1
	s_waitcnt lgkmcnt(0)
	v_mfma_f32_16x16x32_bf16 v[60:63], v[12:15], v[28:31], 0
	v_mfma_f32_16x16x32_bf16 v[64:67], v[20:23], v[28:31], 0
	v_mfma_f32_16x16x32_bf16 v[68:71], v[12:15], v[36:39], 0
	v_mfma_f32_16x16x32_bf16 v[72:75], v[20:23], v[36:39], 0
	v_mfma_f32_16x16x32_bf16 v[76:79], v[12:15], v[44:47], 0
	v_mfma_f32_16x16x32_bf16 v[80:83], v[20:23], v[44:47], 0
	v_mfma_f32_16x16x32_bf16 v[84:87], v[12:15], v[52:55], 0
	v_mfma_f32_16x16x32_bf16 v[88:91], v[20:23], v[52:55], 0
	v_mfma_f32_16x16x32_bf16 v[60:63], v[16:19], v[32:35], v[60:63]
	v_mfma_f32_16x16x32_bf16 v[64:67], v[24:27], v[32:35], v[64:67]
	v_mfma_f32_16x16x32_bf16 v[68:71], v[16:19], v[40:43], v[68:71]
	v_mfma_f32_16x16x32_bf16 v[72:75], v[24:27], v[40:43], v[72:75]
	v_mfma_f32_16x16x32_bf16 v[76:79], v[16:19], v[48:51], v[76:79]
	v_mfma_f32_16x16x32_bf16 v[80:83], v[24:27], v[48:51], v[80:83]
	v_mfma_f32_16x16x32_bf16 v[84:87], v[16:19], v[56:59], v[84:87]
	v_mfma_f32_16x16x32_bf16 v[88:91], v[24:27], v[56:59], v[88:91]
	s_setprio 0
	s_barrier
	v_lshl_add_u64 v[160:161], s[38:39], 0, v[4:5]
	s_add_i32 s29, s52, s33
	v_lshl_add_u64 v[108:109], v[160:161], 0, s[14:15]
	s_mov_b32 m0, s29
	v_lshl_add_u64 v[214:215], s[38:39], 0, v[2:3]
	s_add_i32 s25, s29, 0x2000
	ds_read_b128 v[92:95], v11
	ds_read_b128 v[96:99], v11 offset:1024
	ds_read_b128 v[100:103], v11 offset:2048
	ds_read_b128 v[104:107], v11 offset:3072
	global_load_lds_dwordx4 v[108:109], off
	v_lshl_add_u64 v[108:109], v[214:215], 0, s[14:15]
	s_mov_b32 m0, s25
	s_nop 0
	global_load_lds_dwordx4 v[108:109], off
	s_barrier
	s_waitcnt lgkmcnt(0)
	s_setprio 1
	s_waitcnt lgkmcnt(0)
	v_mfma_f32_16x16x32_bf16 v[108:111], v[92:95], v[28:31], 0
	v_mfma_f32_16x16x32_bf16 v[28:31], v[100:103], v[28:31], 0
	v_mfma_f32_16x16x32_bf16 v[108:111], v[96:99], v[32:35], v[108:111]
	v_mfma_f32_16x16x32_bf16 v[28:31], v[104:107], v[32:35], v[28:31]
	v_mfma_f32_16x16x32_bf16 v[32:35], v[92:95], v[36:39], 0
	v_mfma_f32_16x16x32_bf16 v[36:39], v[100:103], v[36:39], 0
	v_mfma_f32_16x16x32_bf16 v[32:35], v[96:99], v[40:43], v[32:35]
	v_mfma_f32_16x16x32_bf16 v[36:39], v[104:107], v[40:43], v[36:39]
	v_mfma_f32_16x16x32_bf16 v[40:43], v[92:95], v[44:47], 0
	v_mfma_f32_16x16x32_bf16 v[44:47], v[100:103], v[44:47], 0
	v_mfma_f32_16x16x32_bf16 v[40:43], v[96:99], v[48:51], v[40:43]
	v_mfma_f32_16x16x32_bf16 v[44:47], v[104:107], v[48:51], v[44:47]
	v_mfma_f32_16x16x32_bf16 v[48:51], v[92:95], v[52:55], 0
	v_mfma_f32_16x16x32_bf16 v[52:55], v[100:103], v[52:55], 0
	v_mfma_f32_16x16x32_bf16 v[48:51], v[96:99], v[56:59], v[48:51]
	v_mfma_f32_16x16x32_bf16 v[52:55], v[104:107], v[56:59], v[52:55]
	s_setprio 0
	v_lshl_add_u64 v[216:217], s[36:37], 0, v[4:5]
	s_mov_b32 m0, s7
	v_lshl_add_u64 v[140:141], v[216:217], 0, s[14:15]
	v_lshl_add_u64 v[218:219], s[36:37], 0, v[2:3]
	s_barrier
	ds_read_b128 v[56:59], v10 offset:16384
	ds_read_b128 v[112:115], v10 offset:17408
	ds_read_b128 v[116:119], v10 offset:18432
	ds_read_b128 v[120:123], v10 offset:19456
	ds_read_b128 v[124:127], v10 offset:20480
	ds_read_b128 v[128:131], v10 offset:21504
	ds_read_b128 v[132:135], v10 offset:22528
	ds_read_b128 v[136:139], v10 offset:23552
	global_load_lds_dwordx4 v[140:141], off
	v_lshl_add_u64 v[140:141], v[218:219], 0, s[14:15]
	s_mov_b32 m0, s40
	s_nop 0
	global_load_lds_dwordx4 v[140:141], off
	s_barrier
	s_waitcnt lgkmcnt(0)
	s_setprio 1
	s_waitcnt lgkmcnt(0)
	v_mfma_f32_16x16x32_bf16 v[140:143], v[12:15], v[56:59], 0
	v_mfma_f32_16x16x32_bf16 v[148:151], v[12:15], v[116:119], 0
	v_mfma_f32_16x16x32_bf16 v[156:159], v[12:15], v[124:127], 0
	v_mfma_f32_16x16x32_bf16 v[12:15], v[12:15], v[132:135], 0
	v_mfma_f32_16x16x32_bf16 v[140:143], v[16:19], v[112:115], v[140:143]
	v_mfma_f32_16x16x32_bf16 v[144:147], v[20:23], v[56:59], 0
	v_mfma_f32_16x16x32_bf16 v[148:151], v[16:19], v[120:123], v[148:151]
	v_mfma_f32_16x16x32_bf16 v[152:155], v[20:23], v[116:119], 0
	v_mfma_f32_16x16x32_bf16 v[156:159], v[16:19], v[128:131], v[156:159]
	v_mfma_f32_16x16x32_bf16 v[168:171], v[20:23], v[124:127], 0
	v_mfma_f32_16x16x32_bf16 v[12:15], v[16:19], v[136:139], v[12:15]
	v_mfma_f32_16x16x32_bf16 v[16:19], v[20:23], v[132:135], 0
	v_mfma_f32_16x16x32_bf16 v[144:147], v[24:27], v[112:115], v[144:147]
	v_mfma_f32_16x16x32_bf16 v[152:155], v[24:27], v[120:123], v[152:155]
	v_mfma_f32_16x16x32_bf16 v[168:171], v[24:27], v[128:131], v[168:171]
	v_mfma_f32_16x16x32_bf16 v[16:19], v[24:27], v[136:139], v[16:19]
	s_setprio 0
	s_barrier
	s_add_u32 s64, s38, 0x80100
	s_addc_u32 s65, s39, 0
	s_add_i32 s62, s55, s33
	v_lshl_add_u64 v[20:21], s[64:65], 0, v[4:5]
	s_mov_b32 m0, s62
	s_add_i32 s27, s62, 0x2000
	global_load_lds_dwordx4 v[20:21], off
	v_lshl_add_u64 v[20:21], s[64:65], 0, v[2:3]
	s_mov_b32 m0, s27
	s_nop 0
	global_load_lds_dwordx4 v[20:21], off
	s_waitcnt vmcnt(6)
	s_barrier
; #define PG8_STAGE(bufoff, gbase, voff) do { _Pragma("unroll") for (int _i = 0; _i < 2; ++_i) \
;         __builtin_amdgcn_global_load_lds((const unsigned*)((const char*)(gbase) + (voff)[_i]), (LAS unsigned*)(lds + (bufoff) + ldsw + _i * 8192), 16, 0, 0); } while (0)
; #define PG8_LDA(dst, b, h) do { _Pragma("unroll") for (int m = 0; m < 4; ++m) _Pragma("unroll") for (int k = 0; k < 2; ++k) dst[m][k] = *(const LAS bf16x8*)(lds + PG8_SA(b, h) + aoff + m * 2048 + k * 1024); } while (0)
; #define PG8_LDB(dst, b, h) do { _Pragma("unroll") for (int n = 0; n < 2; ++n) _Pragma("unroll") for (int k = 0; k < 2; ++k) dst[n][k] = *(const LAS bf16x8*)(lds + PG8_SB(b, h) + boff + n * 2048 + k * 1024); } while (0)
; #define PG8_MMA(ai, bj, At, Bt) do { __builtin_amdgcn_s_setprio(1); _Pragma("unroll") for (int m = 0; m < 4; ++m) _Pragma("unroll") for (int n = 0; n < 2; ++n) _Pragma("unroll") for (int k = 0; k < 2; ++k) \
;         acc[ai][bj][m][n] = __builtin_amdgcn_mfma_f32_16x16x32_bf16(Bt[n][k], At[m][k], acc[ai][bj][m][n], 0, 0, 0); __builtin_amdgcn_s_setprio(0); } while (0)
; #define PG8_WAIT_V(n) asm volatile("s_waitcnt vmcnt(" #n ")" ::: "memory")
; #define PG8_WAIT_L(n) asm volatile("s_waitcnt lgkmcnt(" #n ")" ::: "memory")
; #define PG8_BAR __builtin_amdgcn_s_barrier()
; #define PG8_SCHED __builtin_amdgcn_sched_barrier(0)
; template <class Epi, class Sched>
; DI void gemm_phase(LAS unsigned char* lds, const Gemm g, const Sched& S, const Epi& E) {
;     ...
;             PG8_WAIT_V(6); PG8_BAR; PG8_MMA(1, 1, At, B1); PG8_BAR;
;             PG8_LDB(B0, 1, 0); PG8_SCHED; PG8_LDA(At, 1, 0); PG8_STAGE(PG8_SA(0, 1), a2 + hstep, voffA);
;             PG8_WAIT_L(8); PG8_BAR; PG8_WAIT_L(0); PG8_MMA(0, 0, At, B0); PG8_BAR; PG8_SCHED;
;             PG8_LDB(B1, 1, 1); PG8_STAGE(PG8_SB(1, 0), b3, voffB);
;             PG8_BAR; PG8_WAIT_L(0); PG8_MMA(0, 1, At, B1); PG8_BAR;
	s_setprio 1
	v_mfma_f32_16x16x32_bf16 v[20:23], v[92:95], v[56:59], 0
	v_mfma_f32_16x16x32_bf16 v[24:27], v[100:103], v[56:59], 0
	v_mfma_f32_16x16x32_bf16 v[20:23], v[96:99], v[112:115], v[20:23]
	v_mfma_f32_16x16x32_bf16 v[24:27], v[104:107], v[112:115], v[24:27]
	v_mfma_f32_16x16x32_bf16 v[56:59], v[92:95], v[116:119], 0
	v_mfma_f32_16x16x32_bf16 v[112:115], v[100:103], v[116:119], 0
	v_mfma_f32_16x16x32_bf16 v[116:119], v[92:95], v[124:127], 0
	v_mfma_f32_16x16x32_bf16 v[92:95], v[92:95], v[132:135], 0
	v_mfma_f32_16x16x32_bf16 v[56:59], v[96:99], v[120:123], v[56:59]
	v_mfma_f32_16x16x32_bf16 v[112:115], v[104:107], v[120:123], v[112:115]
	v_mfma_f32_16x16x32_bf16 v[116:119], v[96:99], v[128:131], v[116:119]
	v_mfma_f32_16x16x32_bf16 v[120:123], v[100:103], v[124:127], 0
	v_mfma_f32_16x16x32_bf16 v[92:95], v[96:99], v[136:139], v[92:95]
	v_mfma_f32_16x16x32_bf16 v[96:99], v[100:103], v[132:135], 0
	v_mfma_f32_16x16x32_bf16 v[120:123], v[104:107], v[128:131], v[120:123]
	v_mfma_f32_16x16x32_bf16 v[96:99], v[104:107], v[136:139], v[96:99]
	s_setprio 0
	s_add_i32 s63, 0, 0x18000
	v_add_u32_e32 v165, s63, v6
	s_barrier
	ds_read_b128 v[100:103], v165
	ds_read_b128 v[104:107], v165 offset:1024
	ds_read_b128 v[124:127], v165 offset:2048
	ds_read_b128 v[128:131], v165 offset:3072
	s_add_u32 s64, s36, 0x80100
	s_addc_u32 s65, s37, 0
	s_mov_b32 m0, s41
	v_lshl_add_u64 v[198:199], s[64:65], 0, v[4:5]
	ds_read_b128 v[132:135], v10 offset:32768
	ds_read_b128 v[136:139], v10 offset:33792
	ds_read_b128 v[172:175], v10 offset:34816
	ds_read_b128 v[176:179], v10 offset:35840
	ds_read_b128 v[180:183], v10 offset:36864
	ds_read_b128 v[184:187], v10 offset:37888
	ds_read_b128 v[188:191], v10 offset:38912
	ds_read_b128 v[192:195], v10 offset:39936
	global_load_lds_dwordx4 v[198:199], off
	v_lshl_add_u64 v[198:199], s[64:65], 0, v[2:3]
	s_mov_b32 m0, s42
	s_nop 0
	global_load_lds_dwordx4 v[198:199], off
	s_waitcnt lgkmcnt(8)
	s_barrier
	s_waitcnt lgkmcnt(0)
	s_setprio 1
	s_waitcnt lgkmcnt(0)
	v_mfma_f32_16x16x32_bf16 v[60:63], v[100:103], v[132:135], v[60:63]
	v_mfma_f32_16x16x32_bf16 v[64:67], v[124:127], v[132:135], v[64:67]
	v_mfma_f32_16x16x32_bf16 v[68:71], v[100:103], v[172:175], v[68:71]
	v_mfma_f32_16x16x32_bf16 v[72:75], v[124:127], v[172:175], v[72:75]
	v_mfma_f32_16x16x32_bf16 v[76:79], v[100:103], v[180:183], v[76:79]
	v_mfma_f32_16x16x32_bf16 v[80:83], v[124:127], v[180:183], v[80:83]
	v_mfma_f32_16x16x32_bf16 v[84:87], v[100:103], v[188:191], v[84:87]
	v_mfma_f32_16x16x32_bf16 v[88:91], v[124:127], v[188:191], v[88:91]
	v_mfma_f32_16x16x32_bf16 v[60:63], v[104:107], v[136:139], v[60:63]
	v_mfma_f32_16x16x32_bf16 v[64:67], v[128:131], v[136:139], v[64:67]
	v_mfma_f32_16x16x32_bf16 v[68:71], v[104:107], v[176:179], v[68:71]
	v_mfma_f32_16x16x32_bf16 v[72:75], v[128:131], v[176:179], v[72:75]
	v_mfma_f32_16x16x32_bf16 v[76:79], v[104:107], v[184:187], v[76:79]
	v_mfma_f32_16x16x32_bf16 v[80:83], v[128:131], v[184:187], v[80:83]
	v_mfma_f32_16x16x32_bf16 v[84:87], v[104:107], v[192:195], v[84:87]
	v_mfma_f32_16x16x32_bf16 v[88:91], v[128:131], v[192:195], v[88:91]
	s_setprio 0
	s_barrier
	s_add_i32 s65, 0, 0x1c000
	s_add_i32 s64, s63, s33
	v_add_u32_e32 v167, s65, v6
	v_lshl_add_u64 v[160:161], v[160:161], 0, s[16:17]
	s_mov_b32 m0, s64
	s_add_i32 s63, s64, 0x2000
	ds_read_b128 v[198:201], v167
	ds_read_b128 v[202:205], v167 offset:1024
	ds_read_b128 v[206:209], v167 offset:2048
	ds_read_b128 v[210:213], v167 offset:3072
	global_load_lds_dwordx4 v[160:161], off
	v_lshl_add_u64 v[160:161], v[214:215], 0, s[16:17]
	s_mov_b32 m0, s63
	s_nop 0
	global_load_lds_dwordx4 v[160:161], off
	s_barrier
	s_waitcnt lgkmcnt(0)
	s_setprio 1
	s_waitcnt lgkmcnt(0)
	v_mfma_f32_16x16x32_bf16 v[108:111], v[198:201], v[132:135], v[108:111]
	v_mfma_f32_16x16x32_bf16 v[28:31], v[206:209], v[132:135], v[28:31]
	v_mfma_f32_16x16x32_bf16 v[32:35], v[198:201], v[172:175], v[32:35]
	v_mfma_f32_16x16x32_bf16 v[36:39], v[206:209], v[172:175], v[36:39]
	v_mfma_f32_16x16x32_bf16 v[40:43], v[198:201], v[180:183], v[40:43]
	v_mfma_f32_16x16x32_bf16 v[44:47], v[206:209], v[180:183], v[44:47]
	v_mfma_f32_16x16x32_bf16 v[48:51], v[198:201], v[188:191], v[48:51]
	v_mfma_f32_16x16x32_bf16 v[52:55], v[206:209], v[188:191], v[52:55]
	v_mfma_f32_16x16x32_bf16 v[108:111], v[202:205], v[136:139], v[108:111]
	v_mfma_f32_16x16x32_bf16 v[28:31], v[210:213], v[136:139], v[28:31]
	v_mfma_f32_16x16x32_bf16 v[32:35], v[202:205], v[176:179], v[32:35]
	v_mfma_f32_16x16x32_bf16 v[36:39], v[210:213], v[176:179], v[36:39]
	v_mfma_f32_16x16x32_bf16 v[40:43], v[202:205], v[184:187], v[40:43]
	v_mfma_f32_16x16x32_bf16 v[44:47], v[210:213], v[184:187], v[44:47]
	v_mfma_f32_16x16x32_bf16 v[48:51], v[202:205], v[192:195], v[48:51]
	v_mfma_f32_16x16x32_bf16 v[52:55], v[210:213], v[192:195], v[52:55]
	s_setprio 0
	s_mov_b32 m0, s43
	v_lshl_add_u64 v[160:161], v[216:217], 0, s[16:17]
	s_barrier
	ds_read_b128 v[132:135], v10 offset:49152
	ds_read_b128 v[136:139], v10 offset:50176
	ds_read_b128 v[172:175], v10 offset:51200
	ds_read_b128 v[176:179], v10 offset:52224
	ds_read_b128 v[180:183], v10 offset:53248
	ds_read_b128 v[184:187], v10 offset:54272
	ds_read_b128 v[188:191], v10 offset:55296
	ds_read_b128 v[192:195], v10 offset:56320
	global_load_lds_dwordx4 v[160:161], off
	v_lshl_add_u64 v[160:161], v[218:219], 0, s[16:17]
	s_mov_b32 m0, s47
	s_nop 0
	global_load_lds_dwordx4 v[160:161], off
	s_barrier
; #define PG8_STAGE(bufoff, gbase, voff) do { _Pragma("unroll") for (int _i = 0; _i < 2; ++_i) \
;         __builtin_amdgcn_global_load_lds((const unsigned*)((const char*)(gbase) + (voff)[_i]), (LAS unsigned*)(lds + (bufoff) + ldsw + _i * 8192), 16, 0, 0); } while (0)
; #define PG8_LDA(dst, b, h) do { _Pragma("unroll") for (int m = 0; m < 4; ++m) _Pragma("unroll") for (int k = 0; k < 2; ++k) dst[m][k] = *(const LAS bf16x8*)(lds + PG8_SA(b, h) + aoff + m * 2048 + k * 1024); } while (0)
; #define PG8_LDB(dst, b, h) do { _Pragma("unroll") for (int n = 0; n < 2; ++n) _Pragma("unroll") for (int k = 0; k < 2; ++k) dst[n][k] = *(const LAS bf16x8*)(lds + PG8_SB(b, h) + boff + n * 2048 + k * 1024); } while (0)
; #define PG8_MMA(ai, bj, At, Bt) do { __builtin_amdgcn_s_setprio(1); _Pragma("unroll") for (int m = 0; m < 4; ++m) _Pragma("unroll") for (int n = 0; n < 2; ++n) _Pragma("unroll") for (int k = 0; k < 2; ++k) \
;         acc[ai][bj][m][n] = __builtin_amdgcn_mfma_f32_16x16x32_bf16(Bt[n][k], At[m][k], acc[ai][bj][m][n], 0, 0, 0); __builtin_amdgcn_s_setprio(0); } while (0)
; #define PG8_WAIT_V(n) asm volatile("s_waitcnt vmcnt(" #n ")" ::: "memory")
; #define PG8_WAIT_L(n) asm volatile("s_waitcnt lgkmcnt(" #n ")" ::: "memory")
; #define PG8_BAR __builtin_amdgcn_s_barrier()
; #define PG8_SCHED __builtin_amdgcn_sched_barrier(0)
; template <class Epi, class Sched>
; DI void gemm_phase(LAS unsigned char* lds, const Gemm g, const Sched& S, const Epi& E) {
;     ...
;             PG8_LDB(B0, 0, 0); PG8_SCHED; PG8_LDA(At, 0, 0); PG8_STAGE(PG8_SA(1, 1), a1 + hstep, voffA);
;             PG8_WAIT_L(8); PG8_BAR; PG8_WAIT_L(0); PG8_MMA(0, 0, At, B0); PG8_BAR; PG8_SCHED;
;             PG8_LDB(B1, 0, 1); PG8_STAGE(PG8_SB(0, 0), b2, voffB);
;     ...
;             PG8_BAR; PG8_WAIT_L(0); PG8_MMA(0, 1, At, B1); PG8_BAR;
;             PG8_LDA(At, 1, 1); PG8_STAGE(PG8_SA(1, 0), a3, voffA);
;             PG8_BAR; PG8_WAIT_L(0); PG8_MMA(1, 0, At, B0); PG8_BAR; PG8_SCHED;
;             PG8_STAGE(PG8_SB(1, 1), b3 + hstep, voffB);
;             PG8_WAIT_V(6); PG8_BAR; PG8_MMA(1, 1, At, B1); PG8_BAR;
	s_waitcnt lgkmcnt(0)
	s_setprio 1
	s_waitcnt lgkmcnt(0)
	v_mfma_f32_16x16x32_bf16 v[140:143], v[100:103], v[132:135], v[140:143]
	v_mfma_f32_16x16x32_bf16 v[144:147], v[124:127], v[132:135], v[144:147]
	v_mfma_f32_16x16x32_bf16 v[148:151], v[100:103], v[172:175], v[148:151]
	v_mfma_f32_16x16x32_bf16 v[152:155], v[124:127], v[172:175], v[152:155]
	v_mfma_f32_16x16x32_bf16 v[156:159], v[100:103], v[180:183], v[156:159]
	v_mfma_f32_16x16x32_bf16 v[168:171], v[124:127], v[180:183], v[168:171]
	v_mfma_f32_16x16x32_bf16 v[12:15], v[100:103], v[188:191], v[12:15]
	v_mfma_f32_16x16x32_bf16 v[16:19], v[124:127], v[188:191], v[16:19]
	v_mfma_f32_16x16x32_bf16 v[140:143], v[104:107], v[136:139], v[140:143]
	v_mfma_f32_16x16x32_bf16 v[144:147], v[128:131], v[136:139], v[144:147]
	v_mfma_f32_16x16x32_bf16 v[148:151], v[104:107], v[176:179], v[148:151]
	v_mfma_f32_16x16x32_bf16 v[152:155], v[128:131], v[176:179], v[152:155]
	v_mfma_f32_16x16x32_bf16 v[156:159], v[104:107], v[184:187], v[156:159]
	v_mfma_f32_16x16x32_bf16 v[168:171], v[128:131], v[184:187], v[168:171]
	v_mfma_f32_16x16x32_bf16 v[12:15], v[104:107], v[192:195], v[12:15]
	v_mfma_f32_16x16x32_bf16 v[16:19], v[128:131], v[192:195], v[16:19]
	s_setprio 0
	s_barrier
	s_add_u32 s66, s38, 0x80180
	s_addc_u32 s67, s39, 0
	s_add_i32 s39, s65, s33
	v_lshl_add_u64 v[100:101], s[66:67], 0, v[4:5]
	s_mov_b32 m0, s39
	s_add_i32 s38, s39, 0x2000
	global_load_lds_dwordx4 v[100:101], off
	v_lshl_add_u64 v[100:101], s[66:67], 0, v[2:3]
	s_mov_b32 m0, s38
	s_nop 0
	global_load_lds_dwordx4 v[100:101], off
	s_waitcnt vmcnt(6)
	s_barrier
	s_setprio 1
	v_mfma_f32_16x16x32_bf16 v[20:23], v[198:201], v[132:135], v[20:23]
	v_mfma_f32_16x16x32_bf16 v[24:27], v[206:209], v[132:135], v[24:27]
	v_mfma_f32_16x16x32_bf16 v[56:59], v[198:201], v[172:175], v[56:59]
	v_mfma_f32_16x16x32_bf16 v[100:103], v[206:209], v[172:175], v[112:115]
	v_mfma_f32_16x16x32_bf16 v[104:107], v[198:201], v[180:183], v[116:119]
	v_mfma_f32_16x16x32_bf16 v[112:115], v[206:209], v[180:183], v[120:123]
	v_mfma_f32_16x16x32_bf16 v[92:95], v[198:201], v[188:191], v[92:95]
	v_mfma_f32_16x16x32_bf16 v[96:99], v[206:209], v[188:191], v[96:99]
	v_mfma_f32_16x16x32_bf16 v[20:23], v[202:205], v[136:139], v[20:23]
	v_mfma_f32_16x16x32_bf16 v[24:27], v[210:213], v[136:139], v[24:27]
	v_mfma_f32_16x16x32_bf16 v[56:59], v[202:205], v[176:179], v[56:59]
	v_mfma_f32_16x16x32_bf16 v[100:103], v[210:213], v[176:179], v[100:103]
	v_mfma_f32_16x16x32_bf16 v[104:107], v[202:205], v[184:187], v[104:107]
	v_mfma_f32_16x16x32_bf16 v[112:115], v[210:213], v[184:187], v[112:115]
	v_mfma_f32_16x16x32_bf16 v[92:95], v[202:205], v[192:195], v[92:95]
	v_mfma_f32_16x16x32_bf16 v[96:99], v[210:213], v[192:195], v[96:99]
	s_setprio 0
	s_barrier
	ds_read_b128 v[116:119], v9
	ds_read_b128 v[120:123], v9 offset:1024
	ds_read_b128 v[124:127], v9 offset:2048
	ds_read_b128 v[128:131], v9 offset:3072
	s_add_u32 s36, s36, 0x80180
	s_addc_u32 s37, s37, 0
	s_mov_b32 m0, s53
	v_lshl_add_u64 v[160:161], s[36:37], 0, v[4:5]
	ds_read_b128 v[132:135], v10
	ds_read_b128 v[136:139], v10 offset:1024
	ds_read_b128 v[172:175], v10 offset:2048
	ds_read_b128 v[176:179], v10 offset:3072
	ds_read_b128 v[180:183], v10 offset:4096
	ds_read_b128 v[184:187], v10 offset:5120
	ds_read_b128 v[188:191], v10 offset:6144
	ds_read_b128 v[192:195], v10 offset:7168
	global_load_lds_dwordx4 v[160:161], off
	v_lshl_add_u64 v[160:161], s[36:37], 0, v[2:3]
	s_mov_b32 m0, s54
	s_nop 0
	global_load_lds_dwordx4 v[160:161], off
	s_waitcnt lgkmcnt(8)
	s_barrier
	s_waitcnt lgkmcnt(0)
	s_setprio 1
	s_waitcnt lgkmcnt(0)
	v_mfma_f32_16x16x32_bf16 v[60:63], v[116:119], v[132:135], v[60:63]
	v_mfma_f32_16x16x32_bf16 v[64:67], v[124:127], v[132:135], v[64:67]
	v_mfma_f32_16x16x32_bf16 v[68:71], v[116:119], v[172:175], v[68:71]
	v_mfma_f32_16x16x32_bf16 v[72:75], v[124:127], v[172:175], v[72:75]
	v_mfma_f32_16x16x32_bf16 v[76:79], v[116:119], v[180:183], v[76:79]
	v_mfma_f32_16x16x32_bf16 v[80:83], v[124:127], v[180:183], v[80:83]
	v_mfma_f32_16x16x32_bf16 v[84:87], v[116:119], v[188:191], v[84:87]
	v_mfma_f32_16x16x32_bf16 v[88:91], v[124:127], v[188:191], v[88:91]
	v_mfma_f32_16x16x32_bf16 v[60:63], v[120:123], v[136:139], v[60:63]
	v_mfma_f32_16x16x32_bf16 v[64:67], v[128:131], v[136:139], v[64:67]
	v_mfma_f32_16x16x32_bf16 v[68:71], v[120:123], v[176:179], v[68:71]
	v_mfma_f32_16x16x32_bf16 v[72:75], v[128:131], v[176:179], v[72:75]
	v_mfma_f32_16x16x32_bf16 v[76:79], v[120:123], v[184:187], v[76:79]
	v_mfma_f32_16x16x32_bf16 v[80:83], v[128:131], v[184:187], v[80:83]
	v_mfma_f32_16x16x32_bf16 v[84:87], v[120:123], v[192:195], v[84:87]
	v_mfma_f32_16x16x32_bf16 v[88:91], v[128:131], v[192:195], v[88:91]
	s_setprio 0
	s_barrier
	s_mov_b32 m0, s29
	v_lshl_add_u64 v[160:161], s[0:1], 0, v[4:5]
	ds_read_b128 v[198:201], v11
	ds_read_b128 v[202:205], v11 offset:1024
	ds_read_b128 v[206:209], v11 offset:2048
	ds_read_b128 v[210:213], v11 offset:3072
	global_load_lds_dwordx4 v[160:161], off
	v_lshl_add_u64 v[214:215], s[0:1], 0, v[2:3]
	s_mov_b32 m0, s25
	s_nop 0
	global_load_lds_dwordx4 v[214:215], off
	s_barrier
; #define PG8_STAGE(bufoff, gbase, voff) do { _Pragma("unroll") for (int _i = 0; _i < 2; ++_i) \
;         __builtin_amdgcn_global_load_lds((const unsigned*)((const char*)(gbase) + (voff)[_i]), (LAS unsigned*)(lds + (bufoff) + ldsw + _i * 8192), 16, 0, 0); } while (0)
; #define PG8_LDA(dst, b, h) do { _Pragma("unroll") for (int m = 0; m < 4; ++m) _Pragma("unroll") for (int k = 0; k < 2; ++k) dst[m][k] = *(const LAS bf16x8*)(lds + PG8_SA(b, h) + aoff + m * 2048 + k * 1024); } while (0)
; #define PG8_LDB(dst, b, h) do { _Pragma("unroll") for (int n = 0; n < 2; ++n) _Pragma("unroll") for (int k = 0; k < 2; ++k) dst[n][k] = *(const LAS bf16x8*)(lds + PG8_SB(b, h) + boff + n * 2048 + k * 1024); } while (0)
; #define PG8_MMA(ai, bj, At, Bt) do { __builtin_amdgcn_s_setprio(1); _Pragma("unroll") for (int m = 0; m < 4; ++m) _Pragma("unroll") for (int n = 0; n < 2; ++n) _Pragma("unroll") for (int k = 0; k < 2; ++k) \
;         acc[ai][bj][m][n] = __builtin_amdgcn_mfma_f32_16x16x32_bf16(Bt[n][k], At[m][k], acc[ai][bj][m][n], 0, 0, 0); __builtin_amdgcn_s_setprio(0); } while (0)
; #define PG8_WAIT_V(n) asm volatile("s_waitcnt vmcnt(" #n ")" ::: "memory")
; #define PG8_WAIT_L(n) asm volatile("s_waitcnt lgkmcnt(" #n ")" ::: "memory")
; #define PG8_BAR __builtin_amdgcn_s_barrier()
; #define PG8_SCHED __builtin_amdgcn_sched_barrier(0)
; template <class Epi, class Sched>
; DI void gemm_phase(LAS unsigned char* lds, const Gemm g, const Sched& S, const Epi& E) {
;     ...
;             PG8_BAR; PG8_WAIT_L(0); PG8_MMA(0, 1, At, B1); PG8_BAR;
;             PG8_LDA(At, 0, 1); PG8_STAGE(PG8_SA(0, 0), a2, voffA);
;             PG8_BAR; PG8_WAIT_L(0); PG8_MMA(1, 0, At, B0); PG8_BAR; PG8_SCHED;
;             PG8_STAGE(PG8_SB(0, 1), b2 + hstep, voffB);
;             PG8_WAIT_V(6); PG8_BAR; PG8_MMA(1, 1, At, B1); PG8_BAR;
;             PG8_LDB(B0, 1, 0); PG8_SCHED; PG8_LDA(At, 1, 0); PG8_STAGE(PG8_SA(0, 1), a2 + hstep, voffA);
	s_waitcnt lgkmcnt(0)
	s_setprio 1
	s_waitcnt lgkmcnt(0)
	v_mfma_f32_16x16x32_bf16 v[108:111], v[198:201], v[132:135], v[108:111]
	v_mfma_f32_16x16x32_bf16 v[28:31], v[206:209], v[132:135], v[28:31]
	v_mfma_f32_16x16x32_bf16 v[32:35], v[198:201], v[172:175], v[32:35]
	v_mfma_f32_16x16x32_bf16 v[36:39], v[206:209], v[172:175], v[36:39]
	v_mfma_f32_16x16x32_bf16 v[40:43], v[198:201], v[180:183], v[40:43]
	v_mfma_f32_16x16x32_bf16 v[44:47], v[206:209], v[180:183], v[44:47]
	v_mfma_f32_16x16x32_bf16 v[48:51], v[198:201], v[188:191], v[48:51]
	v_mfma_f32_16x16x32_bf16 v[52:55], v[206:209], v[188:191], v[52:55]
	v_mfma_f32_16x16x32_bf16 v[108:111], v[202:205], v[136:139], v[108:111]
	v_mfma_f32_16x16x32_bf16 v[28:31], v[210:213], v[136:139], v[28:31]
	v_mfma_f32_16x16x32_bf16 v[32:35], v[202:205], v[176:179], v[32:35]
	v_mfma_f32_16x16x32_bf16 v[36:39], v[210:213], v[176:179], v[36:39]
	v_mfma_f32_16x16x32_bf16 v[40:43], v[202:205], v[184:187], v[40:43]
	v_mfma_f32_16x16x32_bf16 v[44:47], v[210:213], v[184:187], v[44:47]
	v_mfma_f32_16x16x32_bf16 v[48:51], v[202:205], v[192:195], v[48:51]
	v_mfma_f32_16x16x32_bf16 v[52:55], v[210:213], v[192:195], v[52:55]
	s_setprio 0
	s_mov_b32 m0, s7
	v_lshl_add_u64 v[216:217], s[34:35], 0, v[4:5]
	s_barrier
	ds_read_b128 v[132:135], v10 offset:16384
	ds_read_b128 v[136:139], v10 offset:17408
	ds_read_b128 v[172:175], v10 offset:18432
	ds_read_b128 v[176:179], v10 offset:19456
	ds_read_b128 v[180:183], v10 offset:20480
	ds_read_b128 v[184:187], v10 offset:21504
	ds_read_b128 v[188:191], v10 offset:22528
	ds_read_b128 v[192:195], v10 offset:23552
	global_load_lds_dwordx4 v[216:217], off
	v_lshl_add_u64 v[218:219], s[34:35], 0, v[2:3]
	s_mov_b32 m0, s40
	s_nop 0
	global_load_lds_dwordx4 v[218:219], off
	s_barrier
	s_waitcnt lgkmcnt(0)
	s_setprio 1
	s_waitcnt lgkmcnt(0)
	v_mfma_f32_16x16x32_bf16 v[140:143], v[116:119], v[132:135], v[140:143]
	v_mfma_f32_16x16x32_bf16 v[144:147], v[124:127], v[132:135], v[144:147]
	v_mfma_f32_16x16x32_bf16 v[148:151], v[116:119], v[172:175], v[148:151]
	v_mfma_f32_16x16x32_bf16 v[152:155], v[124:127], v[172:175], v[152:155]
	v_mfma_f32_16x16x32_bf16 v[156:159], v[116:119], v[180:183], v[156:159]
	v_mfma_f32_16x16x32_bf16 v[168:171], v[124:127], v[180:183], v[168:171]
	v_mfma_f32_16x16x32_bf16 v[12:15], v[116:119], v[188:191], v[12:15]
	v_mfma_f32_16x16x32_bf16 v[16:19], v[124:127], v[188:191], v[16:19]
	v_mfma_f32_16x16x32_bf16 v[140:143], v[120:123], v[136:139], v[140:143]
	v_mfma_f32_16x16x32_bf16 v[144:147], v[128:131], v[136:139], v[144:147]
	v_mfma_f32_16x16x32_bf16 v[148:151], v[120:123], v[176:179], v[148:151]
	v_mfma_f32_16x16x32_bf16 v[152:155], v[128:131], v[176:179], v[152:155]
	v_mfma_f32_16x16x32_bf16 v[156:159], v[120:123], v[184:187], v[156:159]
	v_mfma_f32_16x16x32_bf16 v[168:171], v[128:131], v[184:187], v[168:171]
	v_mfma_f32_16x16x32_bf16 v[12:15], v[120:123], v[192:195], v[12:15]
	v_mfma_f32_16x16x32_bf16 v[16:19], v[128:131], v[192:195], v[16:19]
	s_setprio 0
	s_barrier
	s_add_u32 s36, s0, 0x80000
	s_addc_u32 s37, s1, 0
	s_mov_b32 m0, s62
	v_lshl_add_u64 v[116:117], s[36:37], 0, v[4:5]
	global_load_lds_dwordx4 v[116:117], off
	v_lshl_add_u64 v[116:117], s[36:37], 0, v[2:3]
	s_mov_b32 m0, s27
	s_nop 0
	global_load_lds_dwordx4 v[116:117], off
	s_waitcnt vmcnt(6)
	s_barrier
	s_setprio 1
	v_mfma_f32_16x16x32_bf16 v[20:23], v[198:201], v[132:135], v[20:23]
	v_mfma_f32_16x16x32_bf16 v[24:27], v[206:209], v[132:135], v[24:27]
	v_mfma_f32_16x16x32_bf16 v[56:59], v[198:201], v[172:175], v[56:59]
	v_mfma_f32_16x16x32_bf16 v[100:103], v[206:209], v[172:175], v[100:103]
	v_mfma_f32_16x16x32_bf16 v[104:107], v[198:201], v[180:183], v[104:107]
	v_mfma_f32_16x16x32_bf16 v[112:115], v[206:209], v[180:183], v[112:115]
	v_mfma_f32_16x16x32_bf16 v[92:95], v[198:201], v[188:191], v[92:95]
	v_mfma_f32_16x16x32_bf16 v[96:99], v[206:209], v[188:191], v[96:99]
	v_mfma_f32_16x16x32_bf16 v[20:23], v[202:205], v[136:139], v[20:23]
	v_mfma_f32_16x16x32_bf16 v[24:27], v[210:213], v[136:139], v[24:27]
	v_mfma_f32_16x16x32_bf16 v[56:59], v[202:205], v[176:179], v[56:59]
	v_mfma_f32_16x16x32_bf16 v[100:103], v[210:213], v[176:179], v[100:103]
	v_mfma_f32_16x16x32_bf16 v[104:107], v[202:205], v[184:187], v[104:107]
	v_mfma_f32_16x16x32_bf16 v[112:115], v[210:213], v[184:187], v[112:115]
	v_mfma_f32_16x16x32_bf16 v[92:95], v[202:205], v[192:195], v[92:95]
	v_mfma_f32_16x16x32_bf16 v[96:99], v[210:213], v[192:195], v[96:99]
	s_setprio 0
	s_barrier
	ds_read_b128 v[116:119], v165
	ds_read_b128 v[120:123], v165 offset:1024
	ds_read_b128 v[124:127], v165 offset:2048
	ds_read_b128 v[128:131], v165 offset:3072
	s_add_u32 s36, s34, 0x80000
	s_addc_u32 s37, s35, 0
	s_mov_b32 m0, s41
	v_lshl_add_u64 v[198:199], s[36:37], 0, v[4:5]
	ds_read_b128 v[132:135], v10 offset:32768
	ds_read_b128 v[136:139], v10 offset:33792
	ds_read_b128 v[172:175], v10 offset:34816
	ds_read_b128 v[176:179], v10 offset:35840
	ds_read_b128 v[180:183], v10 offset:36864
	ds_read_b128 v[184:187], v10 offset:37888
	ds_read_b128 v[188:191], v10 offset:38912
	ds_read_b128 v[192:195], v10 offset:39936
	global_load_lds_dwordx4 v[198:199], off
	v_lshl_add_u64 v[198:199], s[36:37], 0, v[2:3]
	s_mov_b32 m0, s42
	s_nop 0
	global_load_lds_dwordx4 v[198:199], off
	s_waitcnt lgkmcnt(8)
	s_barrier
; #define PG8_STAGE(bufoff, gbase, voff) do { _Pragma("unroll") for (int _i = 0; _i < 2; ++_i) \
;         __builtin_amdgcn_global_load_lds((const unsigned*)((const char*)(gbase) + (voff)[_i]), (LAS unsigned*)(lds + (bufoff) + ldsw + _i * 8192), 16, 0, 0); } while (0)
; #define PG8_LDA(dst, b, h) do { _Pragma("unroll") for (int m = 0; m < 4; ++m) _Pragma("unroll") for (int k = 0; k < 2; ++k) dst[m][k] = *(const LAS bf16x8*)(lds + PG8_SA(b, h) + aoff + m * 2048 + k * 1024); } while (0)
; #define PG8_LDB(dst, b, h) do { _Pragma("unroll") for (int n = 0; n < 2; ++n) _Pragma("unroll") for (int k = 0; k < 2; ++k) dst[n][k] = *(const LAS bf16x8*)(lds + PG8_SB(b, h) + boff + n * 2048 + k * 1024); } while (0)
; #define PG8_MMA(ai, bj, At, Bt) do { __builtin_amdgcn_s_setprio(1); _Pragma("unroll") for (int m = 0; m < 4; ++m) _Pragma("unroll") for (int n = 0; n < 2; ++n) _Pragma("unroll") for (int k = 0; k < 2; ++k) \
;         acc[ai][bj][m][n] = __builtin_amdgcn_mfma_f32_16x16x32_bf16(Bt[n][k], At[m][k], acc[ai][bj][m][n], 0, 0, 0); __builtin_amdgcn_s_setprio(0); } while (0)
; #define PG8_WAIT_V(n) asm volatile("s_waitcnt vmcnt(" #n ")" ::: "memory")
; #define PG8_WAIT_L(n) asm volatile("s_waitcnt lgkmcnt(" #n ")" ::: "memory")
; #define PG8_BAR __builtin_amdgcn_s_barrier()
; #define PG8_SCHED __builtin_amdgcn_sched_barrier(0)
; template <class Epi, class Sched>
; DI void gemm_phase(LAS unsigned char* lds, const Gemm g, const Sched& S, const Epi& E) {
;     ...
;             PG8_WAIT_L(8); PG8_BAR; PG8_WAIT_L(0); PG8_MMA(0, 0, At, B0); PG8_BAR; PG8_SCHED;
;             PG8_LDB(B1, 1, 1); PG8_STAGE(PG8_SB(1, 0), b3, voffB);
;             PG8_BAR; PG8_WAIT_L(0); PG8_MMA(0, 1, At, B1); PG8_BAR;
;             PG8_LDA(At, 1, 1); PG8_STAGE(PG8_SA(1, 0), a3, voffA);
;             PG8_BAR; PG8_WAIT_L(0); PG8_MMA(1, 0, At, B0); PG8_BAR; PG8_SCHED;
;             PG8_STAGE(PG8_SB(1, 1), b3 + hstep, voffB);
;             PG8_WAIT_V(6); PG8_BAR; PG8_MMA(1, 1, At, B1); PG8_BAR;
	s_waitcnt lgkmcnt(0)
	s_setprio 1
	s_waitcnt lgkmcnt(0)
	v_mfma_f32_16x16x32_bf16 v[60:63], v[116:119], v[132:135], v[60:63]
	v_mfma_f32_16x16x32_bf16 v[64:67], v[124:127], v[132:135], v[64:67]
	v_mfma_f32_16x16x32_bf16 v[68:71], v[116:119], v[172:175], v[68:71]
	v_mfma_f32_16x16x32_bf16 v[72:75], v[124:127], v[172:175], v[72:75]
	v_mfma_f32_16x16x32_bf16 v[76:79], v[116:119], v[180:183], v[76:79]
	v_mfma_f32_16x16x32_bf16 v[80:83], v[124:127], v[180:183], v[80:83]
	v_mfma_f32_16x16x32_bf16 v[84:87], v[116:119], v[188:191], v[84:87]
	v_mfma_f32_16x16x32_bf16 v[88:91], v[124:127], v[188:191], v[88:91]
	v_mfma_f32_16x16x32_bf16 v[60:63], v[120:123], v[136:139], v[60:63]
	v_mfma_f32_16x16x32_bf16 v[64:67], v[128:131], v[136:139], v[64:67]
	v_mfma_f32_16x16x32_bf16 v[68:71], v[120:123], v[176:179], v[68:71]
	v_mfma_f32_16x16x32_bf16 v[72:75], v[128:131], v[176:179], v[72:75]
	v_mfma_f32_16x16x32_bf16 v[76:79], v[120:123], v[184:187], v[76:79]
	v_mfma_f32_16x16x32_bf16 v[80:83], v[128:131], v[184:187], v[80:83]
	v_mfma_f32_16x16x32_bf16 v[84:87], v[120:123], v[192:195], v[84:87]
	v_mfma_f32_16x16x32_bf16 v[88:91], v[128:131], v[192:195], v[88:91]
	s_setprio 0
	s_barrier
	s_mov_b32 m0, s64
	v_lshl_add_u64 v[160:161], v[160:161], 0, s[12:13]
	ds_read_b128 v[198:201], v167
	ds_read_b128 v[202:205], v167 offset:1024
	ds_read_b128 v[206:209], v167 offset:2048
	ds_read_b128 v[210:213], v167 offset:3072
	global_load_lds_dwordx4 v[160:161], off
	v_lshl_add_u64 v[160:161], v[214:215], 0, s[12:13]
	s_mov_b32 m0, s63
	s_nop 0
	global_load_lds_dwordx4 v[160:161], off
	s_barrier
	s_waitcnt lgkmcnt(0)
	s_setprio 1
	s_waitcnt lgkmcnt(0)
	v_mfma_f32_16x16x32_bf16 v[108:111], v[198:201], v[132:135], v[108:111]
	v_mfma_f32_16x16x32_bf16 v[28:31], v[206:209], v[132:135], v[28:31]
	v_mfma_f32_16x16x32_bf16 v[32:35], v[198:201], v[172:175], v[32:35]
	v_mfma_f32_16x16x32_bf16 v[36:39], v[206:209], v[172:175], v[36:39]
	v_mfma_f32_16x16x32_bf16 v[40:43], v[198:201], v[180:183], v[40:43]
	v_mfma_f32_16x16x32_bf16 v[44:47], v[206:209], v[180:183], v[44:47]
	v_mfma_f32_16x16x32_bf16 v[48:51], v[198:201], v[188:191], v[48:51]
	v_mfma_f32_16x16x32_bf16 v[52:55], v[206:209], v[188:191], v[52:55]
	v_mfma_f32_16x16x32_bf16 v[108:111], v[202:205], v[136:139], v[108:111]
	v_mfma_f32_16x16x32_bf16 v[28:31], v[210:213], v[136:139], v[28:31]
	v_mfma_f32_16x16x32_bf16 v[32:35], v[202:205], v[176:179], v[32:35]
	v_mfma_f32_16x16x32_bf16 v[36:39], v[210:213], v[176:179], v[36:39]
	v_mfma_f32_16x16x32_bf16 v[40:43], v[202:205], v[184:187], v[40:43]
	v_mfma_f32_16x16x32_bf16 v[44:47], v[210:213], v[184:187], v[44:47]
	v_mfma_f32_16x16x32_bf16 v[48:51], v[202:205], v[192:195], v[48:51]
	v_mfma_f32_16x16x32_bf16 v[52:55], v[210:213], v[192:195], v[52:55]
	s_setprio 0
	s_mov_b32 m0, s43
	v_lshl_add_u64 v[160:161], v[216:217], 0, s[12:13]
	s_barrier
	ds_read_b128 v[132:135], v10 offset:49152
	ds_read_b128 v[136:139], v10 offset:50176
	ds_read_b128 v[172:175], v10 offset:51200
	ds_read_b128 v[176:179], v10 offset:52224
	ds_read_b128 v[180:183], v10 offset:53248
	ds_read_b128 v[184:187], v10 offset:54272
	ds_read_b128 v[188:191], v10 offset:55296
	ds_read_b128 v[192:195], v10 offset:56320
	global_load_lds_dwordx4 v[160:161], off
	v_lshl_add_u64 v[160:161], v[218:219], 0, s[12:13]
	s_mov_b32 m0, s47
	s_nop 0
	global_load_lds_dwordx4 v[160:161], off
	s_barrier
	s_waitcnt lgkmcnt(0)
	s_setprio 1
	s_waitcnt lgkmcnt(0)
	v_mfma_f32_16x16x32_bf16 v[140:143], v[116:119], v[132:135], v[140:143]
	v_mfma_f32_16x16x32_bf16 v[144:147], v[124:127], v[132:135], v[144:147]
	v_mfma_f32_16x16x32_bf16 v[148:151], v[116:119], v[172:175], v[148:151]
	v_mfma_f32_16x16x32_bf16 v[152:155], v[124:127], v[172:175], v[152:155]
	v_mfma_f32_16x16x32_bf16 v[156:159], v[116:119], v[180:183], v[156:159]
	v_mfma_f32_16x16x32_bf16 v[168:171], v[124:127], v[180:183], v[168:171]
	v_mfma_f32_16x16x32_bf16 v[12:15], v[116:119], v[188:191], v[12:15]
	v_mfma_f32_16x16x32_bf16 v[16:19], v[124:127], v[188:191], v[16:19]
	v_mfma_f32_16x16x32_bf16 v[140:143], v[120:123], v[136:139], v[140:143]
	v_mfma_f32_16x16x32_bf16 v[144:147], v[128:131], v[136:139], v[144:147]
	v_mfma_f32_16x16x32_bf16 v[148:151], v[120:123], v[176:179], v[148:151]
	v_mfma_f32_16x16x32_bf16 v[152:155], v[128:131], v[176:179], v[152:155]
	v_mfma_f32_16x16x32_bf16 v[156:159], v[120:123], v[184:187], v[156:159]
	v_mfma_f32_16x16x32_bf16 v[168:171], v[128:131], v[184:187], v[168:171]
	v_mfma_f32_16x16x32_bf16 v[12:15], v[120:123], v[192:195], v[12:15]
	v_mfma_f32_16x16x32_bf16 v[16:19], v[128:131], v[192:195], v[16:19]
	s_setprio 0
	s_barrier
	s_add_u32 s36, s0, 0x80080
	s_addc_u32 s37, s1, 0
	s_mov_b32 m0, s39
	v_lshl_add_u64 v[116:117], s[36:37], 0, v[4:5]
	global_load_lds_dwordx4 v[116:117], off
	v_lshl_add_u64 v[116:117], s[36:37], 0, v[2:3]
	s_mov_b32 m0, s38
	s_nop 0
	global_load_lds_dwordx4 v[116:117], off
	s_waitcnt vmcnt(6)
	s_barrier
; #define PG8_MMA(ai, bj, At, Bt) do { __builtin_amdgcn_s_setprio(1); _Pragma("unroll") for (int m = 0; m < 4; ++m) _Pragma("unroll") for (int n = 0; n < 2; ++n) _Pragma("unroll") for (int k = 0; k < 2; ++k) \
;         acc[ai][bj][m][n] = __builtin_amdgcn_mfma_f32_16x16x32_bf16(Bt[n][k], At[m][k], acc[ai][bj][m][n], 0, 0, 0); __builtin_amdgcn_s_setprio(0); } while (0)
; #define PG8_WAIT_V(n) asm volatile("s_waitcnt vmcnt(" #n ")" ::: "memory")
; #define PG8_BAR __builtin_amdgcn_s_barrier()
;     DI void operator()(const f32x4 (&acc)[2][2][4][2], const Unit& u, int wr, int wc, int fr, int fq) const {
;         const int row0 = (u.pm - 64) * BM + wr * 64 + fr, col0 = u.pn * BM + wc * 32 + 4 * fq;
;         float* base = P + (size_t)u.slice * 1048576;
; #pragma unroll
;         for (int ai = 0; ai < 2; ++ai)
; #pragma unroll
;             for (int m = 0; m < 4; ++m) { float* op = base + (size_t)(row0 + ai * HALF + m * 16) * 1024 + col0;
; #pragma unroll
;                 for (int bj = 0; bj < 2; ++bj)
; #pragma unroll
;                     for (int n = 0; n < 2; ++n) *(f32x4*)(op + bj * HALF + n * 16) = acc[ai][bj][m][n]; }
; template <class Epi, class Sched>
; DI void gemm_phase(LAS unsigned char* lds, const Gemm g, const Sched& S, const Epi& E) {
;     ...
;             PG8_WAIT_V(6); PG8_BAR; PG8_MMA(1, 1, At, B1); PG8_BAR;
	s_setprio 1
	v_mfma_f32_16x16x32_bf16 v[20:23], v[198:201], v[132:135], v[20:23]
	v_mfma_f32_16x16x32_bf16 v[24:27], v[206:209], v[132:135], v[24:27]
	v_mfma_f32_16x16x32_bf16 v[56:59], v[198:201], v[172:175], v[56:59]
	v_mfma_f32_16x16x32_bf16 v[100:103], v[206:209], v[172:175], v[100:103]
	v_mfma_f32_16x16x32_bf16 v[104:107], v[198:201], v[180:183], v[104:107]
	v_mfma_f32_16x16x32_bf16 v[112:115], v[206:209], v[180:183], v[112:115]
	v_mfma_f32_16x16x32_bf16 v[92:95], v[198:201], v[188:191], v[92:95]
	v_mfma_f32_16x16x32_bf16 v[96:99], v[206:209], v[188:191], v[96:99]
	v_mfma_f32_16x16x32_bf16 v[20:23], v[202:205], v[136:139], v[20:23]
	v_mfma_f32_16x16x32_bf16 v[24:27], v[210:213], v[136:139], v[24:27]
	v_mfma_f32_16x16x32_bf16 v[56:59], v[202:205], v[176:179], v[56:59]
	v_mfma_f32_16x16x32_bf16 v[100:103], v[210:213], v[176:179], v[100:103]
	v_mfma_f32_16x16x32_bf16 v[104:107], v[202:205], v[184:187], v[104:107]
	v_mfma_f32_16x16x32_bf16 v[112:115], v[210:213], v[184:187], v[112:115]
	v_mfma_f32_16x16x32_bf16 v[92:95], v[202:205], v[192:195], v[92:95]
	v_mfma_f32_16x16x32_bf16 v[96:99], v[210:213], v[192:195], v[96:99]
	s_setprio 0
	v_and_b32_e32 v221, 63, v1
	v_lshrrev_b32_e32 v222, 3, v221
	v_and_b32_e32 v223, 3, v221
	v_lshl_or_b32 v223, v223, 4, v222
	v_lshlrev_b32_e32 v216, 2, v223
	v_add_u32_e32 v217, 32, v216
	v_and_b32_e32 v223, 0xffffffe0, v8
	v_lshl_or_b32 v223, s9, 8, v223
	v_and_b32_e32 v224, 0xffffffc0, v7
	v_add_u32_e32 v224, v224, v222
	v_lshl_add_u32 v224, s6, 8, v224
	s_ashr_i32 s9, s8, 31
	s_lshl_b64 s[8:9], s[8:9], 22
	s_add_u32 s8, s60, s8
	s_addc_u32 s9, s61, s9
	v_lshlrev_b32_e32 v224, 12, v224
	v_lshl_add_u32 v224, v223, 2, v224
	v_and_b32_e32 v221, 7, v221
	v_lshl_add_u32 v218, v221, 4, v224
	s_mov_b32 s98, 0xf0f0f0f0
	s_mov_b32 s99, 0xf0f0f0f0
	s_barrier
	ds_bpermute_b32 v200, v216, v60
	ds_bpermute_b32 v201, v216, v61
	ds_bpermute_b32 v202, v216, v62
	ds_bpermute_b32 v203, v216, v63
	ds_bpermute_b32 v204, v216, v64
	ds_bpermute_b32 v205, v216, v65
	ds_bpermute_b32 v206, v216, v66
	ds_bpermute_b32 v207, v216, v67
	s_waitcnt lgkmcnt(0)
	v_cndmask_b32_e64 v200, v200, v204, s[98:99]
	v_cndmask_b32_e64 v201, v201, v205, s[98:99]
	v_cndmask_b32_e64 v202, v202, v206, s[98:99]
	v_cndmask_b32_e64 v203, v203, v207, s[98:99]
	global_store_dwordx4 v218, v[200:203], s[8:9]
	s_nop 1
	ds_bpermute_b32 v200, v217, v60
	ds_bpermute_b32 v201, v217, v61
	ds_bpermute_b32 v202, v217, v62
	ds_bpermute_b32 v203, v217, v63
	ds_bpermute_b32 v204, v217, v64
	ds_bpermute_b32 v205, v217, v65
	ds_bpermute_b32 v206, v217, v66
	ds_bpermute_b32 v207, v217, v67
	v_add_u32_e32 v220, 0x8000, v218
	s_waitcnt lgkmcnt(0)
	v_cndmask_b32_e64 v200, v200, v204, s[98:99]
	v_cndmask_b32_e64 v201, v201, v205, s[98:99]
	v_cndmask_b32_e64 v202, v202, v206, s[98:99]
	v_cndmask_b32_e64 v203, v203, v207, s[98:99]
	global_store_dwordx4 v220, v[200:203], s[8:9]
	s_nop 1
	ds_bpermute_b32 v200, v216, v108
	ds_bpermute_b32 v201, v216, v109
	ds_bpermute_b32 v202, v216, v110
	ds_bpermute_b32 v203, v216, v111
	ds_bpermute_b32 v204, v216, v28
	ds_bpermute_b32 v205, v216, v29
	ds_bpermute_b32 v206, v216, v30
	ds_bpermute_b32 v207, v216, v31
	s_waitcnt lgkmcnt(0)
	v_cndmask_b32_e64 v200, v200, v204, s[98:99]
	v_cndmask_b32_e64 v201, v201, v205, s[98:99]
	v_cndmask_b32_e64 v202, v202, v206, s[98:99]
	v_cndmask_b32_e64 v203, v203, v207, s[98:99]
	global_store_dwordx4 v218, v[200:203], s[8:9] offset:512
	s_nop 1
	ds_bpermute_b32 v200, v217, v108
	ds_bpermute_b32 v201, v217, v109
	ds_bpermute_b32 v202, v217, v110
	ds_bpermute_b32 v203, v217, v111
	ds_bpermute_b32 v204, v217, v28
	ds_bpermute_b32 v205, v217, v29
	ds_bpermute_b32 v206, v217, v30
	ds_bpermute_b32 v207, v217, v31
	v_add_u32_e32 v220, 0x8000, v218
	s_waitcnt lgkmcnt(0)
	v_cndmask_b32_e64 v200, v200, v204, s[98:99]
	v_cndmask_b32_e64 v201, v201, v205, s[98:99]
	v_cndmask_b32_e64 v202, v202, v206, s[98:99]
	v_cndmask_b32_e64 v203, v203, v207, s[98:99]
	global_store_dwordx4 v220, v[200:203], s[8:9] offset:512
	s_nop 1
	ds_bpermute_b32 v200, v216, v68
	ds_bpermute_b32 v201, v216, v69
	ds_bpermute_b32 v202, v216, v70
	ds_bpermute_b32 v203, v216, v71
	ds_bpermute_b32 v204, v216, v72
	ds_bpermute_b32 v205, v216, v73
	ds_bpermute_b32 v206, v216, v74
	ds_bpermute_b32 v207, v216, v75
	v_add_u32_e32 v219, 0x10000, v218
	s_waitcnt lgkmcnt(0)
	v_cndmask_b32_e64 v200, v200, v204, s[98:99]
	v_cndmask_b32_e64 v201, v201, v205, s[98:99]
	v_cndmask_b32_e64 v202, v202, v206, s[98:99]
	v_cndmask_b32_e64 v203, v203, v207, s[98:99]
	global_store_dwordx4 v219, v[200:203], s[8:9]
	s_nop 1
	ds_bpermute_b32 v200, v217, v68
	ds_bpermute_b32 v201, v217, v69
	ds_bpermute_b32 v202, v217, v70
	ds_bpermute_b32 v203, v217, v71
	ds_bpermute_b32 v204, v217, v72
	ds_bpermute_b32 v205, v217, v73
	ds_bpermute_b32 v206, v217, v74
	ds_bpermute_b32 v207, v217, v75
	v_add_u32_e32 v220, 0x18000, v218
	s_waitcnt lgkmcnt(0)
	v_cndmask_b32_e64 v200, v200, v204, s[98:99]
	v_cndmask_b32_e64 v201, v201, v205, s[98:99]
	v_cndmask_b32_e64 v202, v202, v206, s[98:99]
	v_cndmask_b32_e64 v203, v203, v207, s[98:99]
	global_store_dwordx4 v220, v[200:203], s[8:9]
	s_nop 1
	ds_bpermute_b32 v200, v216, v32
	ds_bpermute_b32 v201, v216, v33
	ds_bpermute_b32 v202, v216, v34
	ds_bpermute_b32 v203, v216, v35
	ds_bpermute_b32 v204, v216, v36
	ds_bpermute_b32 v205, v216, v37
	ds_bpermute_b32 v206, v216, v38
	ds_bpermute_b32 v207, v216, v39
	v_add_u32_e32 v219, 0x10000, v218
	s_waitcnt lgkmcnt(0)
;     DI void operator()(const f32x4 (&acc)[2][2][4][2], const Unit& u, int wr, int wc, int fr, int fq) const {
;         const int row0 = (u.pm - 64) * BM + wr * 64 + fr, col0 = u.pn * BM + wc * 32 + 4 * fq;
;         float* base = P + (size_t)u.slice * 1048576;
; #pragma unroll
;         for (int ai = 0; ai < 2; ++ai)
; #pragma unroll
;             for (int m = 0; m < 4; ++m) { float* op = base + (size_t)(row0 + ai * HALF + m * 16) * 1024 + col0;
; #pragma unroll
;                 for (int bj = 0; bj < 2; ++bj)
; #pragma unroll
;                     for (int n = 0; n < 2; ++n) *(f32x4*)(op + bj * HALF + n * 16) = acc[ai][bj][m][n]; }
	v_cndmask_b32_e64 v200, v200, v204, s[98:99]
	v_cndmask_b32_e64 v201, v201, v205, s[98:99]
	v_cndmask_b32_e64 v202, v202, v206, s[98:99]
	v_cndmask_b32_e64 v203, v203, v207, s[98:99]
	global_store_dwordx4 v219, v[200:203], s[8:9] offset:512
	s_nop 1
	ds_bpermute_b32 v200, v217, v32
	ds_bpermute_b32 v201, v217, v33
	ds_bpermute_b32 v202, v217, v34
	ds_bpermute_b32 v203, v217, v35
	ds_bpermute_b32 v204, v217, v36
	ds_bpermute_b32 v205, v217, v37
	ds_bpermute_b32 v206, v217, v38
	ds_bpermute_b32 v207, v217, v39
	v_add_u32_e32 v220, 0x18000, v218
	s_waitcnt lgkmcnt(0)
	v_cndmask_b32_e64 v200, v200, v204, s[98:99]
	v_cndmask_b32_e64 v201, v201, v205, s[98:99]
	v_cndmask_b32_e64 v202, v202, v206, s[98:99]
	v_cndmask_b32_e64 v203, v203, v207, s[98:99]
	global_store_dwordx4 v220, v[200:203], s[8:9] offset:512
	s_nop 1
	ds_bpermute_b32 v200, v216, v76
	ds_bpermute_b32 v201, v216, v77
	ds_bpermute_b32 v202, v216, v78
	ds_bpermute_b32 v203, v216, v79
	ds_bpermute_b32 v204, v216, v80
	ds_bpermute_b32 v205, v216, v81
	ds_bpermute_b32 v206, v216, v82
	ds_bpermute_b32 v207, v216, v83
	v_add_u32_e32 v219, 0x20000, v218
	s_waitcnt lgkmcnt(0)
	v_cndmask_b32_e64 v200, v200, v204, s[98:99]
	v_cndmask_b32_e64 v201, v201, v205, s[98:99]
	v_cndmask_b32_e64 v202, v202, v206, s[98:99]
	v_cndmask_b32_e64 v203, v203, v207, s[98:99]
	global_store_dwordx4 v219, v[200:203], s[8:9]
	s_nop 1
	ds_bpermute_b32 v200, v217, v76
	ds_bpermute_b32 v201, v217, v77
	ds_bpermute_b32 v202, v217, v78
	ds_bpermute_b32 v203, v217, v79
	ds_bpermute_b32 v204, v217, v80
	ds_bpermute_b32 v205, v217, v81
	ds_bpermute_b32 v206, v217, v82
	ds_bpermute_b32 v207, v217, v83
	v_add_u32_e32 v220, 0x28000, v218
	s_waitcnt lgkmcnt(0)
	v_cndmask_b32_e64 v200, v200, v204, s[98:99]
	v_cndmask_b32_e64 v201, v201, v205, s[98:99]
	v_cndmask_b32_e64 v202, v202, v206, s[98:99]
	v_cndmask_b32_e64 v203, v203, v207, s[98:99]
	global_store_dwordx4 v220, v[200:203], s[8:9]
	s_nop 1
	ds_bpermute_b32 v200, v216, v40
	ds_bpermute_b32 v201, v216, v41
	ds_bpermute_b32 v202, v216, v42
	ds_bpermute_b32 v203, v216, v43
	ds_bpermute_b32 v204, v216, v44
	ds_bpermute_b32 v205, v216, v45
	ds_bpermute_b32 v206, v216, v46
	ds_bpermute_b32 v207, v216, v47
	v_add_u32_e32 v219, 0x20000, v218
	s_waitcnt lgkmcnt(0)
	v_cndmask_b32_e64 v200, v200, v204, s[98:99]
	v_cndmask_b32_e64 v201, v201, v205, s[98:99]
	v_cndmask_b32_e64 v202, v202, v206, s[98:99]
	v_cndmask_b32_e64 v203, v203, v207, s[98:99]
	global_store_dwordx4 v219, v[200:203], s[8:9] offset:512
	s_nop 1
	ds_bpermute_b32 v200, v217, v40
	ds_bpermute_b32 v201, v217, v41
	ds_bpermute_b32 v202, v217, v42
	ds_bpermute_b32 v203, v217, v43
	ds_bpermute_b32 v204, v217, v44
	ds_bpermute_b32 v205, v217, v45
	ds_bpermute_b32 v206, v217, v46
	ds_bpermute_b32 v207, v217, v47
	v_add_u32_e32 v220, 0x28000, v218
	s_waitcnt lgkmcnt(0)
	v_cndmask_b32_e64 v200, v200, v204, s[98:99]
	v_cndmask_b32_e64 v201, v201, v205, s[98:99]
	v_cndmask_b32_e64 v202, v202, v206, s[98:99]
	v_cndmask_b32_e64 v203, v203, v207, s[98:99]
	global_store_dwordx4 v220, v[200:203], s[8:9] offset:512
	s_nop 1
	ds_bpermute_b32 v200, v216, v84
	ds_bpermute_b32 v201, v216, v85
	ds_bpermute_b32 v202, v216, v86
	ds_bpermute_b32 v203, v216, v87
	ds_bpermute_b32 v204, v216, v88
	ds_bpermute_b32 v205, v216, v89
	ds_bpermute_b32 v206, v216, v90
	ds_bpermute_b32 v207, v216, v91
	v_add_u32_e32 v219, 0x30000, v218
	s_waitcnt lgkmcnt(0)
	v_cndmask_b32_e64 v200, v200, v204, s[98:99]
	v_cndmask_b32_e64 v201, v201, v205, s[98:99]
	v_cndmask_b32_e64 v202, v202, v206, s[98:99]
	v_cndmask_b32_e64 v203, v203, v207, s[98:99]
	global_store_dwordx4 v219, v[200:203], s[8:9]
	s_nop 1
	ds_bpermute_b32 v200, v217, v84
	ds_bpermute_b32 v201, v217, v85
	ds_bpermute_b32 v202, v217, v86
	ds_bpermute_b32 v203, v217, v87
	ds_bpermute_b32 v204, v217, v88
	ds_bpermute_b32 v205, v217, v89
	ds_bpermute_b32 v206, v217, v90
	ds_bpermute_b32 v207, v217, v91
	v_add_u32_e32 v220, 0x38000, v218
	s_waitcnt lgkmcnt(0)
	v_cndmask_b32_e64 v200, v200, v204, s[98:99]
	v_cndmask_b32_e64 v201, v201, v205, s[98:99]
	v_cndmask_b32_e64 v202, v202, v206, s[98:99]
	v_cndmask_b32_e64 v203, v203, v207, s[98:99]
	global_store_dwordx4 v220, v[200:203], s[8:9]
	s_nop 1
	ds_bpermute_b32 v200, v216, v48
	ds_bpermute_b32 v201, v216, v49
	ds_bpermute_b32 v202, v216, v50
	ds_bpermute_b32 v203, v216, v51
	ds_bpermute_b32 v204, v216, v52
	ds_bpermute_b32 v205, v216, v53
	ds_bpermute_b32 v206, v216, v54
	ds_bpermute_b32 v207, v216, v55
	v_add_u32_e32 v219, 0x30000, v218
	s_waitcnt lgkmcnt(0)
	v_cndmask_b32_e64 v200, v200, v204, s[98:99]
	v_cndmask_b32_e64 v201, v201, v205, s[98:99]
	v_cndmask_b32_e64 v202, v202, v206, s[98:99]
	v_cndmask_b32_e64 v203, v203, v207, s[98:99]
	global_store_dwordx4 v219, v[200:203], s[8:9] offset:512
	s_nop 1
	ds_bpermute_b32 v200, v217, v48
	ds_bpermute_b32 v201, v217, v49
	ds_bpermute_b32 v202, v217, v50
	ds_bpermute_b32 v203, v217, v51
	ds_bpermute_b32 v204, v217, v52
	ds_bpermute_b32 v205, v217, v53
	ds_bpermute_b32 v206, v217, v54
	ds_bpermute_b32 v207, v217, v55
	v_add_u32_e32 v220, 0x38000, v218
	s_waitcnt lgkmcnt(0)
	v_cndmask_b32_e64 v200, v200, v204, s[98:99]
	v_cndmask_b32_e64 v201, v201, v205, s[98:99]
	v_cndmask_b32_e64 v202, v202, v206, s[98:99]
	v_cndmask_b32_e64 v203, v203, v207, s[98:99]
	global_store_dwordx4 v220, v[200:203], s[8:9] offset:512
	s_nop 1
	ds_bpermute_b32 v200, v216, v140
	ds_bpermute_b32 v201, v216, v141
	ds_bpermute_b32 v202, v216, v142
	ds_bpermute_b32 v203, v216, v143
	ds_bpermute_b32 v204, v216, v144
	ds_bpermute_b32 v205, v216, v145
	ds_bpermute_b32 v206, v216, v146
	ds_bpermute_b32 v207, v216, v147
	v_add_u32_e32 v219, 0x80000, v218
	s_waitcnt lgkmcnt(0)
;     DI void operator()(const f32x4 (&acc)[2][2][4][2], const Unit& u, int wr, int wc, int fr, int fq) const {
;         const int row0 = (u.pm - 64) * BM + wr * 64 + fr, col0 = u.pn * BM + wc * 32 + 4 * fq;
;         float* base = P + (size_t)u.slice * 1048576;
; #pragma unroll
;         for (int ai = 0; ai < 2; ++ai)
; #pragma unroll
;             for (int m = 0; m < 4; ++m) { float* op = base + (size_t)(row0 + ai * HALF + m * 16) * 1024 + col0;
; #pragma unroll
;                 for (int bj = 0; bj < 2; ++bj)
; #pragma unroll
;                     for (int n = 0; n < 2; ++n) *(f32x4*)(op + bj * HALF + n * 16) = acc[ai][bj][m][n]; }
	v_cndmask_b32_e64 v200, v200, v204, s[98:99]
	v_cndmask_b32_e64 v201, v201, v205, s[98:99]
	v_cndmask_b32_e64 v202, v202, v206, s[98:99]
	v_cndmask_b32_e64 v203, v203, v207, s[98:99]
	global_store_dwordx4 v219, v[200:203], s[8:9]
	s_nop 1
	ds_bpermute_b32 v200, v217, v140
	ds_bpermute_b32 v201, v217, v141
	ds_bpermute_b32 v202, v217, v142
	ds_bpermute_b32 v203, v217, v143
	ds_bpermute_b32 v204, v217, v144
	ds_bpermute_b32 v205, v217, v145
	ds_bpermute_b32 v206, v217, v146
	ds_bpermute_b32 v207, v217, v147
	v_add_u32_e32 v220, 0x88000, v218
	s_waitcnt lgkmcnt(0)
	v_cndmask_b32_e64 v200, v200, v204, s[98:99]
	v_cndmask_b32_e64 v201, v201, v205, s[98:99]
	v_cndmask_b32_e64 v202, v202, v206, s[98:99]
	v_cndmask_b32_e64 v203, v203, v207, s[98:99]
	global_store_dwordx4 v220, v[200:203], s[8:9]
	s_nop 1
	ds_bpermute_b32 v200, v216, v20
	ds_bpermute_b32 v201, v216, v21
	ds_bpermute_b32 v202, v216, v22
	ds_bpermute_b32 v203, v216, v23
	ds_bpermute_b32 v204, v216, v24
	ds_bpermute_b32 v205, v216, v25
	ds_bpermute_b32 v206, v216, v26
	ds_bpermute_b32 v207, v216, v27
	v_add_u32_e32 v219, 0x80000, v218
	s_waitcnt lgkmcnt(0)
	v_cndmask_b32_e64 v200, v200, v204, s[98:99]
	v_cndmask_b32_e64 v201, v201, v205, s[98:99]
	v_cndmask_b32_e64 v202, v202, v206, s[98:99]
	v_cndmask_b32_e64 v203, v203, v207, s[98:99]
	global_store_dwordx4 v219, v[200:203], s[8:9] offset:512
	s_nop 1
	ds_bpermute_b32 v200, v217, v20
	ds_bpermute_b32 v201, v217, v21
	ds_bpermute_b32 v202, v217, v22
	ds_bpermute_b32 v203, v217, v23
	ds_bpermute_b32 v204, v217, v24
	ds_bpermute_b32 v205, v217, v25
	ds_bpermute_b32 v206, v217, v26
	ds_bpermute_b32 v207, v217, v27
	v_add_u32_e32 v220, 0x88000, v218
	s_waitcnt lgkmcnt(0)
	v_cndmask_b32_e64 v200, v200, v204, s[98:99]
	v_cndmask_b32_e64 v201, v201, v205, s[98:99]
	v_cndmask_b32_e64 v202, v202, v206, s[98:99]
	v_cndmask_b32_e64 v203, v203, v207, s[98:99]
	global_store_dwordx4 v220, v[200:203], s[8:9] offset:512
	s_nop 1
	ds_bpermute_b32 v200, v216, v148
	ds_bpermute_b32 v201, v216, v149
	ds_bpermute_b32 v202, v216, v150
	ds_bpermute_b32 v203, v216, v151
	ds_bpermute_b32 v204, v216, v152
	ds_bpermute_b32 v205, v216, v153
	ds_bpermute_b32 v206, v216, v154
	ds_bpermute_b32 v207, v216, v155
	v_add_u32_e32 v219, 0x90000, v218
	s_waitcnt lgkmcnt(0)
	v_cndmask_b32_e64 v200, v200, v204, s[98:99]
	v_cndmask_b32_e64 v201, v201, v205, s[98:99]
	v_cndmask_b32_e64 v202, v202, v206, s[98:99]
	v_cndmask_b32_e64 v203, v203, v207, s[98:99]
	global_store_dwordx4 v219, v[200:203], s[8:9]
	s_nop 1
	ds_bpermute_b32 v200, v217, v148
	ds_bpermute_b32 v201, v217, v149
	ds_bpermute_b32 v202, v217, v150
	ds_bpermute_b32 v203, v217, v151
	ds_bpermute_b32 v204, v217, v152
	ds_bpermute_b32 v205, v217, v153
	ds_bpermute_b32 v206, v217, v154
	ds_bpermute_b32 v207, v217, v155
	v_add_u32_e32 v220, 0x98000, v218
	s_waitcnt lgkmcnt(0)
	v_cndmask_b32_e64 v200, v200, v204, s[98:99]
	v_cndmask_b32_e64 v201, v201, v205, s[98:99]
	v_cndmask_b32_e64 v202, v202, v206, s[98:99]
	v_cndmask_b32_e64 v203, v203, v207, s[98:99]
	global_store_dwordx4 v220, v[200:203], s[8:9]
	s_nop 1
	ds_bpermute_b32 v200, v216, v56
	ds_bpermute_b32 v201, v216, v57
	ds_bpermute_b32 v202, v216, v58
	ds_bpermute_b32 v203, v216, v59
	ds_bpermute_b32 v204, v216, v100
	ds_bpermute_b32 v205, v216, v101
	ds_bpermute_b32 v206, v216, v102
	ds_bpermute_b32 v207, v216, v103
	v_add_u32_e32 v219, 0x90000, v218
	s_waitcnt lgkmcnt(0)
	v_cndmask_b32_e64 v200, v200, v204, s[98:99]
	v_cndmask_b32_e64 v201, v201, v205, s[98:99]
	v_cndmask_b32_e64 v202, v202, v206, s[98:99]
	v_cndmask_b32_e64 v203, v203, v207, s[98:99]
	global_store_dwordx4 v219, v[200:203], s[8:9] offset:512
	s_nop 1
	ds_bpermute_b32 v200, v217, v56
	ds_bpermute_b32 v201, v217, v57
	ds_bpermute_b32 v202, v217, v58
	ds_bpermute_b32 v203, v217, v59
	ds_bpermute_b32 v204, v217, v100
	ds_bpermute_b32 v205, v217, v101
	ds_bpermute_b32 v206, v217, v102
	ds_bpermute_b32 v207, v217, v103
	v_add_u32_e32 v220, 0x98000, v218
	s_waitcnt lgkmcnt(0)
	v_cndmask_b32_e64 v200, v200, v204, s[98:99]
	v_cndmask_b32_e64 v201, v201, v205, s[98:99]
	v_cndmask_b32_e64 v202, v202, v206, s[98:99]
	v_cndmask_b32_e64 v203, v203, v207, s[98:99]
	global_store_dwordx4 v220, v[200:203], s[8:9] offset:512
	s_nop 1
	ds_bpermute_b32 v200, v216, v156
	ds_bpermute_b32 v201, v216, v157
	ds_bpermute_b32 v202, v216, v158
	ds_bpermute_b32 v203, v216, v159
	ds_bpermute_b32 v204, v216, v168
	ds_bpermute_b32 v205, v216, v169
	ds_bpermute_b32 v206, v216, v170
	ds_bpermute_b32 v207, v216, v171
	v_add_u32_e32 v219, 0xa0000, v218
	s_waitcnt lgkmcnt(0)
;     DI void operator()(const f32x4 (&acc)[2][2][4][2], const Unit& u, int wr, int wc, int fr, int fq) const {
;         const int row0 = (u.pm - 64) * BM + wr * 64 + fr, col0 = u.pn * BM + wc * 32 + 4 * fq;
;         float* base = P + (size_t)u.slice * 1048576;
; #pragma unroll
;         for (int ai = 0; ai < 2; ++ai)
; #pragma unroll
;             for (int m = 0; m < 4; ++m) { float* op = base + (size_t)(row0 + ai * HALF + m * 16) * 1024 + col0;
; #pragma unroll
;                 for (int bj = 0; bj < 2; ++bj)
; #pragma unroll
;                     for (int n = 0; n < 2; ++n) *(f32x4*)(op + bj * HALF + n * 16) = acc[ai][bj][m][n]; }
	v_cndmask_b32_e64 v200, v200, v204, s[98:99]
	v_cndmask_b32_e64 v201, v201, v205, s[98:99]
	v_cndmask_b32_e64 v202, v202, v206, s[98:99]
	v_cndmask_b32_e64 v203, v203, v207, s[98:99]
	global_store_dwordx4 v219, v[200:203], s[8:9]
	s_nop 1
	ds_bpermute_b32 v200, v217, v156
	ds_bpermute_b32 v201, v217, v157
	ds_bpermute_b32 v202, v217, v158
	ds_bpermute_b32 v203, v217, v159
	ds_bpermute_b32 v204, v217, v168
	ds_bpermute_b32 v205, v217, v169
	ds_bpermute_b32 v206, v217, v170
	ds_bpermute_b32 v207, v217, v171
	v_add_u32_e32 v220, 0xa8000, v218
	s_waitcnt lgkmcnt(0)
	v_cndmask_b32_e64 v200, v200, v204, s[98:99]
	v_cndmask_b32_e64 v201, v201, v205, s[98:99]
	v_cndmask_b32_e64 v202, v202, v206, s[98:99]
	v_cndmask_b32_e64 v203, v203, v207, s[98:99]
	global_store_dwordx4 v220, v[200:203], s[8:9]
	s_nop 1
	ds_bpermute_b32 v200, v216, v104
	ds_bpermute_b32 v201, v216, v105
	ds_bpermute_b32 v202, v216, v106
	ds_bpermute_b32 v203, v216, v107
	ds_bpermute_b32 v204, v216, v112
	ds_bpermute_b32 v205, v216, v113
	ds_bpermute_b32 v206, v216, v114
	ds_bpermute_b32 v207, v216, v115
	v_add_u32_e32 v219, 0xa0000, v218
	s_waitcnt lgkmcnt(0)
	v_cndmask_b32_e64 v200, v200, v204, s[98:99]
	v_cndmask_b32_e64 v201, v201, v205, s[98:99]
	v_cndmask_b32_e64 v202, v202, v206, s[98:99]
	v_cndmask_b32_e64 v203, v203, v207, s[98:99]
	global_store_dwordx4 v219, v[200:203], s[8:9] offset:512
	s_nop 1
	ds_bpermute_b32 v200, v217, v104
	ds_bpermute_b32 v201, v217, v105
	ds_bpermute_b32 v202, v217, v106
	ds_bpermute_b32 v203, v217, v107
	ds_bpermute_b32 v204, v217, v112
	ds_bpermute_b32 v205, v217, v113
	ds_bpermute_b32 v206, v217, v114
	ds_bpermute_b32 v207, v217, v115
	v_add_u32_e32 v220, 0xa8000, v218
	s_waitcnt lgkmcnt(0)
	v_cndmask_b32_e64 v200, v200, v204, s[98:99]
	v_cndmask_b32_e64 v201, v201, v205, s[98:99]
	v_cndmask_b32_e64 v202, v202, v206, s[98:99]
	v_cndmask_b32_e64 v203, v203, v207, s[98:99]
	global_store_dwordx4 v220, v[200:203], s[8:9] offset:512
	s_nop 1
	ds_bpermute_b32 v200, v216, v12
	ds_bpermute_b32 v201, v216, v13
	ds_bpermute_b32 v202, v216, v14
	ds_bpermute_b32 v203, v216, v15
	ds_bpermute_b32 v204, v216, v16
	ds_bpermute_b32 v205, v216, v17
	ds_bpermute_b32 v206, v216, v18
	ds_bpermute_b32 v207, v216, v19
	v_add_u32_e32 v219, 0xb0000, v218
	s_waitcnt lgkmcnt(0)
	v_cndmask_b32_e64 v200, v200, v204, s[98:99]
	v_cndmask_b32_e64 v201, v201, v205, s[98:99]
	v_cndmask_b32_e64 v202, v202, v206, s[98:99]
	v_cndmask_b32_e64 v203, v203, v207, s[98:99]
	global_store_dwordx4 v219, v[200:203], s[8:9]
	s_nop 1
	ds_bpermute_b32 v200, v217, v12
	ds_bpermute_b32 v201, v217, v13
	ds_bpermute_b32 v202, v217, v14
	ds_bpermute_b32 v203, v217, v15
	ds_bpermute_b32 v204, v217, v16
	ds_bpermute_b32 v205, v217, v17
	ds_bpermute_b32 v206, v217, v18
	ds_bpermute_b32 v207, v217, v19
	v_add_u32_e32 v220, 0xb8000, v218
	s_waitcnt lgkmcnt(0)
	v_cndmask_b32_e64 v200, v200, v204, s[98:99]
	v_cndmask_b32_e64 v201, v201, v205, s[98:99]
	v_cndmask_b32_e64 v202, v202, v206, s[98:99]
	v_cndmask_b32_e64 v203, v203, v207, s[98:99]
	global_store_dwordx4 v220, v[200:203], s[8:9]
	s_nop 1
	ds_bpermute_b32 v200, v216, v92
	ds_bpermute_b32 v201, v216, v93
	ds_bpermute_b32 v202, v216, v94
	ds_bpermute_b32 v203, v216, v95
	ds_bpermute_b32 v204, v216, v96
	ds_bpermute_b32 v205, v216, v97
	ds_bpermute_b32 v206, v216, v98
	ds_bpermute_b32 v207, v216, v99
	v_add_u32_e32 v219, 0xb0000, v218
	s_waitcnt lgkmcnt(0)
	v_cndmask_b32_e64 v200, v200, v204, s[98:99]
	v_cndmask_b32_e64 v201, v201, v205, s[98:99]
	v_cndmask_b32_e64 v202, v202, v206, s[98:99]
	v_cndmask_b32_e64 v203, v203, v207, s[98:99]
	global_store_dwordx4 v219, v[200:203], s[8:9] offset:512
	s_nop 1
	ds_bpermute_b32 v200, v217, v92
	ds_bpermute_b32 v201, v217, v93
	ds_bpermute_b32 v202, v217, v94
	ds_bpermute_b32 v203, v217, v95
	ds_bpermute_b32 v204, v217, v96
	ds_bpermute_b32 v205, v217, v97
	ds_bpermute_b32 v206, v217, v98
	ds_bpermute_b32 v207, v217, v99
	v_add_u32_e32 v220, 0xb8000, v218
	s_waitcnt lgkmcnt(0)
	v_cndmask_b32_e64 v200, v200, v204, s[98:99]
	v_cndmask_b32_e64 v201, v201, v205, s[98:99]
	v_cndmask_b32_e64 v202, v202, v206, s[98:99]
	v_cndmask_b32_e64 v203, v203, v207, s[98:99]
	global_store_dwordx4 v220, v[200:203], s[8:9] offset:512
	s_nop 1
	s_add_i32 s50, s50, s51
	s_mov_b32 s8, s59
	s_mov_b32 s9, s26
	s_mov_b32 s6, s24
	s_andn2_b64 vcc, exec, s[30:31]
	s_mov_b64 s[38:39], s[0:1]
	s_mov_b64 s[36:37], s[34:35]
	s_cbranch_vccz .LBB0_1539
